# P2 conv: one tap-weight register set (each channel third reloaded from LDS right after its last use) frees 12 registers for two more raw-row slots: six rows in flight per wave instead of four
# baseline (speedup 1.0000x reference)
.Lcv_pre_skip2:
	s_waitcnt lgkmcnt(0)
	s_barrier
	v_readlane_b32 s0, v254, 41
	s_cmpk_gt_i32 s0, 0xfff
	s_cbranch_scc1 .LBB0_280
	v_mov_b32_e32 v86, 0
	v_readlane_b32 s4, v254, 23
	v_lshlrev_b32_e32 v2, 4, v199
	v_mov_b32_e32 v3, v86
	v_readlane_b32 s5, v254, 24
	v_mbcnt_lo_u32_b32 v1, -1, 0
	v_lshl_add_u64 v[88:89], s[64:65], 0, v[2:3]
	v_lshl_add_u64 v[92:93], s[62:63], 0, v[2:3]
	v_lshl_add_u64 v[94:95], s[66:67], 0, v[2:3]
	v_lshl_add_u64 v[96:97], s[4:5], 0, v[2:3]
	v_mbcnt_hi_u32_b32 v2, -1, v1
	v_and_b32_e32 v1, 64, v2
	v_add_u32_e32 v3, 64, v1
	v_xor_b32_e32 v1, 1, v2
	v_cmp_lt_i32_e32 vcc, v1, v3
	v_xor_b32_e32 v6, 2, v2
	v_readlane_b32 s1, v254, 40
	v_cndmask_b32_e32 v1, v2, v1, vcc
	v_cmp_lt_i32_e32 vcc, v6, v3
	s_lshl_b32 s0, s80, 5
	s_lshl_b32 s1, s1, 2
	v_cndmask_b32_e32 v6, v2, v6, vcc
	v_lshlrev_b32_e32 v162, 2, v6
	v_xor_b32_e32 v6, 4, v2
	v_cmp_lt_i32_e32 vcc, v6, v3
	v_lshlrev_b32_e32 v4, 3, v199
	v_mov_b32_e32 v5, v86
	v_cndmask_b32_e32 v6, v2, v6, vcc
	v_lshlrev_b32_e32 v163, 2, v6
	v_xor_b32_e32 v6, 8, v2
	v_cmp_lt_i32_e32 vcc, v6, v3
	v_readlane_b32 s8, v254, 27
	v_readlane_b32 s9, v254, 28
	v_cndmask_b32_e32 v6, v2, v6, vcc
	v_lshlrev_b32_e32 v164, 2, v6
	v_xor_b32_e32 v6, 16, v2
	v_cmp_lt_i32_e32 vcc, v6, v3
	v_readlane_b32 s10, v254, 29
	v_readlane_b32 s11, v254, 30
	v_cndmask_b32_e32 v6, v2, v6, vcc
	v_lshlrev_b32_e32 v165, 2, v6
	v_xor_b32_e32 v6, 32, v2
	v_cmp_lt_i32_e32 vcc, v6, v3
	v_readlane_b32 s12, v254, 31
	v_readlane_b32 s13, v254, 32
	v_readlane_b32 s14, v254, 33
	v_readlane_b32 s15, v254, 34
	v_cndmask_b32_e32 v2, v2, v6, vcc
	s_add_i32 s0, s0, s1
	v_lshl_add_u64 v[90:91], s[38:39], 0, v[4:5]
	v_lshlrev_b32_e32 v1, 2, v1
	v_lshlrev_b32_e32 v166, 2, v2
	v_lshl_add_u64 v[98:99], s[44:45], 0, v[4:5]
	s_sub_i32 s8, s0, 27
	s_lshl_b32 s9, s33, 5
	v_mov_b32_e32 v167, 0x600
	s_movk_i32 s10, 0x1000
	s_movk_i32 s11, 0x2000
	s_movk_i32 s12, 0x3000
	s_movk_i32 s13, 0x4000
	s_movk_i32 s14, 0x5000
	v_mov_b32_e32 v168, 0x3727c5ac
	v_readlane_b32 s15, v254, 41
	v_readlane_b32 s6, v254, 25
	v_readlane_b32 s7, v254, 26
	v_readlane_b32 s16, v254, 35
	v_readlane_b32 s17, v254, 36
	v_readlane_b32 s18, v254, 37
	v_readlane_b32 s19, v254, 38
	v_readlane_b32 s40, v254, 41
	v_readlane_b32 s42, v254, 23
	v_readlane_b32 s43, v254, 24
	v_lshlrev_b32_e32 v2, 4, v199
	v_lshlrev_b32_e32 v3, 3, v199
	s_cmpk_gt_u32 s40, 0x7ff
	s_cbranch_scc1 .LBB0_280
	s_lshl_b32 s41, s40, 3
	s_mov_b64 s[50:51], s[62:63]
	v_add_u32_e32 v208, 0x10000, v2
	global_load_dwordx4 v[222:225], v2, s[64:65]
	global_load_dwordx4 v[226:229], v2, s[64:65] offset:1024
	global_load_dwordx4 v[230:233], v2, s[64:65] offset:2048
	s_add_i32 s52, s41, -30
	s_max_i32 s52, s52, 0
	s_mulk_i32 s52, 0x600
	v_add_u32_e32 v196, s52, v3
	global_load_dwordx2 v[234:235], v196, s[38:39]
	global_load_dwordx2 v[236:237], v196, s[38:39] offset:512
	global_load_dwordx2 v[238:239], v196, s[38:39] offset:1024
	s_add_i32 s52, s41, -29
	s_max_i32 s52, s52, 0
	s_mulk_i32 s52, 0x600
	v_add_u32_e32 v196, s52, v3
	global_load_dwordx2 v[240:241], v196, s[38:39]
	global_load_dwordx2 v[242:243], v196, s[38:39] offset:512
	global_load_dwordx2 v[244:245], v196, s[38:39] offset:1024
	s_add_i32 s52, s41, -28
	s_max_i32 s52, s52, 0
	s_mulk_i32 s52, 0x600
	v_add_u32_e32 v196, s52, v3
	global_load_dwordx2 v[246:247], v196, s[38:39]
	global_load_dwordx2 v[248:249], v196, s[38:39] offset:512
	global_load_dwordx2 v[250:251], v196, s[38:39] offset:1024
	s_add_i32 s52, s41, -27
	s_max_i32 s52, s52, 0
	s_mulk_i32 s52, 0x600
	v_add_u32_e32 v196, s52, v3
	global_load_dwordx2 v[204:205], v196, s[38:39]
	global_load_dwordx2 v[206:207], v196, s[38:39] offset:512
	global_load_dwordx2 v[252:253], v196, s[38:39] offset:1024
	s_add_i32 s52, s41, -26
	s_max_i32 s52, s52, 0
	s_mulk_i32 s52, 0x600
	v_add_u32_e32 v196, s52, v3
	global_load_dwordx2 v[154:155], v196, s[38:39]
	global_load_dwordx2 v[156:157], v196, s[38:39] offset:512
	global_load_dwordx2 v[158:159], v196, s[38:39] offset:1024
	s_add_i32 s52, s41, -25
	s_max_i32 s52, s52, 0
	s_mulk_i32 s52, 0x600
	v_add_u32_e32 v196, s52, v3
	global_load_dwordx2 v[166:167], v196, s[38:39]
	global_load_dwordx2 v[168:169], v196, s[38:39] offset:512
	global_load_dwordx2 v[170:171], v196, s[38:39] offset:1024
	s_add_i32 s52, s41, -24
	s_max_i32 s52, s52, 0
	s_mulk_i32 s52, 0x600
	v_add_u32_e32 v196, s52, v3
	global_load_dwordx2 v[178:179], v196, s[38:39]
	global_load_dwordx2 v[180:181], v196, s[38:39] offset:512
	global_load_dwordx2 v[182:183], v196, s[38:39] offset:1024
	s_add_i32 s52, s41, -23
	s_max_i32 s52, s52, 0
	s_mulk_i32 s52, 0x600
	v_add_u32_e32 v196, s52, v3
	global_load_dwordx2 v[190:191], v196, s[38:39]
	global_load_dwordx2 v[192:193], v196, s[38:39] offset:512
	global_load_dwordx2 v[194:195], v196, s[38:39] offset:1024
	ds_read_b128 v[210:213], v2
	ds_read_b128 v[214:217], v2 offset:1024
	ds_read_b128 v[218:221], v2 offset:2048
	s_waitcnt vmcnt(24)
	v_mov_b32_e32 v4, v222
	v_mov_b32_e32 v5, v223
	v_mov_b32_e32 v6, v224
	v_mov_b32_e32 v7, v225
	v_mov_b32_e32 v8, v226
	v_mov_b32_e32 v9, v227
	v_mov_b32_e32 v10, v228
	v_mov_b32_e32 v11, v229
	v_mov_b32_e32 v12, v230
	v_mov_b32_e32 v13, v231
	v_mov_b32_e32 v14, v232
	v_mov_b32_e32 v15, v233
	v_mov_b32_e32 v16, v222
	v_mov_b32_e32 v17, v223
	v_mov_b32_e32 v18, v224
	v_mov_b32_e32 v19, v225
	v_mov_b32_e32 v20, v226
	v_mov_b32_e32 v21, v227
	v_mov_b32_e32 v22, v228
	v_mov_b32_e32 v23, v229
	v_mov_b32_e32 v24, v230
	v_mov_b32_e32 v25, v231
	v_mov_b32_e32 v26, v232
	v_mov_b32_e32 v27, v233
	v_mov_b32_e32 v28, v222
	v_mov_b32_e32 v29, v223
	v_mov_b32_e32 v30, v224
	v_mov_b32_e32 v31, v225
	v_mov_b32_e32 v32, v226
	v_mov_b32_e32 v33, v227
	v_mov_b32_e32 v34, v228
	v_mov_b32_e32 v35, v229
	v_mov_b32_e32 v36, v230
	v_mov_b32_e32 v37, v231
	v_mov_b32_e32 v38, v232
	v_mov_b32_e32 v39, v233
	v_mov_b32_e32 v40, v222
	v_mov_b32_e32 v41, v223
	v_mov_b32_e32 v42, v224
	v_mov_b32_e32 v43, v225
	v_mov_b32_e32 v44, v226
	v_mov_b32_e32 v45, v227
	v_mov_b32_e32 v46, v228
	v_mov_b32_e32 v47, v229
	v_mov_b32_e32 v48, v230
	v_mov_b32_e32 v49, v231
	v_mov_b32_e32 v50, v232
	v_mov_b32_e32 v51, v233
	v_mov_b32_e32 v52, v222
	v_mov_b32_e32 v53, v223
	v_mov_b32_e32 v54, v224
	v_mov_b32_e32 v55, v225
	v_mov_b32_e32 v56, v226
	v_mov_b32_e32 v57, v227
	v_mov_b32_e32 v58, v228
	v_mov_b32_e32 v59, v229
	v_mov_b32_e32 v60, v230
	v_mov_b32_e32 v61, v231
	v_mov_b32_e32 v62, v232
	v_mov_b32_e32 v63, v233
	v_mov_b32_e32 v64, v222
	v_mov_b32_e32 v65, v223
	v_mov_b32_e32 v66, v224
	v_mov_b32_e32 v67, v225
	v_mov_b32_e32 v68, v226
	v_mov_b32_e32 v69, v227
	v_mov_b32_e32 v70, v228
	v_mov_b32_e32 v71, v229
	v_mov_b32_e32 v72, v230
	v_mov_b32_e32 v73, v231
	v_mov_b32_e32 v74, v232
	v_mov_b32_e32 v75, v233
	v_mov_b32_e32 v76, v222
	v_mov_b32_e32 v77, v223
	v_mov_b32_e32 v78, v224
	v_mov_b32_e32 v79, v225
	v_mov_b32_e32 v80, v226
	v_mov_b32_e32 v81, v227
	v_mov_b32_e32 v82, v228
	v_mov_b32_e32 v83, v229
	v_mov_b32_e32 v84, v230
	v_mov_b32_e32 v85, v231
	v_mov_b32_e32 v86, v232
	v_mov_b32_e32 v87, v233
	v_mov_b32_e32 v88, v222
	v_mov_b32_e32 v89, v223
	v_mov_b32_e32 v90, v224
	v_mov_b32_e32 v91, v225
	v_mov_b32_e32 v92, v226
	v_mov_b32_e32 v93, v227
	v_mov_b32_e32 v94, v228
	v_mov_b32_e32 v95, v229
	v_mov_b32_e32 v96, v230
	v_mov_b32_e32 v97, v231
	v_mov_b32_e32 v98, v232
	v_mov_b32_e32 v99, v233
	s_add_i32 s52, s41, -18
	s_max_i32 s52, s52, 0
	s_mulk_i32 s52, 0x600
	v_add_u32_e32 v196, s52, v3
	global_load_dwordx2 v[222:223], v196, s[38:39]
	global_load_dwordx2 v[224:225], v196, s[38:39] offset:512
	global_load_dwordx2 v[226:227], v196, s[38:39] offset:1024
	s_add_i32 s52, s41, -17
	s_max_i32 s52, s52, 0
	s_mulk_i32 s52, 0x600
	v_add_u32_e32 v196, s52, v3
	global_load_dwordx2 v[228:229], v196, s[38:39]
	global_load_dwordx2 v[230:231], v196, s[38:39] offset:512
	global_load_dwordx2 v[232:233], v196, s[38:39] offset:1024
	s_waitcnt vmcnt(27)
	s_add_i32 s52, s41, -30
	s_cmp_lt_i32 s52, 0
	s_cbranch_scc1 .Lcv_z0_zero
	v_lshlrev_b32_e32 v100, 16, v234
	v_and_b32_e32 v101, 0xffff0000, v234
	v_lshlrev_b32_e32 v102, 16, v235
	v_and_b32_e32 v103, 0xffff0000, v235
	v_lshlrev_b32_e32 v104, 16, v236
	v_and_b32_e32 v105, 0xffff0000, v236
	v_lshlrev_b32_e32 v106, 16, v237
	v_and_b32_e32 v107, 0xffff0000, v237
	v_lshlrev_b32_e32 v108, 16, v238
	v_and_b32_e32 v109, 0xffff0000, v238
	v_lshlrev_b32_e32 v110, 16, v239
	v_and_b32_e32 v111, 0xffff0000, v239
	s_branch .Lcv_z0_done

.Lcv_z7_done:
	s_waitcnt lgkmcnt(2)
	v_pk_fma_f32 v[4:5], v[100:101], v[210:211], v[4:5]
	v_pk_fma_f32 v[6:7], v[102:103], v[212:213], v[6:7]
	v_pk_fma_f32 v[16:17], v[112:113], v[210:211], v[16:17]
	v_pk_fma_f32 v[18:19], v[114:115], v[212:213], v[18:19]
	v_pk_fma_f32 v[28:29], v[124:125], v[210:211], v[28:29]
	v_pk_fma_f32 v[30:31], v[126:127], v[212:213], v[30:31]
	v_pk_fma_f32 v[40:41], v[136:137], v[210:211], v[40:41]
	v_pk_fma_f32 v[42:43], v[138:139], v[212:213], v[42:43]
	v_pk_fma_f32 v[52:53], v[148:149], v[210:211], v[52:53]
	v_pk_fma_f32 v[54:55], v[150:151], v[212:213], v[54:55]
	v_pk_fma_f32 v[64:65], v[160:161], v[210:211], v[64:65]
	v_pk_fma_f32 v[66:67], v[162:163], v[212:213], v[66:67]
	v_pk_fma_f32 v[76:77], v[172:173], v[210:211], v[76:77]
	v_pk_fma_f32 v[78:79], v[174:175], v[212:213], v[78:79]
	v_pk_fma_f32 v[88:89], v[184:185], v[210:211], v[88:89]
	v_pk_fma_f32 v[90:91], v[186:187], v[212:213], v[90:91]
	ds_read_b128 v[210:213], v2 offset:3072
	s_waitcnt lgkmcnt(2)
	v_pk_fma_f32 v[8:9], v[104:105], v[214:215], v[8:9]
	v_pk_fma_f32 v[10:11], v[106:107], v[216:217], v[10:11]
	v_pk_fma_f32 v[20:21], v[116:117], v[214:215], v[20:21]
	v_pk_fma_f32 v[22:23], v[118:119], v[216:217], v[22:23]
	v_pk_fma_f32 v[32:33], v[128:129], v[214:215], v[32:33]
	v_pk_fma_f32 v[34:35], v[130:131], v[216:217], v[34:35]
	v_pk_fma_f32 v[44:45], v[140:141], v[214:215], v[44:45]
	v_pk_fma_f32 v[46:47], v[142:143], v[216:217], v[46:47]
	v_pk_fma_f32 v[56:57], v[152:153], v[214:215], v[56:57]
	v_pk_fma_f32 v[58:59], v[154:155], v[216:217], v[58:59]
	v_pk_fma_f32 v[68:69], v[164:165], v[214:215], v[68:69]
	v_pk_fma_f32 v[70:71], v[166:167], v[216:217], v[70:71]
	v_pk_fma_f32 v[80:81], v[176:177], v[214:215], v[80:81]
	v_pk_fma_f32 v[82:83], v[178:179], v[216:217], v[82:83]
	v_pk_fma_f32 v[92:93], v[188:189], v[214:215], v[92:93]
	v_pk_fma_f32 v[94:95], v[190:191], v[216:217], v[94:95]
	ds_read_b128 v[214:217], v2 offset:4096
	s_waitcnt lgkmcnt(2)
	v_pk_fma_f32 v[12:13], v[108:109], v[218:219], v[12:13]
	v_pk_fma_f32 v[14:15], v[110:111], v[220:221], v[14:15]
	v_pk_fma_f32 v[24:25], v[120:121], v[218:219], v[24:25]
	v_pk_fma_f32 v[26:27], v[122:123], v[220:221], v[26:27]
	v_pk_fma_f32 v[36:37], v[132:133], v[218:219], v[36:37]
	v_pk_fma_f32 v[38:39], v[134:135], v[220:221], v[38:39]
	v_pk_fma_f32 v[48:49], v[144:145], v[218:219], v[48:49]
	v_pk_fma_f32 v[50:51], v[146:147], v[220:221], v[50:51]
	v_pk_fma_f32 v[60:61], v[156:157], v[218:219], v[60:61]
	v_pk_fma_f32 v[62:63], v[158:159], v[220:221], v[62:63]
	v_pk_fma_f32 v[72:73], v[168:169], v[218:219], v[72:73]
	v_pk_fma_f32 v[74:75], v[170:171], v[220:221], v[74:75]
	v_pk_fma_f32 v[84:85], v[180:181], v[218:219], v[84:85]
	v_pk_fma_f32 v[86:87], v[182:183], v[220:221], v[86:87]
	v_pk_fma_f32 v[96:97], v[192:193], v[218:219], v[96:97]
	v_pk_fma_f32 v[98:99], v[194:195], v[220:221], v[98:99]
	ds_read_b128 v[218:221], v2 offset:5120
	s_waitcnt vmcnt(9)
	s_add_i32 s52, s41, -22
	s_cmp_lt_i32 s52, 0
	s_cbranch_scc1 .Lcv_z8_zero
	v_lshlrev_b32_e32 v100, 16, v234
	v_and_b32_e32 v101, 0xffff0000, v234
	v_lshlrev_b32_e32 v102, 16, v235
	v_and_b32_e32 v103, 0xffff0000, v235
	v_lshlrev_b32_e32 v104, 16, v236
	v_and_b32_e32 v105, 0xffff0000, v236
	v_lshlrev_b32_e32 v106, 16, v237
	v_and_b32_e32 v107, 0xffff0000, v237
	v_lshlrev_b32_e32 v108, 16, v238
	v_and_b32_e32 v109, 0xffff0000, v238
	v_lshlrev_b32_e32 v110, 16, v239
	v_and_b32_e32 v111, 0xffff0000, v239
	s_branch .Lcv_z8_done

.Lcv_z8_done:
	s_add_i32 s52, s41, -16
	s_max_i32 s52, s52, 0
	s_mulk_i32 s52, 0x600
	v_add_u32_e32 v196, s52, v3
	global_load_dwordx2 v[234:235], v196, s[38:39]
	global_load_dwordx2 v[236:237], v196, s[38:39] offset:512
	global_load_dwordx2 v[238:239], v196, s[38:39] offset:1024
	s_waitcnt lgkmcnt(2)
	v_pk_fma_f32 v[4:5], v[112:113], v[210:211], v[4:5]
	v_pk_fma_f32 v[6:7], v[114:115], v[212:213], v[6:7]
	v_pk_fma_f32 v[16:17], v[124:125], v[210:211], v[16:17]
	v_pk_fma_f32 v[18:19], v[126:127], v[212:213], v[18:19]
	v_pk_fma_f32 v[28:29], v[136:137], v[210:211], v[28:29]
	v_pk_fma_f32 v[30:31], v[138:139], v[212:213], v[30:31]
	v_pk_fma_f32 v[40:41], v[148:149], v[210:211], v[40:41]
	v_pk_fma_f32 v[42:43], v[150:151], v[212:213], v[42:43]
	v_pk_fma_f32 v[52:53], v[160:161], v[210:211], v[52:53]
	v_pk_fma_f32 v[54:55], v[162:163], v[212:213], v[54:55]
	v_pk_fma_f32 v[64:65], v[172:173], v[210:211], v[64:65]
	v_pk_fma_f32 v[66:67], v[174:175], v[212:213], v[66:67]
	v_pk_fma_f32 v[76:77], v[184:185], v[210:211], v[76:77]
	v_pk_fma_f32 v[78:79], v[186:187], v[212:213], v[78:79]
	v_pk_fma_f32 v[88:89], v[100:101], v[210:211], v[88:89]
	v_pk_fma_f32 v[90:91], v[102:103], v[212:213], v[90:91]
	ds_read_b128 v[210:213], v2 offset:6144
	s_waitcnt lgkmcnt(2)
	v_pk_fma_f32 v[8:9], v[116:117], v[214:215], v[8:9]
	v_pk_fma_f32 v[10:11], v[118:119], v[216:217], v[10:11]
	v_pk_fma_f32 v[20:21], v[128:129], v[214:215], v[20:21]
	v_pk_fma_f32 v[22:23], v[130:131], v[216:217], v[22:23]
	v_pk_fma_f32 v[32:33], v[140:141], v[214:215], v[32:33]
	v_pk_fma_f32 v[34:35], v[142:143], v[216:217], v[34:35]
	v_pk_fma_f32 v[44:45], v[152:153], v[214:215], v[44:45]
	v_pk_fma_f32 v[46:47], v[154:155], v[216:217], v[46:47]
	v_pk_fma_f32 v[56:57], v[164:165], v[214:215], v[56:57]
	v_pk_fma_f32 v[58:59], v[166:167], v[216:217], v[58:59]
	v_pk_fma_f32 v[68:69], v[176:177], v[214:215], v[68:69]
	v_pk_fma_f32 v[70:71], v[178:179], v[216:217], v[70:71]
	v_pk_fma_f32 v[80:81], v[188:189], v[214:215], v[80:81]
	v_pk_fma_f32 v[82:83], v[190:191], v[216:217], v[82:83]
	v_pk_fma_f32 v[92:93], v[104:105], v[214:215], v[92:93]
	v_pk_fma_f32 v[94:95], v[106:107], v[216:217], v[94:95]
	ds_read_b128 v[214:217], v2 offset:7168
	s_waitcnt lgkmcnt(2)
	v_pk_fma_f32 v[12:13], v[120:121], v[218:219], v[12:13]
	v_pk_fma_f32 v[14:15], v[122:123], v[220:221], v[14:15]
	v_pk_fma_f32 v[24:25], v[132:133], v[218:219], v[24:25]
	v_pk_fma_f32 v[26:27], v[134:135], v[220:221], v[26:27]
	v_pk_fma_f32 v[36:37], v[144:145], v[218:219], v[36:37]
	v_pk_fma_f32 v[38:39], v[146:147], v[220:221], v[38:39]
	v_pk_fma_f32 v[48:49], v[156:157], v[218:219], v[48:49]
	v_pk_fma_f32 v[50:51], v[158:159], v[220:221], v[50:51]
	v_pk_fma_f32 v[60:61], v[168:169], v[218:219], v[60:61]
	v_pk_fma_f32 v[62:63], v[170:171], v[220:221], v[62:63]
	v_pk_fma_f32 v[72:73], v[180:181], v[218:219], v[72:73]
	v_pk_fma_f32 v[74:75], v[182:183], v[220:221], v[74:75]
	v_pk_fma_f32 v[84:85], v[192:193], v[218:219], v[84:85]
	v_pk_fma_f32 v[86:87], v[194:195], v[220:221], v[86:87]
	v_pk_fma_f32 v[96:97], v[108:109], v[218:219], v[96:97]
	v_pk_fma_f32 v[98:99], v[110:111], v[220:221], v[98:99]
	ds_read_b128 v[218:221], v2 offset:8192
	s_waitcnt vmcnt(9)
	s_add_i32 s52, s41, -21
	s_cmp_lt_i32 s52, 0
	s_cbranch_scc1 .Lcv_z9_zero
	v_lshlrev_b32_e32 v112, 16, v240
	v_and_b32_e32 v113, 0xffff0000, v240
	v_lshlrev_b32_e32 v114, 16, v241
	v_and_b32_e32 v115, 0xffff0000, v241
	v_lshlrev_b32_e32 v116, 16, v242
	v_and_b32_e32 v117, 0xffff0000, v242
	v_lshlrev_b32_e32 v118, 16, v243
	v_and_b32_e32 v119, 0xffff0000, v243
	v_lshlrev_b32_e32 v120, 16, v244
	v_and_b32_e32 v121, 0xffff0000, v244
	v_lshlrev_b32_e32 v122, 16, v245
	v_and_b32_e32 v123, 0xffff0000, v245
	s_branch .Lcv_z9_done

.Lcv_z9_done:
	s_add_i32 s52, s41, -15
	s_max_i32 s52, s52, 0
	s_mulk_i32 s52, 0x600
	v_add_u32_e32 v196, s52, v3
	global_load_dwordx2 v[240:241], v196, s[38:39]
	global_load_dwordx2 v[242:243], v196, s[38:39] offset:512
	global_load_dwordx2 v[244:245], v196, s[38:39] offset:1024
	s_waitcnt lgkmcnt(2)
	v_pk_fma_f32 v[4:5], v[124:125], v[210:211], v[4:5]
	v_pk_fma_f32 v[6:7], v[126:127], v[212:213], v[6:7]
	v_pk_fma_f32 v[16:17], v[136:137], v[210:211], v[16:17]
	v_pk_fma_f32 v[18:19], v[138:139], v[212:213], v[18:19]
	v_pk_fma_f32 v[28:29], v[148:149], v[210:211], v[28:29]
	v_pk_fma_f32 v[30:31], v[150:151], v[212:213], v[30:31]
	v_pk_fma_f32 v[40:41], v[160:161], v[210:211], v[40:41]
	v_pk_fma_f32 v[42:43], v[162:163], v[212:213], v[42:43]
	v_pk_fma_f32 v[52:53], v[172:173], v[210:211], v[52:53]
	v_pk_fma_f32 v[54:55], v[174:175], v[212:213], v[54:55]
	v_pk_fma_f32 v[64:65], v[184:185], v[210:211], v[64:65]
	v_pk_fma_f32 v[66:67], v[186:187], v[212:213], v[66:67]
	v_pk_fma_f32 v[76:77], v[100:101], v[210:211], v[76:77]
	v_pk_fma_f32 v[78:79], v[102:103], v[212:213], v[78:79]
	v_pk_fma_f32 v[88:89], v[112:113], v[210:211], v[88:89]
	v_pk_fma_f32 v[90:91], v[114:115], v[212:213], v[90:91]
	ds_read_b128 v[210:213], v2 offset:9216
	s_waitcnt lgkmcnt(2)
	v_pk_fma_f32 v[8:9], v[128:129], v[214:215], v[8:9]
	v_pk_fma_f32 v[10:11], v[130:131], v[216:217], v[10:11]
	v_pk_fma_f32 v[20:21], v[140:141], v[214:215], v[20:21]
	v_pk_fma_f32 v[22:23], v[142:143], v[216:217], v[22:23]
	v_pk_fma_f32 v[32:33], v[152:153], v[214:215], v[32:33]
	v_pk_fma_f32 v[34:35], v[154:155], v[216:217], v[34:35]
	v_pk_fma_f32 v[44:45], v[164:165], v[214:215], v[44:45]
	v_pk_fma_f32 v[46:47], v[166:167], v[216:217], v[46:47]
	v_pk_fma_f32 v[56:57], v[176:177], v[214:215], v[56:57]
	v_pk_fma_f32 v[58:59], v[178:179], v[216:217], v[58:59]
	v_pk_fma_f32 v[68:69], v[188:189], v[214:215], v[68:69]
	v_pk_fma_f32 v[70:71], v[190:191], v[216:217], v[70:71]
	v_pk_fma_f32 v[80:81], v[104:105], v[214:215], v[80:81]
	v_pk_fma_f32 v[82:83], v[106:107], v[216:217], v[82:83]
	v_pk_fma_f32 v[92:93], v[116:117], v[214:215], v[92:93]
	v_pk_fma_f32 v[94:95], v[118:119], v[216:217], v[94:95]
	ds_read_b128 v[214:217], v2 offset:10240
	s_waitcnt lgkmcnt(2)
	v_pk_fma_f32 v[12:13], v[132:133], v[218:219], v[12:13]
	v_pk_fma_f32 v[14:15], v[134:135], v[220:221], v[14:15]
	v_pk_fma_f32 v[24:25], v[144:145], v[218:219], v[24:25]
	v_pk_fma_f32 v[26:27], v[146:147], v[220:221], v[26:27]
	v_pk_fma_f32 v[36:37], v[156:157], v[218:219], v[36:37]
	v_pk_fma_f32 v[38:39], v[158:159], v[220:221], v[38:39]
	v_pk_fma_f32 v[48:49], v[168:169], v[218:219], v[48:49]
	v_pk_fma_f32 v[50:51], v[170:171], v[220:221], v[50:51]
	v_pk_fma_f32 v[60:61], v[180:181], v[218:219], v[60:61]
	v_pk_fma_f32 v[62:63], v[182:183], v[220:221], v[62:63]
	v_pk_fma_f32 v[72:73], v[192:193], v[218:219], v[72:73]
	v_pk_fma_f32 v[74:75], v[194:195], v[220:221], v[74:75]
	v_pk_fma_f32 v[84:85], v[108:109], v[218:219], v[84:85]
	v_pk_fma_f32 v[86:87], v[110:111], v[220:221], v[86:87]
	v_pk_fma_f32 v[96:97], v[120:121], v[218:219], v[96:97]
	v_pk_fma_f32 v[98:99], v[122:123], v[220:221], v[98:99]
	ds_read_b128 v[218:221], v2 offset:11264
	s_waitcnt vmcnt(9)
	s_add_i32 s52, s41, -20
	s_cmp_lt_i32 s52, 0
	s_cbranch_scc1 .Lcv_z10_zero
	v_lshlrev_b32_e32 v124, 16, v246
	v_and_b32_e32 v125, 0xffff0000, v246
	v_lshlrev_b32_e32 v126, 16, v247
	v_and_b32_e32 v127, 0xffff0000, v247
	v_lshlrev_b32_e32 v128, 16, v248
	v_and_b32_e32 v129, 0xffff0000, v248
	v_lshlrev_b32_e32 v130, 16, v249
	v_and_b32_e32 v131, 0xffff0000, v249
	v_lshlrev_b32_e32 v132, 16, v250
	v_and_b32_e32 v133, 0xffff0000, v250
	v_lshlrev_b32_e32 v134, 16, v251
	v_and_b32_e32 v135, 0xffff0000, v251
	s_branch .Lcv_z10_done

.Lcv_z10_done:
	s_add_i32 s52, s41, -14
	s_max_i32 s52, s52, 0
	s_mulk_i32 s52, 0x600
	v_add_u32_e32 v196, s52, v3
	global_load_dwordx2 v[246:247], v196, s[38:39]
	global_load_dwordx2 v[248:249], v196, s[38:39] offset:512
	global_load_dwordx2 v[250:251], v196, s[38:39] offset:1024
	s_waitcnt lgkmcnt(2)
	v_pk_fma_f32 v[4:5], v[136:137], v[210:211], v[4:5]
	v_pk_fma_f32 v[6:7], v[138:139], v[212:213], v[6:7]
	v_pk_fma_f32 v[16:17], v[148:149], v[210:211], v[16:17]
	v_pk_fma_f32 v[18:19], v[150:151], v[212:213], v[18:19]
	v_pk_fma_f32 v[28:29], v[160:161], v[210:211], v[28:29]
	v_pk_fma_f32 v[30:31], v[162:163], v[212:213], v[30:31]
	v_pk_fma_f32 v[40:41], v[172:173], v[210:211], v[40:41]
	v_pk_fma_f32 v[42:43], v[174:175], v[212:213], v[42:43]
	v_pk_fma_f32 v[52:53], v[184:185], v[210:211], v[52:53]
	v_pk_fma_f32 v[54:55], v[186:187], v[212:213], v[54:55]
	v_pk_fma_f32 v[64:65], v[100:101], v[210:211], v[64:65]
	v_pk_fma_f32 v[66:67], v[102:103], v[212:213], v[66:67]
	v_pk_fma_f32 v[76:77], v[112:113], v[210:211], v[76:77]
	v_pk_fma_f32 v[78:79], v[114:115], v[212:213], v[78:79]
	v_pk_fma_f32 v[88:89], v[124:125], v[210:211], v[88:89]
	v_pk_fma_f32 v[90:91], v[126:127], v[212:213], v[90:91]
	ds_read_b128 v[210:213], v2 offset:12288
	s_waitcnt lgkmcnt(2)
	v_pk_fma_f32 v[8:9], v[140:141], v[214:215], v[8:9]
	v_pk_fma_f32 v[10:11], v[142:143], v[216:217], v[10:11]
	v_pk_fma_f32 v[20:21], v[152:153], v[214:215], v[20:21]
	v_pk_fma_f32 v[22:23], v[154:155], v[216:217], v[22:23]
	v_pk_fma_f32 v[32:33], v[164:165], v[214:215], v[32:33]
	v_pk_fma_f32 v[34:35], v[166:167], v[216:217], v[34:35]
	v_pk_fma_f32 v[44:45], v[176:177], v[214:215], v[44:45]
	v_pk_fma_f32 v[46:47], v[178:179], v[216:217], v[46:47]
	v_pk_fma_f32 v[56:57], v[188:189], v[214:215], v[56:57]
	v_pk_fma_f32 v[58:59], v[190:191], v[216:217], v[58:59]
	v_pk_fma_f32 v[68:69], v[104:105], v[214:215], v[68:69]
	v_pk_fma_f32 v[70:71], v[106:107], v[216:217], v[70:71]
	v_pk_fma_f32 v[80:81], v[116:117], v[214:215], v[80:81]
	v_pk_fma_f32 v[82:83], v[118:119], v[216:217], v[82:83]
	v_pk_fma_f32 v[92:93], v[128:129], v[214:215], v[92:93]
	v_pk_fma_f32 v[94:95], v[130:131], v[216:217], v[94:95]
	ds_read_b128 v[214:217], v2 offset:13312
	s_waitcnt lgkmcnt(2)
	v_pk_fma_f32 v[12:13], v[144:145], v[218:219], v[12:13]
	v_pk_fma_f32 v[14:15], v[146:147], v[220:221], v[14:15]
	v_pk_fma_f32 v[24:25], v[156:157], v[218:219], v[24:25]
	v_pk_fma_f32 v[26:27], v[158:159], v[220:221], v[26:27]
	v_pk_fma_f32 v[36:37], v[168:169], v[218:219], v[36:37]
	v_pk_fma_f32 v[38:39], v[170:171], v[220:221], v[38:39]
	v_pk_fma_f32 v[48:49], v[180:181], v[218:219], v[48:49]
	v_pk_fma_f32 v[50:51], v[182:183], v[220:221], v[50:51]
	v_pk_fma_f32 v[60:61], v[192:193], v[218:219], v[60:61]
	v_pk_fma_f32 v[62:63], v[194:195], v[220:221], v[62:63]
	v_pk_fma_f32 v[72:73], v[108:109], v[218:219], v[72:73]
	v_pk_fma_f32 v[74:75], v[110:111], v[220:221], v[74:75]
	v_pk_fma_f32 v[84:85], v[120:121], v[218:219], v[84:85]
	v_pk_fma_f32 v[86:87], v[122:123], v[220:221], v[86:87]
	v_pk_fma_f32 v[96:97], v[132:133], v[218:219], v[96:97]
	v_pk_fma_f32 v[98:99], v[134:135], v[220:221], v[98:99]
	ds_read_b128 v[218:221], v2 offset:14336
	s_waitcnt vmcnt(9)
	s_add_i32 s52, s41, -19
	s_cmp_lt_i32 s52, 0
	s_cbranch_scc1 .Lcv_z11_zero
	v_lshlrev_b32_e32 v136, 16, v204
	v_and_b32_e32 v137, 0xffff0000, v204
	v_lshlrev_b32_e32 v138, 16, v205
	v_and_b32_e32 v139, 0xffff0000, v205
	v_lshlrev_b32_e32 v140, 16, v206
	v_and_b32_e32 v141, 0xffff0000, v206
	v_lshlrev_b32_e32 v142, 16, v207
	v_and_b32_e32 v143, 0xffff0000, v207
	v_lshlrev_b32_e32 v144, 16, v252
	v_and_b32_e32 v145, 0xffff0000, v252
	v_lshlrev_b32_e32 v146, 16, v253
	v_and_b32_e32 v147, 0xffff0000, v253
	s_branch .Lcv_z11_done

.Lcv_z11_done:
	s_add_i32 s52, s41, -13
	s_max_i32 s52, s52, 0
	s_mulk_i32 s52, 0x600
	v_add_u32_e32 v196, s52, v3
	global_load_dwordx2 v[204:205], v196, s[38:39]
	global_load_dwordx2 v[206:207], v196, s[38:39] offset:512
	global_load_dwordx2 v[252:253], v196, s[38:39] offset:1024
	s_waitcnt lgkmcnt(2)
	v_pk_fma_f32 v[4:5], v[148:149], v[210:211], v[4:5]
	v_pk_fma_f32 v[6:7], v[150:151], v[212:213], v[6:7]
	v_pk_fma_f32 v[16:17], v[160:161], v[210:211], v[16:17]
	v_pk_fma_f32 v[18:19], v[162:163], v[212:213], v[18:19]
	v_pk_fma_f32 v[28:29], v[172:173], v[210:211], v[28:29]
	v_pk_fma_f32 v[30:31], v[174:175], v[212:213], v[30:31]
	v_pk_fma_f32 v[40:41], v[184:185], v[210:211], v[40:41]
	v_pk_fma_f32 v[42:43], v[186:187], v[212:213], v[42:43]
	v_pk_fma_f32 v[52:53], v[100:101], v[210:211], v[52:53]
	v_pk_fma_f32 v[54:55], v[102:103], v[212:213], v[54:55]
	v_pk_fma_f32 v[64:65], v[112:113], v[210:211], v[64:65]
	v_pk_fma_f32 v[66:67], v[114:115], v[212:213], v[66:67]
	v_pk_fma_f32 v[76:77], v[124:125], v[210:211], v[76:77]
	v_pk_fma_f32 v[78:79], v[126:127], v[212:213], v[78:79]
	v_pk_fma_f32 v[88:89], v[136:137], v[210:211], v[88:89]
	v_pk_fma_f32 v[90:91], v[138:139], v[212:213], v[90:91]
	ds_read_b128 v[210:213], v2 offset:15360
	s_waitcnt lgkmcnt(2)
	v_pk_fma_f32 v[8:9], v[152:153], v[214:215], v[8:9]
	v_pk_fma_f32 v[10:11], v[154:155], v[216:217], v[10:11]
	v_pk_fma_f32 v[20:21], v[164:165], v[214:215], v[20:21]
	v_pk_fma_f32 v[22:23], v[166:167], v[216:217], v[22:23]
	v_pk_fma_f32 v[32:33], v[176:177], v[214:215], v[32:33]
	v_pk_fma_f32 v[34:35], v[178:179], v[216:217], v[34:35]
	v_pk_fma_f32 v[44:45], v[188:189], v[214:215], v[44:45]
	v_pk_fma_f32 v[46:47], v[190:191], v[216:217], v[46:47]
	v_pk_fma_f32 v[56:57], v[104:105], v[214:215], v[56:57]
	v_pk_fma_f32 v[58:59], v[106:107], v[216:217], v[58:59]
	v_pk_fma_f32 v[68:69], v[116:117], v[214:215], v[68:69]
	v_pk_fma_f32 v[70:71], v[118:119], v[216:217], v[70:71]
	v_pk_fma_f32 v[80:81], v[128:129], v[214:215], v[80:81]
	v_pk_fma_f32 v[82:83], v[130:131], v[216:217], v[82:83]
	v_pk_fma_f32 v[92:93], v[140:141], v[214:215], v[92:93]
	v_pk_fma_f32 v[94:95], v[142:143], v[216:217], v[94:95]
	ds_read_b128 v[214:217], v2 offset:16384
	s_waitcnt lgkmcnt(2)
	v_pk_fma_f32 v[12:13], v[156:157], v[218:219], v[12:13]
	v_pk_fma_f32 v[14:15], v[158:159], v[220:221], v[14:15]
	v_pk_fma_f32 v[24:25], v[168:169], v[218:219], v[24:25]
	v_pk_fma_f32 v[26:27], v[170:171], v[220:221], v[26:27]
	v_pk_fma_f32 v[36:37], v[180:181], v[218:219], v[36:37]
	v_pk_fma_f32 v[38:39], v[182:183], v[220:221], v[38:39]
	v_pk_fma_f32 v[48:49], v[192:193], v[218:219], v[48:49]
	v_pk_fma_f32 v[50:51], v[194:195], v[220:221], v[50:51]
	v_pk_fma_f32 v[60:61], v[108:109], v[218:219], v[60:61]
	v_pk_fma_f32 v[62:63], v[110:111], v[220:221], v[62:63]
	v_pk_fma_f32 v[72:73], v[120:121], v[218:219], v[72:73]
	v_pk_fma_f32 v[74:75], v[122:123], v[220:221], v[74:75]
	v_pk_fma_f32 v[84:85], v[132:133], v[218:219], v[84:85]
	v_pk_fma_f32 v[86:87], v[134:135], v[220:221], v[86:87]
	v_pk_fma_f32 v[96:97], v[144:145], v[218:219], v[96:97]
	v_pk_fma_f32 v[98:99], v[146:147], v[220:221], v[98:99]
	ds_read_b128 v[218:221], v2 offset:17408
	s_add_i32 s52, s41, -18
	s_cmp_lt_i32 s52, 0
	s_cbranch_scc1 .Lcv_z12_zero
	v_lshlrev_b32_e32 v148, 16, v222
	v_and_b32_e32 v149, 0xffff0000, v222
	v_lshlrev_b32_e32 v150, 16, v223
	v_and_b32_e32 v151, 0xffff0000, v223
	v_lshlrev_b32_e32 v152, 16, v224
	v_and_b32_e32 v153, 0xffff0000, v224
	v_lshlrev_b32_e32 v154, 16, v225
	v_and_b32_e32 v155, 0xffff0000, v225
	v_lshlrev_b32_e32 v156, 16, v226
	v_and_b32_e32 v157, 0xffff0000, v226
	v_lshlrev_b32_e32 v158, 16, v227
	v_and_b32_e32 v159, 0xffff0000, v227
	s_branch .Lcv_z12_done

.Lcv_z12_done:
	s_add_i32 s52, s41, -12
	s_max_i32 s52, s52, 0
	s_mulk_i32 s52, 0x600
	v_add_u32_e32 v196, s52, v3
	global_load_dwordx2 v[222:223], v196, s[38:39]
	global_load_dwordx2 v[224:225], v196, s[38:39] offset:512
	global_load_dwordx2 v[226:227], v196, s[38:39] offset:1024
	s_waitcnt lgkmcnt(2)
	v_pk_fma_f32 v[4:5], v[160:161], v[210:211], v[4:5]
	v_pk_fma_f32 v[6:7], v[162:163], v[212:213], v[6:7]
	v_pk_fma_f32 v[16:17], v[172:173], v[210:211], v[16:17]
	v_pk_fma_f32 v[18:19], v[174:175], v[212:213], v[18:19]
	v_pk_fma_f32 v[28:29], v[184:185], v[210:211], v[28:29]
	v_pk_fma_f32 v[30:31], v[186:187], v[212:213], v[30:31]
	v_pk_fma_f32 v[40:41], v[100:101], v[210:211], v[40:41]
	v_pk_fma_f32 v[42:43], v[102:103], v[212:213], v[42:43]
	v_pk_fma_f32 v[52:53], v[112:113], v[210:211], v[52:53]
	v_pk_fma_f32 v[54:55], v[114:115], v[212:213], v[54:55]
	v_pk_fma_f32 v[64:65], v[124:125], v[210:211], v[64:65]
	v_pk_fma_f32 v[66:67], v[126:127], v[212:213], v[66:67]
	v_pk_fma_f32 v[76:77], v[136:137], v[210:211], v[76:77]
	v_pk_fma_f32 v[78:79], v[138:139], v[212:213], v[78:79]
	v_pk_fma_f32 v[88:89], v[148:149], v[210:211], v[88:89]
	v_pk_fma_f32 v[90:91], v[150:151], v[212:213], v[90:91]
	ds_read_b128 v[210:213], v2 offset:18432
	s_waitcnt lgkmcnt(2)
	v_pk_fma_f32 v[8:9], v[164:165], v[214:215], v[8:9]
	v_pk_fma_f32 v[10:11], v[166:167], v[216:217], v[10:11]
	v_pk_fma_f32 v[20:21], v[176:177], v[214:215], v[20:21]
	v_pk_fma_f32 v[22:23], v[178:179], v[216:217], v[22:23]
	v_pk_fma_f32 v[32:33], v[188:189], v[214:215], v[32:33]
	v_pk_fma_f32 v[34:35], v[190:191], v[216:217], v[34:35]
	v_pk_fma_f32 v[44:45], v[104:105], v[214:215], v[44:45]
	v_pk_fma_f32 v[46:47], v[106:107], v[216:217], v[46:47]
	v_pk_fma_f32 v[56:57], v[116:117], v[214:215], v[56:57]
	v_pk_fma_f32 v[58:59], v[118:119], v[216:217], v[58:59]
	v_pk_fma_f32 v[68:69], v[128:129], v[214:215], v[68:69]
	v_pk_fma_f32 v[70:71], v[130:131], v[216:217], v[70:71]
	v_pk_fma_f32 v[80:81], v[140:141], v[214:215], v[80:81]
	v_pk_fma_f32 v[82:83], v[142:143], v[216:217], v[82:83]
	v_pk_fma_f32 v[92:93], v[152:153], v[214:215], v[92:93]
	v_pk_fma_f32 v[94:95], v[154:155], v[216:217], v[94:95]
	ds_read_b128 v[214:217], v2 offset:19456
	s_waitcnt lgkmcnt(2)
	v_pk_fma_f32 v[12:13], v[168:169], v[218:219], v[12:13]
	v_pk_fma_f32 v[14:15], v[170:171], v[220:221], v[14:15]
	v_pk_fma_f32 v[24:25], v[180:181], v[218:219], v[24:25]
	v_pk_fma_f32 v[26:27], v[182:183], v[220:221], v[26:27]
	v_pk_fma_f32 v[36:37], v[192:193], v[218:219], v[36:37]
	v_pk_fma_f32 v[38:39], v[194:195], v[220:221], v[38:39]
	v_pk_fma_f32 v[48:49], v[108:109], v[218:219], v[48:49]
	v_pk_fma_f32 v[50:51], v[110:111], v[220:221], v[50:51]
	v_pk_fma_f32 v[60:61], v[120:121], v[218:219], v[60:61]
	v_pk_fma_f32 v[62:63], v[122:123], v[220:221], v[62:63]
	v_pk_fma_f32 v[72:73], v[132:133], v[218:219], v[72:73]
	v_pk_fma_f32 v[74:75], v[134:135], v[220:221], v[74:75]
	v_pk_fma_f32 v[84:85], v[144:145], v[218:219], v[84:85]
	v_pk_fma_f32 v[86:87], v[146:147], v[220:221], v[86:87]
	v_pk_fma_f32 v[96:97], v[156:157], v[218:219], v[96:97]
	v_pk_fma_f32 v[98:99], v[158:159], v[220:221], v[98:99]
	ds_read_b128 v[218:221], v2 offset:20480
	s_add_i32 s52, s41, -17
	s_cmp_lt_i32 s52, 0
	s_cbranch_scc1 .Lcv_z13_zero
	v_lshlrev_b32_e32 v160, 16, v228
	v_and_b32_e32 v161, 0xffff0000, v228
	v_lshlrev_b32_e32 v162, 16, v229
	v_and_b32_e32 v163, 0xffff0000, v229
	v_lshlrev_b32_e32 v164, 16, v230
	v_and_b32_e32 v165, 0xffff0000, v230
	v_lshlrev_b32_e32 v166, 16, v231
	v_and_b32_e32 v167, 0xffff0000, v231
	v_lshlrev_b32_e32 v168, 16, v232
	v_and_b32_e32 v169, 0xffff0000, v232
	v_lshlrev_b32_e32 v170, 16, v233
	v_and_b32_e32 v171, 0xffff0000, v233
	s_branch .Lcv_z13_done

.Lcv_z13_done:
	s_add_i32 s52, s41, -11
	s_max_i32 s52, s52, 0
	s_mulk_i32 s52, 0x600
	v_add_u32_e32 v196, s52, v3
	global_load_dwordx2 v[228:229], v196, s[38:39]
	global_load_dwordx2 v[230:231], v196, s[38:39] offset:512
	global_load_dwordx2 v[232:233], v196, s[38:39] offset:1024
	s_waitcnt lgkmcnt(2)
	v_pk_fma_f32 v[4:5], v[172:173], v[210:211], v[4:5]
	v_pk_fma_f32 v[6:7], v[174:175], v[212:213], v[6:7]
	v_pk_fma_f32 v[16:17], v[184:185], v[210:211], v[16:17]
	v_pk_fma_f32 v[18:19], v[186:187], v[212:213], v[18:19]
	v_pk_fma_f32 v[28:29], v[100:101], v[210:211], v[28:29]
	v_pk_fma_f32 v[30:31], v[102:103], v[212:213], v[30:31]
	v_pk_fma_f32 v[40:41], v[112:113], v[210:211], v[40:41]
	v_pk_fma_f32 v[42:43], v[114:115], v[212:213], v[42:43]
	v_pk_fma_f32 v[52:53], v[124:125], v[210:211], v[52:53]
	v_pk_fma_f32 v[54:55], v[126:127], v[212:213], v[54:55]
	v_pk_fma_f32 v[64:65], v[136:137], v[210:211], v[64:65]
	v_pk_fma_f32 v[66:67], v[138:139], v[212:213], v[66:67]
	v_pk_fma_f32 v[76:77], v[148:149], v[210:211], v[76:77]
	v_pk_fma_f32 v[78:79], v[150:151], v[212:213], v[78:79]
	v_pk_fma_f32 v[88:89], v[160:161], v[210:211], v[88:89]
	v_pk_fma_f32 v[90:91], v[162:163], v[212:213], v[90:91]
	ds_read_b128 v[210:213], v2 offset:21504
	s_waitcnt lgkmcnt(2)
	v_pk_fma_f32 v[8:9], v[176:177], v[214:215], v[8:9]
	v_pk_fma_f32 v[10:11], v[178:179], v[216:217], v[10:11]
	v_pk_fma_f32 v[20:21], v[188:189], v[214:215], v[20:21]
	v_pk_fma_f32 v[22:23], v[190:191], v[216:217], v[22:23]
	v_pk_fma_f32 v[32:33], v[104:105], v[214:215], v[32:33]
	v_pk_fma_f32 v[34:35], v[106:107], v[216:217], v[34:35]
	v_pk_fma_f32 v[44:45], v[116:117], v[214:215], v[44:45]
	v_pk_fma_f32 v[46:47], v[118:119], v[216:217], v[46:47]
	v_pk_fma_f32 v[56:57], v[128:129], v[214:215], v[56:57]
	v_pk_fma_f32 v[58:59], v[130:131], v[216:217], v[58:59]
	v_pk_fma_f32 v[68:69], v[140:141], v[214:215], v[68:69]
	v_pk_fma_f32 v[70:71], v[142:143], v[216:217], v[70:71]
	v_pk_fma_f32 v[80:81], v[152:153], v[214:215], v[80:81]
	v_pk_fma_f32 v[82:83], v[154:155], v[216:217], v[82:83]
	v_pk_fma_f32 v[92:93], v[164:165], v[214:215], v[92:93]
	v_pk_fma_f32 v[94:95], v[166:167], v[216:217], v[94:95]
	ds_read_b128 v[214:217], v2 offset:22528
	s_waitcnt lgkmcnt(2)
	v_pk_fma_f32 v[12:13], v[180:181], v[218:219], v[12:13]
	v_pk_fma_f32 v[14:15], v[182:183], v[220:221], v[14:15]
	v_pk_fma_f32 v[24:25], v[192:193], v[218:219], v[24:25]
	v_pk_fma_f32 v[26:27], v[194:195], v[220:221], v[26:27]
	v_pk_fma_f32 v[36:37], v[108:109], v[218:219], v[36:37]
	v_pk_fma_f32 v[38:39], v[110:111], v[220:221], v[38:39]
	v_pk_fma_f32 v[48:49], v[120:121], v[218:219], v[48:49]
	v_pk_fma_f32 v[50:51], v[122:123], v[220:221], v[50:51]
	v_pk_fma_f32 v[60:61], v[132:133], v[218:219], v[60:61]
	v_pk_fma_f32 v[62:63], v[134:135], v[220:221], v[62:63]
	v_pk_fma_f32 v[72:73], v[144:145], v[218:219], v[72:73]
	v_pk_fma_f32 v[74:75], v[146:147], v[220:221], v[74:75]
	v_pk_fma_f32 v[84:85], v[156:157], v[218:219], v[84:85]
	v_pk_fma_f32 v[86:87], v[158:159], v[220:221], v[86:87]
	v_pk_fma_f32 v[96:97], v[168:169], v[218:219], v[96:97]
	v_pk_fma_f32 v[98:99], v[170:171], v[220:221], v[98:99]
	ds_read_b128 v[218:221], v2 offset:23552
	s_waitcnt vmcnt(15)
	s_add_i32 s52, s41, -16
	s_cmp_lt_i32 s52, 0
	s_cbranch_scc1 .Lcv_z14_zero
	v_lshlrev_b32_e32 v172, 16, v234
	v_and_b32_e32 v173, 0xffff0000, v234
	v_lshlrev_b32_e32 v174, 16, v235
	v_and_b32_e32 v175, 0xffff0000, v235
	v_lshlrev_b32_e32 v176, 16, v236
	v_and_b32_e32 v177, 0xffff0000, v236
	v_lshlrev_b32_e32 v178, 16, v237
	v_and_b32_e32 v179, 0xffff0000, v237
	v_lshlrev_b32_e32 v180, 16, v238
	v_and_b32_e32 v181, 0xffff0000, v238
	v_lshlrev_b32_e32 v182, 16, v239
	v_and_b32_e32 v183, 0xffff0000, v239
	s_branch .Lcv_z14_done

.Lcv_z14_done:
	s_add_i32 s52, s41, -10
	s_max_i32 s52, s52, 0
	s_mulk_i32 s52, 0x600
	v_add_u32_e32 v196, s52, v3
	global_load_dwordx2 v[234:235], v196, s[38:39]
	global_load_dwordx2 v[236:237], v196, s[38:39] offset:512
	global_load_dwordx2 v[238:239], v196, s[38:39] offset:1024
	s_waitcnt lgkmcnt(2)
	v_pk_fma_f32 v[4:5], v[184:185], v[210:211], v[4:5]
	v_pk_fma_f32 v[6:7], v[186:187], v[212:213], v[6:7]
	v_pk_fma_f32 v[16:17], v[100:101], v[210:211], v[16:17]
	v_pk_fma_f32 v[18:19], v[102:103], v[212:213], v[18:19]
	v_pk_fma_f32 v[28:29], v[112:113], v[210:211], v[28:29]
	v_pk_fma_f32 v[30:31], v[114:115], v[212:213], v[30:31]
	v_pk_fma_f32 v[40:41], v[124:125], v[210:211], v[40:41]
	v_pk_fma_f32 v[42:43], v[126:127], v[212:213], v[42:43]
	v_pk_fma_f32 v[52:53], v[136:137], v[210:211], v[52:53]
	v_pk_fma_f32 v[54:55], v[138:139], v[212:213], v[54:55]
	v_pk_fma_f32 v[64:65], v[148:149], v[210:211], v[64:65]
	v_pk_fma_f32 v[66:67], v[150:151], v[212:213], v[66:67]
	v_pk_fma_f32 v[76:77], v[160:161], v[210:211], v[76:77]
	v_pk_fma_f32 v[78:79], v[162:163], v[212:213], v[78:79]
	v_pk_fma_f32 v[88:89], v[172:173], v[210:211], v[88:89]
	v_pk_fma_f32 v[90:91], v[174:175], v[212:213], v[90:91]
	ds_read_b128 v[210:213], v2 offset:24576
	s_waitcnt lgkmcnt(2)
	v_pk_fma_f32 v[8:9], v[188:189], v[214:215], v[8:9]
	v_pk_fma_f32 v[10:11], v[190:191], v[216:217], v[10:11]
	v_pk_fma_f32 v[20:21], v[104:105], v[214:215], v[20:21]
	v_pk_fma_f32 v[22:23], v[106:107], v[216:217], v[22:23]
	v_pk_fma_f32 v[32:33], v[116:117], v[214:215], v[32:33]
	v_pk_fma_f32 v[34:35], v[118:119], v[216:217], v[34:35]
	v_pk_fma_f32 v[44:45], v[128:129], v[214:215], v[44:45]
	v_pk_fma_f32 v[46:47], v[130:131], v[216:217], v[46:47]
	v_pk_fma_f32 v[56:57], v[140:141], v[214:215], v[56:57]
	v_pk_fma_f32 v[58:59], v[142:143], v[216:217], v[58:59]
	v_pk_fma_f32 v[68:69], v[152:153], v[214:215], v[68:69]
	v_pk_fma_f32 v[70:71], v[154:155], v[216:217], v[70:71]
	v_pk_fma_f32 v[80:81], v[164:165], v[214:215], v[80:81]
	v_pk_fma_f32 v[82:83], v[166:167], v[216:217], v[82:83]
	v_pk_fma_f32 v[92:93], v[176:177], v[214:215], v[92:93]
	v_pk_fma_f32 v[94:95], v[178:179], v[216:217], v[94:95]
	ds_read_b128 v[214:217], v2 offset:25600
	s_waitcnt lgkmcnt(2)
	v_pk_fma_f32 v[12:13], v[192:193], v[218:219], v[12:13]
	v_pk_fma_f32 v[14:15], v[194:195], v[220:221], v[14:15]
	v_pk_fma_f32 v[24:25], v[108:109], v[218:219], v[24:25]
	v_pk_fma_f32 v[26:27], v[110:111], v[220:221], v[26:27]
	v_pk_fma_f32 v[36:37], v[120:121], v[218:219], v[36:37]
	v_pk_fma_f32 v[38:39], v[122:123], v[220:221], v[38:39]
	v_pk_fma_f32 v[48:49], v[132:133], v[218:219], v[48:49]
	v_pk_fma_f32 v[50:51], v[134:135], v[220:221], v[50:51]
	v_pk_fma_f32 v[60:61], v[144:145], v[218:219], v[60:61]
	v_pk_fma_f32 v[62:63], v[146:147], v[220:221], v[62:63]
	v_pk_fma_f32 v[72:73], v[156:157], v[218:219], v[72:73]
	v_pk_fma_f32 v[74:75], v[158:159], v[220:221], v[74:75]
	v_pk_fma_f32 v[84:85], v[168:169], v[218:219], v[84:85]
	v_pk_fma_f32 v[86:87], v[170:171], v[220:221], v[86:87]
	v_pk_fma_f32 v[96:97], v[180:181], v[218:219], v[96:97]
	v_pk_fma_f32 v[98:99], v[182:183], v[220:221], v[98:99]
	ds_read_b128 v[218:221], v2 offset:26624
	s_waitcnt vmcnt(15)
	s_add_i32 s52, s41, -15
	s_cmp_lt_i32 s52, 0
	s_cbranch_scc1 .Lcv_z15_zero
	v_lshlrev_b32_e32 v184, 16, v240
	v_and_b32_e32 v185, 0xffff0000, v240
	v_lshlrev_b32_e32 v186, 16, v241
	v_and_b32_e32 v187, 0xffff0000, v241
	v_lshlrev_b32_e32 v188, 16, v242
	v_and_b32_e32 v189, 0xffff0000, v242
	v_lshlrev_b32_e32 v190, 16, v243
	v_and_b32_e32 v191, 0xffff0000, v243
	v_lshlrev_b32_e32 v192, 16, v244
	v_and_b32_e32 v193, 0xffff0000, v244
	v_lshlrev_b32_e32 v194, 16, v245
	v_and_b32_e32 v195, 0xffff0000, v245
	s_branch .Lcv_z15_done

.Lcv_z15_done:
	s_add_i32 s52, s41, -9
	s_max_i32 s52, s52, 0
	s_mulk_i32 s52, 0x600
	v_add_u32_e32 v196, s52, v3
	global_load_dwordx2 v[240:241], v196, s[38:39]
	global_load_dwordx2 v[242:243], v196, s[38:39] offset:512
	global_load_dwordx2 v[244:245], v196, s[38:39] offset:1024
	s_waitcnt lgkmcnt(2)
	v_pk_fma_f32 v[4:5], v[100:101], v[210:211], v[4:5]
	v_pk_fma_f32 v[6:7], v[102:103], v[212:213], v[6:7]
	v_pk_fma_f32 v[16:17], v[112:113], v[210:211], v[16:17]
	v_pk_fma_f32 v[18:19], v[114:115], v[212:213], v[18:19]
	v_pk_fma_f32 v[28:29], v[124:125], v[210:211], v[28:29]
	v_pk_fma_f32 v[30:31], v[126:127], v[212:213], v[30:31]
	v_pk_fma_f32 v[40:41], v[136:137], v[210:211], v[40:41]
	v_pk_fma_f32 v[42:43], v[138:139], v[212:213], v[42:43]
	v_pk_fma_f32 v[52:53], v[148:149], v[210:211], v[52:53]
	v_pk_fma_f32 v[54:55], v[150:151], v[212:213], v[54:55]
	v_pk_fma_f32 v[64:65], v[160:161], v[210:211], v[64:65]
	v_pk_fma_f32 v[66:67], v[162:163], v[212:213], v[66:67]
	v_pk_fma_f32 v[76:77], v[172:173], v[210:211], v[76:77]
	v_pk_fma_f32 v[78:79], v[174:175], v[212:213], v[78:79]
	v_pk_fma_f32 v[88:89], v[184:185], v[210:211], v[88:89]
	v_pk_fma_f32 v[90:91], v[186:187], v[212:213], v[90:91]
	ds_read_b128 v[210:213], v2 offset:27648
	s_waitcnt lgkmcnt(2)
	v_pk_fma_f32 v[8:9], v[104:105], v[214:215], v[8:9]
	v_pk_fma_f32 v[10:11], v[106:107], v[216:217], v[10:11]
	v_pk_fma_f32 v[20:21], v[116:117], v[214:215], v[20:21]
	v_pk_fma_f32 v[22:23], v[118:119], v[216:217], v[22:23]
	v_pk_fma_f32 v[32:33], v[128:129], v[214:215], v[32:33]
	v_pk_fma_f32 v[34:35], v[130:131], v[216:217], v[34:35]
	v_pk_fma_f32 v[44:45], v[140:141], v[214:215], v[44:45]
	v_pk_fma_f32 v[46:47], v[142:143], v[216:217], v[46:47]
	v_pk_fma_f32 v[56:57], v[152:153], v[214:215], v[56:57]
	v_pk_fma_f32 v[58:59], v[154:155], v[216:217], v[58:59]
	v_pk_fma_f32 v[68:69], v[164:165], v[214:215], v[68:69]
	v_pk_fma_f32 v[70:71], v[166:167], v[216:217], v[70:71]
	v_pk_fma_f32 v[80:81], v[176:177], v[214:215], v[80:81]
	v_pk_fma_f32 v[82:83], v[178:179], v[216:217], v[82:83]
	v_pk_fma_f32 v[92:93], v[188:189], v[214:215], v[92:93]
	v_pk_fma_f32 v[94:95], v[190:191], v[216:217], v[94:95]
	ds_read_b128 v[214:217], v2 offset:28672
	s_waitcnt lgkmcnt(2)
	v_pk_fma_f32 v[12:13], v[108:109], v[218:219], v[12:13]
	v_pk_fma_f32 v[14:15], v[110:111], v[220:221], v[14:15]
	v_pk_fma_f32 v[24:25], v[120:121], v[218:219], v[24:25]
	v_pk_fma_f32 v[26:27], v[122:123], v[220:221], v[26:27]
	v_pk_fma_f32 v[36:37], v[132:133], v[218:219], v[36:37]
	v_pk_fma_f32 v[38:39], v[134:135], v[220:221], v[38:39]
	v_pk_fma_f32 v[48:49], v[144:145], v[218:219], v[48:49]
	v_pk_fma_f32 v[50:51], v[146:147], v[220:221], v[50:51]
	v_pk_fma_f32 v[60:61], v[156:157], v[218:219], v[60:61]
	v_pk_fma_f32 v[62:63], v[158:159], v[220:221], v[62:63]
	v_pk_fma_f32 v[72:73], v[168:169], v[218:219], v[72:73]
	v_pk_fma_f32 v[74:75], v[170:171], v[220:221], v[74:75]
	v_pk_fma_f32 v[84:85], v[180:181], v[218:219], v[84:85]
	v_pk_fma_f32 v[86:87], v[182:183], v[220:221], v[86:87]
	v_pk_fma_f32 v[96:97], v[192:193], v[218:219], v[96:97]
	v_pk_fma_f32 v[98:99], v[194:195], v[220:221], v[98:99]
	ds_read_b128 v[218:221], v2 offset:29696
	s_waitcnt vmcnt(15)
	s_add_i32 s52, s41, -14
	s_cmp_lt_i32 s52, 0
	s_cbranch_scc1 .Lcv_z16_zero
	v_lshlrev_b32_e32 v100, 16, v246
	v_and_b32_e32 v101, 0xffff0000, v246
	v_lshlrev_b32_e32 v102, 16, v247
	v_and_b32_e32 v103, 0xffff0000, v247
	v_lshlrev_b32_e32 v104, 16, v248
	v_and_b32_e32 v105, 0xffff0000, v248
	v_lshlrev_b32_e32 v106, 16, v249
	v_and_b32_e32 v107, 0xffff0000, v249
	v_lshlrev_b32_e32 v108, 16, v250
	v_and_b32_e32 v109, 0xffff0000, v250
	v_lshlrev_b32_e32 v110, 16, v251
	v_and_b32_e32 v111, 0xffff0000, v251
	s_branch .Lcv_z16_done

.Lcv_z16_done:
	s_add_i32 s52, s41, -8
	s_max_i32 s52, s52, 0
	s_mulk_i32 s52, 0x600
	v_add_u32_e32 v196, s52, v3
	global_load_dwordx2 v[246:247], v196, s[38:39]
	global_load_dwordx2 v[248:249], v196, s[38:39] offset:512
	global_load_dwordx2 v[250:251], v196, s[38:39] offset:1024
	s_waitcnt lgkmcnt(2)
	v_pk_fma_f32 v[4:5], v[112:113], v[210:211], v[4:5]
	v_pk_fma_f32 v[6:7], v[114:115], v[212:213], v[6:7]
	v_pk_fma_f32 v[16:17], v[124:125], v[210:211], v[16:17]
	v_pk_fma_f32 v[18:19], v[126:127], v[212:213], v[18:19]
	v_pk_fma_f32 v[28:29], v[136:137], v[210:211], v[28:29]
	v_pk_fma_f32 v[30:31], v[138:139], v[212:213], v[30:31]
	v_pk_fma_f32 v[40:41], v[148:149], v[210:211], v[40:41]
	v_pk_fma_f32 v[42:43], v[150:151], v[212:213], v[42:43]
	v_pk_fma_f32 v[52:53], v[160:161], v[210:211], v[52:53]
	v_pk_fma_f32 v[54:55], v[162:163], v[212:213], v[54:55]
	v_pk_fma_f32 v[64:65], v[172:173], v[210:211], v[64:65]
	v_pk_fma_f32 v[66:67], v[174:175], v[212:213], v[66:67]
	v_pk_fma_f32 v[76:77], v[184:185], v[210:211], v[76:77]
	v_pk_fma_f32 v[78:79], v[186:187], v[212:213], v[78:79]
	v_pk_fma_f32 v[88:89], v[100:101], v[210:211], v[88:89]
	v_pk_fma_f32 v[90:91], v[102:103], v[212:213], v[90:91]
	ds_read_b128 v[210:213], v2 offset:30720
	s_waitcnt lgkmcnt(2)
	v_pk_fma_f32 v[8:9], v[116:117], v[214:215], v[8:9]
	v_pk_fma_f32 v[10:11], v[118:119], v[216:217], v[10:11]
	v_pk_fma_f32 v[20:21], v[128:129], v[214:215], v[20:21]
	v_pk_fma_f32 v[22:23], v[130:131], v[216:217], v[22:23]
	v_pk_fma_f32 v[32:33], v[140:141], v[214:215], v[32:33]
	v_pk_fma_f32 v[34:35], v[142:143], v[216:217], v[34:35]
	v_pk_fma_f32 v[44:45], v[152:153], v[214:215], v[44:45]
	v_pk_fma_f32 v[46:47], v[154:155], v[216:217], v[46:47]
	v_pk_fma_f32 v[56:57], v[164:165], v[214:215], v[56:57]
	v_pk_fma_f32 v[58:59], v[166:167], v[216:217], v[58:59]
	v_pk_fma_f32 v[68:69], v[176:177], v[214:215], v[68:69]
	v_pk_fma_f32 v[70:71], v[178:179], v[216:217], v[70:71]
	v_pk_fma_f32 v[80:81], v[188:189], v[214:215], v[80:81]
	v_pk_fma_f32 v[82:83], v[190:191], v[216:217], v[82:83]
	v_pk_fma_f32 v[92:93], v[104:105], v[214:215], v[92:93]
	v_pk_fma_f32 v[94:95], v[106:107], v[216:217], v[94:95]
	ds_read_b128 v[214:217], v2 offset:31744
	s_waitcnt lgkmcnt(2)
	v_pk_fma_f32 v[12:13], v[120:121], v[218:219], v[12:13]
	v_pk_fma_f32 v[14:15], v[122:123], v[220:221], v[14:15]
	v_pk_fma_f32 v[24:25], v[132:133], v[218:219], v[24:25]
	v_pk_fma_f32 v[26:27], v[134:135], v[220:221], v[26:27]
	v_pk_fma_f32 v[36:37], v[144:145], v[218:219], v[36:37]
	v_pk_fma_f32 v[38:39], v[146:147], v[220:221], v[38:39]
	v_pk_fma_f32 v[48:49], v[156:157], v[218:219], v[48:49]
	v_pk_fma_f32 v[50:51], v[158:159], v[220:221], v[50:51]
	v_pk_fma_f32 v[60:61], v[168:169], v[218:219], v[60:61]
	v_pk_fma_f32 v[62:63], v[170:171], v[220:221], v[62:63]
	v_pk_fma_f32 v[72:73], v[180:181], v[218:219], v[72:73]
	v_pk_fma_f32 v[74:75], v[182:183], v[220:221], v[74:75]
	v_pk_fma_f32 v[84:85], v[192:193], v[218:219], v[84:85]
	v_pk_fma_f32 v[86:87], v[194:195], v[220:221], v[86:87]
	v_pk_fma_f32 v[96:97], v[108:109], v[218:219], v[96:97]
	v_pk_fma_f32 v[98:99], v[110:111], v[220:221], v[98:99]
	ds_read_b128 v[218:221], v2 offset:32768
	s_waitcnt vmcnt(15)
	s_add_i32 s52, s41, -13
	s_cmp_lt_i32 s52, 0
	s_cbranch_scc1 .Lcv_z17_zero
	v_lshlrev_b32_e32 v112, 16, v204
	v_and_b32_e32 v113, 0xffff0000, v204
	v_lshlrev_b32_e32 v114, 16, v205
	v_and_b32_e32 v115, 0xffff0000, v205
	v_lshlrev_b32_e32 v116, 16, v206
	v_and_b32_e32 v117, 0xffff0000, v206
	v_lshlrev_b32_e32 v118, 16, v207
	v_and_b32_e32 v119, 0xffff0000, v207
	v_lshlrev_b32_e32 v120, 16, v252
	v_and_b32_e32 v121, 0xffff0000, v252
	v_lshlrev_b32_e32 v122, 16, v253
	v_and_b32_e32 v123, 0xffff0000, v253
	s_branch .Lcv_z17_done

.Lcv_z17_done:
	s_add_i32 s52, s41, -7
	s_max_i32 s52, s52, 0
	s_mulk_i32 s52, 0x600
	v_add_u32_e32 v196, s52, v3
	global_load_dwordx2 v[204:205], v196, s[38:39]
	global_load_dwordx2 v[206:207], v196, s[38:39] offset:512
	global_load_dwordx2 v[252:253], v196, s[38:39] offset:1024
	s_waitcnt lgkmcnt(2)
	v_pk_fma_f32 v[4:5], v[124:125], v[210:211], v[4:5]
	v_pk_fma_f32 v[6:7], v[126:127], v[212:213], v[6:7]
	v_pk_fma_f32 v[16:17], v[136:137], v[210:211], v[16:17]
	v_pk_fma_f32 v[18:19], v[138:139], v[212:213], v[18:19]
	v_pk_fma_f32 v[28:29], v[148:149], v[210:211], v[28:29]
	v_pk_fma_f32 v[30:31], v[150:151], v[212:213], v[30:31]
	v_pk_fma_f32 v[40:41], v[160:161], v[210:211], v[40:41]
	v_pk_fma_f32 v[42:43], v[162:163], v[212:213], v[42:43]
	v_pk_fma_f32 v[52:53], v[172:173], v[210:211], v[52:53]
	v_pk_fma_f32 v[54:55], v[174:175], v[212:213], v[54:55]
	v_pk_fma_f32 v[64:65], v[184:185], v[210:211], v[64:65]
	v_pk_fma_f32 v[66:67], v[186:187], v[212:213], v[66:67]
	v_pk_fma_f32 v[76:77], v[100:101], v[210:211], v[76:77]
	v_pk_fma_f32 v[78:79], v[102:103], v[212:213], v[78:79]
	v_pk_fma_f32 v[88:89], v[112:113], v[210:211], v[88:89]
	v_pk_fma_f32 v[90:91], v[114:115], v[212:213], v[90:91]
	ds_read_b128 v[210:213], v2 offset:33792
	s_waitcnt lgkmcnt(2)
	v_pk_fma_f32 v[8:9], v[128:129], v[214:215], v[8:9]
	v_pk_fma_f32 v[10:11], v[130:131], v[216:217], v[10:11]
	v_pk_fma_f32 v[20:21], v[140:141], v[214:215], v[20:21]
	v_pk_fma_f32 v[22:23], v[142:143], v[216:217], v[22:23]
	v_pk_fma_f32 v[32:33], v[152:153], v[214:215], v[32:33]
	v_pk_fma_f32 v[34:35], v[154:155], v[216:217], v[34:35]
	v_pk_fma_f32 v[44:45], v[164:165], v[214:215], v[44:45]
	v_pk_fma_f32 v[46:47], v[166:167], v[216:217], v[46:47]
	v_pk_fma_f32 v[56:57], v[176:177], v[214:215], v[56:57]
	v_pk_fma_f32 v[58:59], v[178:179], v[216:217], v[58:59]
	v_pk_fma_f32 v[68:69], v[188:189], v[214:215], v[68:69]
	v_pk_fma_f32 v[70:71], v[190:191], v[216:217], v[70:71]
	v_pk_fma_f32 v[80:81], v[104:105], v[214:215], v[80:81]
	v_pk_fma_f32 v[82:83], v[106:107], v[216:217], v[82:83]
	v_pk_fma_f32 v[92:93], v[116:117], v[214:215], v[92:93]
	v_pk_fma_f32 v[94:95], v[118:119], v[216:217], v[94:95]
	ds_read_b128 v[214:217], v2 offset:34816
	s_waitcnt lgkmcnt(2)
	v_pk_fma_f32 v[12:13], v[132:133], v[218:219], v[12:13]
	v_pk_fma_f32 v[14:15], v[134:135], v[220:221], v[14:15]
	v_pk_fma_f32 v[24:25], v[144:145], v[218:219], v[24:25]
	v_pk_fma_f32 v[26:27], v[146:147], v[220:221], v[26:27]
	v_pk_fma_f32 v[36:37], v[156:157], v[218:219], v[36:37]
	v_pk_fma_f32 v[38:39], v[158:159], v[220:221], v[38:39]
	v_pk_fma_f32 v[48:49], v[168:169], v[218:219], v[48:49]
	v_pk_fma_f32 v[50:51], v[170:171], v[220:221], v[50:51]
	v_pk_fma_f32 v[60:61], v[180:181], v[218:219], v[60:61]
	v_pk_fma_f32 v[62:63], v[182:183], v[220:221], v[62:63]
	v_pk_fma_f32 v[72:73], v[192:193], v[218:219], v[72:73]
	v_pk_fma_f32 v[74:75], v[194:195], v[220:221], v[74:75]
	v_pk_fma_f32 v[84:85], v[108:109], v[218:219], v[84:85]
	v_pk_fma_f32 v[86:87], v[110:111], v[220:221], v[86:87]
	v_pk_fma_f32 v[96:97], v[120:121], v[218:219], v[96:97]
	v_pk_fma_f32 v[98:99], v[122:123], v[220:221], v[98:99]
	ds_read_b128 v[218:221], v2 offset:35840
	s_waitcnt vmcnt(15)
	s_add_i32 s52, s41, -12
	s_cmp_lt_i32 s52, 0
	s_cbranch_scc1 .Lcv_z18_zero
	v_lshlrev_b32_e32 v124, 16, v222
	v_and_b32_e32 v125, 0xffff0000, v222
	v_lshlrev_b32_e32 v126, 16, v223
	v_and_b32_e32 v127, 0xffff0000, v223
	v_lshlrev_b32_e32 v128, 16, v224
	v_and_b32_e32 v129, 0xffff0000, v224
	v_lshlrev_b32_e32 v130, 16, v225
	v_and_b32_e32 v131, 0xffff0000, v225
	v_lshlrev_b32_e32 v132, 16, v226
	v_and_b32_e32 v133, 0xffff0000, v226
	v_lshlrev_b32_e32 v134, 16, v227
	v_and_b32_e32 v135, 0xffff0000, v227
	s_branch .Lcv_z18_done

.Lcv_z18_done:
	s_add_i32 s52, s41, -6
	s_max_i32 s52, s52, 0
	s_mulk_i32 s52, 0x600
	v_add_u32_e32 v196, s52, v3
	global_load_dwordx2 v[222:223], v196, s[38:39]
	global_load_dwordx2 v[224:225], v196, s[38:39] offset:512
	global_load_dwordx2 v[226:227], v196, s[38:39] offset:1024
	s_waitcnt lgkmcnt(2)
	v_pk_fma_f32 v[4:5], v[136:137], v[210:211], v[4:5]
	v_pk_fma_f32 v[6:7], v[138:139], v[212:213], v[6:7]
	v_pk_fma_f32 v[16:17], v[148:149], v[210:211], v[16:17]
	v_pk_fma_f32 v[18:19], v[150:151], v[212:213], v[18:19]
	v_pk_fma_f32 v[28:29], v[160:161], v[210:211], v[28:29]
	v_pk_fma_f32 v[30:31], v[162:163], v[212:213], v[30:31]
	v_pk_fma_f32 v[40:41], v[172:173], v[210:211], v[40:41]
	v_pk_fma_f32 v[42:43], v[174:175], v[212:213], v[42:43]
	v_pk_fma_f32 v[52:53], v[184:185], v[210:211], v[52:53]
	v_pk_fma_f32 v[54:55], v[186:187], v[212:213], v[54:55]
	v_pk_fma_f32 v[64:65], v[100:101], v[210:211], v[64:65]
	v_pk_fma_f32 v[66:67], v[102:103], v[212:213], v[66:67]
	v_pk_fma_f32 v[76:77], v[112:113], v[210:211], v[76:77]
	v_pk_fma_f32 v[78:79], v[114:115], v[212:213], v[78:79]
	v_pk_fma_f32 v[88:89], v[124:125], v[210:211], v[88:89]
	v_pk_fma_f32 v[90:91], v[126:127], v[212:213], v[90:91]
	ds_read_b128 v[210:213], v2 offset:36864
	s_waitcnt lgkmcnt(2)
	v_pk_fma_f32 v[8:9], v[140:141], v[214:215], v[8:9]
	v_pk_fma_f32 v[10:11], v[142:143], v[216:217], v[10:11]
	v_pk_fma_f32 v[20:21], v[152:153], v[214:215], v[20:21]
	v_pk_fma_f32 v[22:23], v[154:155], v[216:217], v[22:23]
	v_pk_fma_f32 v[32:33], v[164:165], v[214:215], v[32:33]
	v_pk_fma_f32 v[34:35], v[166:167], v[216:217], v[34:35]
	v_pk_fma_f32 v[44:45], v[176:177], v[214:215], v[44:45]
	v_pk_fma_f32 v[46:47], v[178:179], v[216:217], v[46:47]
	v_pk_fma_f32 v[56:57], v[188:189], v[214:215], v[56:57]
	v_pk_fma_f32 v[58:59], v[190:191], v[216:217], v[58:59]
	v_pk_fma_f32 v[68:69], v[104:105], v[214:215], v[68:69]
	v_pk_fma_f32 v[70:71], v[106:107], v[216:217], v[70:71]
	v_pk_fma_f32 v[80:81], v[116:117], v[214:215], v[80:81]
	v_pk_fma_f32 v[82:83], v[118:119], v[216:217], v[82:83]
	v_pk_fma_f32 v[92:93], v[128:129], v[214:215], v[92:93]
	v_pk_fma_f32 v[94:95], v[130:131], v[216:217], v[94:95]
	ds_read_b128 v[214:217], v2 offset:37888
	s_waitcnt lgkmcnt(2)
	v_pk_fma_f32 v[12:13], v[144:145], v[218:219], v[12:13]
	v_pk_fma_f32 v[14:15], v[146:147], v[220:221], v[14:15]
	v_pk_fma_f32 v[24:25], v[156:157], v[218:219], v[24:25]
	v_pk_fma_f32 v[26:27], v[158:159], v[220:221], v[26:27]
	v_pk_fma_f32 v[36:37], v[168:169], v[218:219], v[36:37]
	v_pk_fma_f32 v[38:39], v[170:171], v[220:221], v[38:39]
	v_pk_fma_f32 v[48:49], v[180:181], v[218:219], v[48:49]
	v_pk_fma_f32 v[50:51], v[182:183], v[220:221], v[50:51]
	v_pk_fma_f32 v[60:61], v[192:193], v[218:219], v[60:61]
	v_pk_fma_f32 v[62:63], v[194:195], v[220:221], v[62:63]
	v_pk_fma_f32 v[72:73], v[108:109], v[218:219], v[72:73]
	v_pk_fma_f32 v[74:75], v[110:111], v[220:221], v[74:75]
	v_pk_fma_f32 v[84:85], v[120:121], v[218:219], v[84:85]
	v_pk_fma_f32 v[86:87], v[122:123], v[220:221], v[86:87]
	v_pk_fma_f32 v[96:97], v[132:133], v[218:219], v[96:97]
	v_pk_fma_f32 v[98:99], v[134:135], v[220:221], v[98:99]
	ds_read_b128 v[218:221], v2 offset:38912
	s_waitcnt vmcnt(15)
	s_add_i32 s52, s41, -11
	s_cmp_lt_i32 s52, 0
	s_cbranch_scc1 .Lcv_z19_zero
	v_lshlrev_b32_e32 v136, 16, v228
	v_and_b32_e32 v137, 0xffff0000, v228
	v_lshlrev_b32_e32 v138, 16, v229
	v_and_b32_e32 v139, 0xffff0000, v229
	v_lshlrev_b32_e32 v140, 16, v230
	v_and_b32_e32 v141, 0xffff0000, v230
	v_lshlrev_b32_e32 v142, 16, v231
	v_and_b32_e32 v143, 0xffff0000, v231
	v_lshlrev_b32_e32 v144, 16, v232
	v_and_b32_e32 v145, 0xffff0000, v232
	v_lshlrev_b32_e32 v146, 16, v233
	v_and_b32_e32 v147, 0xffff0000, v233
	s_branch .Lcv_z19_done

.Lcv_z19_done:
	s_add_i32 s52, s41, -5
	s_max_i32 s52, s52, 0
	s_mulk_i32 s52, 0x600
	v_add_u32_e32 v196, s52, v3
	global_load_dwordx2 v[228:229], v196, s[38:39]
	global_load_dwordx2 v[230:231], v196, s[38:39] offset:512
	global_load_dwordx2 v[232:233], v196, s[38:39] offset:1024
	s_waitcnt lgkmcnt(2)
	v_pk_fma_f32 v[4:5], v[148:149], v[210:211], v[4:5]
	v_pk_fma_f32 v[6:7], v[150:151], v[212:213], v[6:7]
	v_pk_fma_f32 v[16:17], v[160:161], v[210:211], v[16:17]
	v_pk_fma_f32 v[18:19], v[162:163], v[212:213], v[18:19]
	v_pk_fma_f32 v[28:29], v[172:173], v[210:211], v[28:29]
	v_pk_fma_f32 v[30:31], v[174:175], v[212:213], v[30:31]
	v_pk_fma_f32 v[40:41], v[184:185], v[210:211], v[40:41]
	v_pk_fma_f32 v[42:43], v[186:187], v[212:213], v[42:43]
	v_pk_fma_f32 v[52:53], v[100:101], v[210:211], v[52:53]
	v_pk_fma_f32 v[54:55], v[102:103], v[212:213], v[54:55]
	v_pk_fma_f32 v[64:65], v[112:113], v[210:211], v[64:65]
	v_pk_fma_f32 v[66:67], v[114:115], v[212:213], v[66:67]
	v_pk_fma_f32 v[76:77], v[124:125], v[210:211], v[76:77]
	v_pk_fma_f32 v[78:79], v[126:127], v[212:213], v[78:79]
	v_pk_fma_f32 v[88:89], v[136:137], v[210:211], v[88:89]
	v_pk_fma_f32 v[90:91], v[138:139], v[212:213], v[90:91]
	ds_read_b128 v[210:213], v2 offset:39936
	s_waitcnt lgkmcnt(2)
	v_pk_fma_f32 v[8:9], v[152:153], v[214:215], v[8:9]
	v_pk_fma_f32 v[10:11], v[154:155], v[216:217], v[10:11]
	v_pk_fma_f32 v[20:21], v[164:165], v[214:215], v[20:21]
	v_pk_fma_f32 v[22:23], v[166:167], v[216:217], v[22:23]
	v_pk_fma_f32 v[32:33], v[176:177], v[214:215], v[32:33]
	v_pk_fma_f32 v[34:35], v[178:179], v[216:217], v[34:35]
	v_pk_fma_f32 v[44:45], v[188:189], v[214:215], v[44:45]
	v_pk_fma_f32 v[46:47], v[190:191], v[216:217], v[46:47]
	v_pk_fma_f32 v[56:57], v[104:105], v[214:215], v[56:57]
	v_pk_fma_f32 v[58:59], v[106:107], v[216:217], v[58:59]
	v_pk_fma_f32 v[68:69], v[116:117], v[214:215], v[68:69]
	v_pk_fma_f32 v[70:71], v[118:119], v[216:217], v[70:71]
	v_pk_fma_f32 v[80:81], v[128:129], v[214:215], v[80:81]
	v_pk_fma_f32 v[82:83], v[130:131], v[216:217], v[82:83]
	v_pk_fma_f32 v[92:93], v[140:141], v[214:215], v[92:93]
	v_pk_fma_f32 v[94:95], v[142:143], v[216:217], v[94:95]
	ds_read_b128 v[214:217], v2 offset:40960
	s_waitcnt lgkmcnt(2)
	v_pk_fma_f32 v[12:13], v[156:157], v[218:219], v[12:13]
	v_pk_fma_f32 v[14:15], v[158:159], v[220:221], v[14:15]
	v_pk_fma_f32 v[24:25], v[168:169], v[218:219], v[24:25]
	v_pk_fma_f32 v[26:27], v[170:171], v[220:221], v[26:27]
	v_pk_fma_f32 v[36:37], v[180:181], v[218:219], v[36:37]
	v_pk_fma_f32 v[38:39], v[182:183], v[220:221], v[38:39]
	v_pk_fma_f32 v[48:49], v[192:193], v[218:219], v[48:49]
	v_pk_fma_f32 v[50:51], v[194:195], v[220:221], v[50:51]
	v_pk_fma_f32 v[60:61], v[108:109], v[218:219], v[60:61]
	v_pk_fma_f32 v[62:63], v[110:111], v[220:221], v[62:63]
	v_pk_fma_f32 v[72:73], v[120:121], v[218:219], v[72:73]
	v_pk_fma_f32 v[74:75], v[122:123], v[220:221], v[74:75]
	v_pk_fma_f32 v[84:85], v[132:133], v[218:219], v[84:85]
	v_pk_fma_f32 v[86:87], v[134:135], v[220:221], v[86:87]
	v_pk_fma_f32 v[96:97], v[144:145], v[218:219], v[96:97]
	v_pk_fma_f32 v[98:99], v[146:147], v[220:221], v[98:99]
	ds_read_b128 v[218:221], v2 offset:41984
	s_waitcnt vmcnt(15)
	s_add_i32 s52, s41, -10
	s_cmp_lt_i32 s52, 0
	s_cbranch_scc1 .Lcv_z20_zero
	v_lshlrev_b32_e32 v148, 16, v234
	v_and_b32_e32 v149, 0xffff0000, v234
	v_lshlrev_b32_e32 v150, 16, v235
	v_and_b32_e32 v151, 0xffff0000, v235
	v_lshlrev_b32_e32 v152, 16, v236
	v_and_b32_e32 v153, 0xffff0000, v236
	v_lshlrev_b32_e32 v154, 16, v237
	v_and_b32_e32 v155, 0xffff0000, v237
	v_lshlrev_b32_e32 v156, 16, v238
	v_and_b32_e32 v157, 0xffff0000, v238
	v_lshlrev_b32_e32 v158, 16, v239
	v_and_b32_e32 v159, 0xffff0000, v239
	s_branch .Lcv_z20_done

.Lcv_z20_done:
	s_add_i32 s52, s41, -4
	s_max_i32 s52, s52, 0
	s_mulk_i32 s52, 0x600
	v_add_u32_e32 v196, s52, v3
	global_load_dwordx2 v[234:235], v196, s[38:39]
	global_load_dwordx2 v[236:237], v196, s[38:39] offset:512
	global_load_dwordx2 v[238:239], v196, s[38:39] offset:1024
	s_waitcnt lgkmcnt(2)
	v_pk_fma_f32 v[4:5], v[160:161], v[210:211], v[4:5]
	v_pk_fma_f32 v[6:7], v[162:163], v[212:213], v[6:7]
	v_pk_fma_f32 v[16:17], v[172:173], v[210:211], v[16:17]
	v_pk_fma_f32 v[18:19], v[174:175], v[212:213], v[18:19]
	v_pk_fma_f32 v[28:29], v[184:185], v[210:211], v[28:29]
	v_pk_fma_f32 v[30:31], v[186:187], v[212:213], v[30:31]
	v_pk_fma_f32 v[40:41], v[100:101], v[210:211], v[40:41]
	v_pk_fma_f32 v[42:43], v[102:103], v[212:213], v[42:43]
	v_pk_fma_f32 v[52:53], v[112:113], v[210:211], v[52:53]
	v_pk_fma_f32 v[54:55], v[114:115], v[212:213], v[54:55]
	v_pk_fma_f32 v[64:65], v[124:125], v[210:211], v[64:65]
	v_pk_fma_f32 v[66:67], v[126:127], v[212:213], v[66:67]
	v_pk_fma_f32 v[76:77], v[136:137], v[210:211], v[76:77]
	v_pk_fma_f32 v[78:79], v[138:139], v[212:213], v[78:79]
	v_pk_fma_f32 v[88:89], v[148:149], v[210:211], v[88:89]
	v_pk_fma_f32 v[90:91], v[150:151], v[212:213], v[90:91]
	ds_read_b128 v[210:213], v2 offset:43008
	s_waitcnt lgkmcnt(2)
	v_pk_fma_f32 v[8:9], v[164:165], v[214:215], v[8:9]
	v_pk_fma_f32 v[10:11], v[166:167], v[216:217], v[10:11]
	v_pk_fma_f32 v[20:21], v[176:177], v[214:215], v[20:21]
	v_pk_fma_f32 v[22:23], v[178:179], v[216:217], v[22:23]
	v_pk_fma_f32 v[32:33], v[188:189], v[214:215], v[32:33]
	v_pk_fma_f32 v[34:35], v[190:191], v[216:217], v[34:35]
	v_pk_fma_f32 v[44:45], v[104:105], v[214:215], v[44:45]
	v_pk_fma_f32 v[46:47], v[106:107], v[216:217], v[46:47]
	v_pk_fma_f32 v[56:57], v[116:117], v[214:215], v[56:57]
	v_pk_fma_f32 v[58:59], v[118:119], v[216:217], v[58:59]
	v_pk_fma_f32 v[68:69], v[128:129], v[214:215], v[68:69]
	v_pk_fma_f32 v[70:71], v[130:131], v[216:217], v[70:71]
	v_pk_fma_f32 v[80:81], v[140:141], v[214:215], v[80:81]
	v_pk_fma_f32 v[82:83], v[142:143], v[216:217], v[82:83]
	v_pk_fma_f32 v[92:93], v[152:153], v[214:215], v[92:93]
	v_pk_fma_f32 v[94:95], v[154:155], v[216:217], v[94:95]
	ds_read_b128 v[214:217], v2 offset:44032
	s_waitcnt lgkmcnt(2)
	v_pk_fma_f32 v[12:13], v[168:169], v[218:219], v[12:13]
	v_pk_fma_f32 v[14:15], v[170:171], v[220:221], v[14:15]
	v_pk_fma_f32 v[24:25], v[180:181], v[218:219], v[24:25]
	v_pk_fma_f32 v[26:27], v[182:183], v[220:221], v[26:27]
	v_pk_fma_f32 v[36:37], v[192:193], v[218:219], v[36:37]
	v_pk_fma_f32 v[38:39], v[194:195], v[220:221], v[38:39]
	v_pk_fma_f32 v[48:49], v[108:109], v[218:219], v[48:49]
	v_pk_fma_f32 v[50:51], v[110:111], v[220:221], v[50:51]
	v_pk_fma_f32 v[60:61], v[120:121], v[218:219], v[60:61]
	v_pk_fma_f32 v[62:63], v[122:123], v[220:221], v[62:63]
	v_pk_fma_f32 v[72:73], v[132:133], v[218:219], v[72:73]
	v_pk_fma_f32 v[74:75], v[134:135], v[220:221], v[74:75]
	v_pk_fma_f32 v[84:85], v[144:145], v[218:219], v[84:85]
	v_pk_fma_f32 v[86:87], v[146:147], v[220:221], v[86:87]
	v_pk_fma_f32 v[96:97], v[156:157], v[218:219], v[96:97]
	v_pk_fma_f32 v[98:99], v[158:159], v[220:221], v[98:99]
	ds_read_b128 v[218:221], v2 offset:45056
	s_waitcnt vmcnt(15)
	s_add_i32 s52, s41, -9
	s_cmp_lt_i32 s52, 0
	s_cbranch_scc1 .Lcv_z21_zero
	v_lshlrev_b32_e32 v160, 16, v240
	v_and_b32_e32 v161, 0xffff0000, v240
	v_lshlrev_b32_e32 v162, 16, v241
	v_and_b32_e32 v163, 0xffff0000, v241
	v_lshlrev_b32_e32 v164, 16, v242
	v_and_b32_e32 v165, 0xffff0000, v242
	v_lshlrev_b32_e32 v166, 16, v243
	v_and_b32_e32 v167, 0xffff0000, v243
	v_lshlrev_b32_e32 v168, 16, v244
	v_and_b32_e32 v169, 0xffff0000, v244
	v_lshlrev_b32_e32 v170, 16, v245
	v_and_b32_e32 v171, 0xffff0000, v245
	s_branch .Lcv_z21_done

.Lcv_z21_done:
	s_add_i32 s52, s41, -3
	s_max_i32 s52, s52, 0
	s_mulk_i32 s52, 0x600
	v_add_u32_e32 v196, s52, v3
	global_load_dwordx2 v[240:241], v196, s[38:39]
	global_load_dwordx2 v[242:243], v196, s[38:39] offset:512
	global_load_dwordx2 v[244:245], v196, s[38:39] offset:1024
	s_waitcnt lgkmcnt(2)
	v_pk_fma_f32 v[4:5], v[172:173], v[210:211], v[4:5]
	v_pk_fma_f32 v[6:7], v[174:175], v[212:213], v[6:7]
	v_pk_fma_f32 v[16:17], v[184:185], v[210:211], v[16:17]
	v_pk_fma_f32 v[18:19], v[186:187], v[212:213], v[18:19]
	v_pk_fma_f32 v[28:29], v[100:101], v[210:211], v[28:29]
	v_pk_fma_f32 v[30:31], v[102:103], v[212:213], v[30:31]
	v_pk_fma_f32 v[40:41], v[112:113], v[210:211], v[40:41]
	v_pk_fma_f32 v[42:43], v[114:115], v[212:213], v[42:43]
	v_pk_fma_f32 v[52:53], v[124:125], v[210:211], v[52:53]
	v_pk_fma_f32 v[54:55], v[126:127], v[212:213], v[54:55]
	v_pk_fma_f32 v[64:65], v[136:137], v[210:211], v[64:65]
	v_pk_fma_f32 v[66:67], v[138:139], v[212:213], v[66:67]
	v_pk_fma_f32 v[76:77], v[148:149], v[210:211], v[76:77]
	v_pk_fma_f32 v[78:79], v[150:151], v[212:213], v[78:79]
	v_pk_fma_f32 v[88:89], v[160:161], v[210:211], v[88:89]
	v_pk_fma_f32 v[90:91], v[162:163], v[212:213], v[90:91]
	ds_read_b128 v[210:213], v2 offset:46080
	s_waitcnt lgkmcnt(2)
	v_pk_fma_f32 v[8:9], v[176:177], v[214:215], v[8:9]
	v_pk_fma_f32 v[10:11], v[178:179], v[216:217], v[10:11]
	v_pk_fma_f32 v[20:21], v[188:189], v[214:215], v[20:21]
	v_pk_fma_f32 v[22:23], v[190:191], v[216:217], v[22:23]
	v_pk_fma_f32 v[32:33], v[104:105], v[214:215], v[32:33]
	v_pk_fma_f32 v[34:35], v[106:107], v[216:217], v[34:35]
	v_pk_fma_f32 v[44:45], v[116:117], v[214:215], v[44:45]
	v_pk_fma_f32 v[46:47], v[118:119], v[216:217], v[46:47]
	v_pk_fma_f32 v[56:57], v[128:129], v[214:215], v[56:57]
	v_pk_fma_f32 v[58:59], v[130:131], v[216:217], v[58:59]
	v_pk_fma_f32 v[68:69], v[140:141], v[214:215], v[68:69]
	v_pk_fma_f32 v[70:71], v[142:143], v[216:217], v[70:71]
	v_pk_fma_f32 v[80:81], v[152:153], v[214:215], v[80:81]
	v_pk_fma_f32 v[82:83], v[154:155], v[216:217], v[82:83]
	v_pk_fma_f32 v[92:93], v[164:165], v[214:215], v[92:93]
	v_pk_fma_f32 v[94:95], v[166:167], v[216:217], v[94:95]
	ds_read_b128 v[214:217], v2 offset:47104
	s_waitcnt lgkmcnt(2)
	v_pk_fma_f32 v[12:13], v[180:181], v[218:219], v[12:13]
	v_pk_fma_f32 v[14:15], v[182:183], v[220:221], v[14:15]
	v_pk_fma_f32 v[24:25], v[192:193], v[218:219], v[24:25]
	v_pk_fma_f32 v[26:27], v[194:195], v[220:221], v[26:27]
	v_pk_fma_f32 v[36:37], v[108:109], v[218:219], v[36:37]
	v_pk_fma_f32 v[38:39], v[110:111], v[220:221], v[38:39]
	v_pk_fma_f32 v[48:49], v[120:121], v[218:219], v[48:49]
	v_pk_fma_f32 v[50:51], v[122:123], v[220:221], v[50:51]
	v_pk_fma_f32 v[60:61], v[132:133], v[218:219], v[60:61]
	v_pk_fma_f32 v[62:63], v[134:135], v[220:221], v[62:63]
	v_pk_fma_f32 v[72:73], v[144:145], v[218:219], v[72:73]
	v_pk_fma_f32 v[74:75], v[146:147], v[220:221], v[74:75]
	v_pk_fma_f32 v[84:85], v[156:157], v[218:219], v[84:85]
	v_pk_fma_f32 v[86:87], v[158:159], v[220:221], v[86:87]
	v_pk_fma_f32 v[96:97], v[168:169], v[218:219], v[96:97]
	v_pk_fma_f32 v[98:99], v[170:171], v[220:221], v[98:99]
	ds_read_b128 v[218:221], v2 offset:48128
	s_waitcnt vmcnt(15)
	s_add_i32 s52, s41, -8
	s_cmp_lt_i32 s52, 0
	s_cbranch_scc1 .Lcv_z22_zero
	v_lshlrev_b32_e32 v172, 16, v246
	v_and_b32_e32 v173, 0xffff0000, v246
	v_lshlrev_b32_e32 v174, 16, v247
	v_and_b32_e32 v175, 0xffff0000, v247
	v_lshlrev_b32_e32 v176, 16, v248
	v_and_b32_e32 v177, 0xffff0000, v248
	v_lshlrev_b32_e32 v178, 16, v249
	v_and_b32_e32 v179, 0xffff0000, v249
	v_lshlrev_b32_e32 v180, 16, v250
	v_and_b32_e32 v181, 0xffff0000, v250
	v_lshlrev_b32_e32 v182, 16, v251
	v_and_b32_e32 v183, 0xffff0000, v251
	s_branch .Lcv_z22_done

.Lcv_z22_done:
	s_add_i32 s52, s41, -2
	s_max_i32 s52, s52, 0
	s_mulk_i32 s52, 0x600
	v_add_u32_e32 v196, s52, v3
	global_load_dwordx2 v[246:247], v196, s[38:39]
	global_load_dwordx2 v[248:249], v196, s[38:39] offset:512
	global_load_dwordx2 v[250:251], v196, s[38:39] offset:1024
	s_waitcnt lgkmcnt(2)
	v_pk_fma_f32 v[4:5], v[184:185], v[210:211], v[4:5]
	v_pk_fma_f32 v[6:7], v[186:187], v[212:213], v[6:7]
	v_pk_fma_f32 v[16:17], v[100:101], v[210:211], v[16:17]
	v_pk_fma_f32 v[18:19], v[102:103], v[212:213], v[18:19]
	v_pk_fma_f32 v[28:29], v[112:113], v[210:211], v[28:29]
	v_pk_fma_f32 v[30:31], v[114:115], v[212:213], v[30:31]
	v_pk_fma_f32 v[40:41], v[124:125], v[210:211], v[40:41]
	v_pk_fma_f32 v[42:43], v[126:127], v[212:213], v[42:43]
	v_pk_fma_f32 v[52:53], v[136:137], v[210:211], v[52:53]
	v_pk_fma_f32 v[54:55], v[138:139], v[212:213], v[54:55]
	v_pk_fma_f32 v[64:65], v[148:149], v[210:211], v[64:65]
	v_pk_fma_f32 v[66:67], v[150:151], v[212:213], v[66:67]
	v_pk_fma_f32 v[76:77], v[160:161], v[210:211], v[76:77]
	v_pk_fma_f32 v[78:79], v[162:163], v[212:213], v[78:79]
	v_pk_fma_f32 v[88:89], v[172:173], v[210:211], v[88:89]
	v_pk_fma_f32 v[90:91], v[174:175], v[212:213], v[90:91]
	ds_read_b128 v[210:213], v2 offset:49152
	s_waitcnt lgkmcnt(2)
	v_pk_fma_f32 v[8:9], v[188:189], v[214:215], v[8:9]
	v_pk_fma_f32 v[10:11], v[190:191], v[216:217], v[10:11]
	v_pk_fma_f32 v[20:21], v[104:105], v[214:215], v[20:21]
	v_pk_fma_f32 v[22:23], v[106:107], v[216:217], v[22:23]
	v_pk_fma_f32 v[32:33], v[116:117], v[214:215], v[32:33]
	v_pk_fma_f32 v[34:35], v[118:119], v[216:217], v[34:35]
	v_pk_fma_f32 v[44:45], v[128:129], v[214:215], v[44:45]
	v_pk_fma_f32 v[46:47], v[130:131], v[216:217], v[46:47]
	v_pk_fma_f32 v[56:57], v[140:141], v[214:215], v[56:57]
	v_pk_fma_f32 v[58:59], v[142:143], v[216:217], v[58:59]
	v_pk_fma_f32 v[68:69], v[152:153], v[214:215], v[68:69]
	v_pk_fma_f32 v[70:71], v[154:155], v[216:217], v[70:71]
	v_pk_fma_f32 v[80:81], v[164:165], v[214:215], v[80:81]
	v_pk_fma_f32 v[82:83], v[166:167], v[216:217], v[82:83]
	v_pk_fma_f32 v[92:93], v[176:177], v[214:215], v[92:93]
	v_pk_fma_f32 v[94:95], v[178:179], v[216:217], v[94:95]
	ds_read_b128 v[214:217], v2 offset:50176
	s_waitcnt lgkmcnt(2)
	v_pk_fma_f32 v[12:13], v[192:193], v[218:219], v[12:13]
	v_pk_fma_f32 v[14:15], v[194:195], v[220:221], v[14:15]
	v_pk_fma_f32 v[24:25], v[108:109], v[218:219], v[24:25]
	v_pk_fma_f32 v[26:27], v[110:111], v[220:221], v[26:27]
	v_pk_fma_f32 v[36:37], v[120:121], v[218:219], v[36:37]
	v_pk_fma_f32 v[38:39], v[122:123], v[220:221], v[38:39]
	v_pk_fma_f32 v[48:49], v[132:133], v[218:219], v[48:49]
	v_pk_fma_f32 v[50:51], v[134:135], v[220:221], v[50:51]
	v_pk_fma_f32 v[60:61], v[144:145], v[218:219], v[60:61]
	v_pk_fma_f32 v[62:63], v[146:147], v[220:221], v[62:63]
	v_pk_fma_f32 v[72:73], v[156:157], v[218:219], v[72:73]
	v_pk_fma_f32 v[74:75], v[158:159], v[220:221], v[74:75]
	v_pk_fma_f32 v[84:85], v[168:169], v[218:219], v[84:85]
	v_pk_fma_f32 v[86:87], v[170:171], v[220:221], v[86:87]
	v_pk_fma_f32 v[96:97], v[180:181], v[218:219], v[96:97]
	v_pk_fma_f32 v[98:99], v[182:183], v[220:221], v[98:99]
	ds_read_b128 v[218:221], v2 offset:51200
	s_waitcnt vmcnt(15)
	s_add_i32 s52, s41, -7
	s_cmp_lt_i32 s52, 0
	s_cbranch_scc1 .Lcv_z23_zero
	v_lshlrev_b32_e32 v184, 16, v204
	v_and_b32_e32 v185, 0xffff0000, v204
	v_lshlrev_b32_e32 v186, 16, v205
	v_and_b32_e32 v187, 0xffff0000, v205
	v_lshlrev_b32_e32 v188, 16, v206
	v_and_b32_e32 v189, 0xffff0000, v206
	v_lshlrev_b32_e32 v190, 16, v207
	v_and_b32_e32 v191, 0xffff0000, v207
	v_lshlrev_b32_e32 v192, 16, v252
	v_and_b32_e32 v193, 0xffff0000, v252
	v_lshlrev_b32_e32 v194, 16, v253
	v_and_b32_e32 v195, 0xffff0000, v253
	s_branch .Lcv_z23_done

.Lcv_z23_done:
	s_add_i32 s52, s41, -1
	s_max_i32 s52, s52, 0
	s_mulk_i32 s52, 0x600
	v_add_u32_e32 v196, s52, v3
	global_load_dwordx2 v[204:205], v196, s[38:39]
	global_load_dwordx2 v[206:207], v196, s[38:39] offset:512
	global_load_dwordx2 v[252:253], v196, s[38:39] offset:1024
	s_waitcnt lgkmcnt(2)
	v_pk_fma_f32 v[4:5], v[100:101], v[210:211], v[4:5]
	v_pk_fma_f32 v[6:7], v[102:103], v[212:213], v[6:7]
	v_pk_fma_f32 v[16:17], v[112:113], v[210:211], v[16:17]
	v_pk_fma_f32 v[18:19], v[114:115], v[212:213], v[18:19]
	v_pk_fma_f32 v[28:29], v[124:125], v[210:211], v[28:29]
	v_pk_fma_f32 v[30:31], v[126:127], v[212:213], v[30:31]
	v_pk_fma_f32 v[40:41], v[136:137], v[210:211], v[40:41]
	v_pk_fma_f32 v[42:43], v[138:139], v[212:213], v[42:43]
	v_pk_fma_f32 v[52:53], v[148:149], v[210:211], v[52:53]
	v_pk_fma_f32 v[54:55], v[150:151], v[212:213], v[54:55]
	v_pk_fma_f32 v[64:65], v[160:161], v[210:211], v[64:65]
	v_pk_fma_f32 v[66:67], v[162:163], v[212:213], v[66:67]
	v_pk_fma_f32 v[76:77], v[172:173], v[210:211], v[76:77]
	v_pk_fma_f32 v[78:79], v[174:175], v[212:213], v[78:79]
	v_pk_fma_f32 v[88:89], v[184:185], v[210:211], v[88:89]
	v_pk_fma_f32 v[90:91], v[186:187], v[212:213], v[90:91]
	ds_read_b128 v[210:213], v2 offset:52224
	s_waitcnt lgkmcnt(2)
	v_pk_fma_f32 v[8:9], v[104:105], v[214:215], v[8:9]
	v_pk_fma_f32 v[10:11], v[106:107], v[216:217], v[10:11]
	v_pk_fma_f32 v[20:21], v[116:117], v[214:215], v[20:21]
	v_pk_fma_f32 v[22:23], v[118:119], v[216:217], v[22:23]
	v_pk_fma_f32 v[32:33], v[128:129], v[214:215], v[32:33]
	v_pk_fma_f32 v[34:35], v[130:131], v[216:217], v[34:35]
	v_pk_fma_f32 v[44:45], v[140:141], v[214:215], v[44:45]
	v_pk_fma_f32 v[46:47], v[142:143], v[216:217], v[46:47]
	v_pk_fma_f32 v[56:57], v[152:153], v[214:215], v[56:57]
	v_pk_fma_f32 v[58:59], v[154:155], v[216:217], v[58:59]
	v_pk_fma_f32 v[68:69], v[164:165], v[214:215], v[68:69]
	v_pk_fma_f32 v[70:71], v[166:167], v[216:217], v[70:71]
	v_pk_fma_f32 v[80:81], v[176:177], v[214:215], v[80:81]
	v_pk_fma_f32 v[82:83], v[178:179], v[216:217], v[82:83]
	v_pk_fma_f32 v[92:93], v[188:189], v[214:215], v[92:93]
	v_pk_fma_f32 v[94:95], v[190:191], v[216:217], v[94:95]
	ds_read_b128 v[214:217], v2 offset:53248
	s_waitcnt lgkmcnt(2)
	v_pk_fma_f32 v[12:13], v[108:109], v[218:219], v[12:13]
	v_pk_fma_f32 v[14:15], v[110:111], v[220:221], v[14:15]
	v_pk_fma_f32 v[24:25], v[120:121], v[218:219], v[24:25]
	v_pk_fma_f32 v[26:27], v[122:123], v[220:221], v[26:27]
	v_pk_fma_f32 v[36:37], v[132:133], v[218:219], v[36:37]
	v_pk_fma_f32 v[38:39], v[134:135], v[220:221], v[38:39]
	v_pk_fma_f32 v[48:49], v[144:145], v[218:219], v[48:49]
	v_pk_fma_f32 v[50:51], v[146:147], v[220:221], v[50:51]
	v_pk_fma_f32 v[60:61], v[156:157], v[218:219], v[60:61]
	v_pk_fma_f32 v[62:63], v[158:159], v[220:221], v[62:63]
	v_pk_fma_f32 v[72:73], v[168:169], v[218:219], v[72:73]
	v_pk_fma_f32 v[74:75], v[170:171], v[220:221], v[74:75]
	v_pk_fma_f32 v[84:85], v[180:181], v[218:219], v[84:85]
	v_pk_fma_f32 v[86:87], v[182:183], v[220:221], v[86:87]
	v_pk_fma_f32 v[96:97], v[192:193], v[218:219], v[96:97]
	v_pk_fma_f32 v[98:99], v[194:195], v[220:221], v[98:99]
	ds_read_b128 v[218:221], v2 offset:54272
	s_waitcnt vmcnt(15)
	s_add_i32 s52, s41, -6
	s_cmp_lt_i32 s52, 0
	s_cbranch_scc1 .Lcv_z24_zero
	v_lshlrev_b32_e32 v100, 16, v222
	v_and_b32_e32 v101, 0xffff0000, v222
	v_lshlrev_b32_e32 v102, 16, v223
	v_and_b32_e32 v103, 0xffff0000, v223
	v_lshlrev_b32_e32 v104, 16, v224
	v_and_b32_e32 v105, 0xffff0000, v224
	v_lshlrev_b32_e32 v106, 16, v225
	v_and_b32_e32 v107, 0xffff0000, v225
	v_lshlrev_b32_e32 v108, 16, v226
	v_and_b32_e32 v109, 0xffff0000, v226
	v_lshlrev_b32_e32 v110, 16, v227
	v_and_b32_e32 v111, 0xffff0000, v227
	s_branch .Lcv_z24_done

.Lcv_z24_done:
	s_add_i32 s52, s41, 0
	s_mulk_i32 s52, 0x600
	v_add_u32_e32 v196, s52, v3
	global_load_dwordx2 v[222:223], v196, s[38:39]
	global_load_dwordx2 v[224:225], v196, s[38:39] offset:512
	global_load_dwordx2 v[226:227], v196, s[38:39] offset:1024
	s_waitcnt lgkmcnt(2)
	v_pk_fma_f32 v[4:5], v[112:113], v[210:211], v[4:5]
	v_pk_fma_f32 v[6:7], v[114:115], v[212:213], v[6:7]
	v_pk_fma_f32 v[16:17], v[124:125], v[210:211], v[16:17]
	v_pk_fma_f32 v[18:19], v[126:127], v[212:213], v[18:19]
	v_pk_fma_f32 v[28:29], v[136:137], v[210:211], v[28:29]
	v_pk_fma_f32 v[30:31], v[138:139], v[212:213], v[30:31]
	v_pk_fma_f32 v[40:41], v[148:149], v[210:211], v[40:41]
	v_pk_fma_f32 v[42:43], v[150:151], v[212:213], v[42:43]
	v_pk_fma_f32 v[52:53], v[160:161], v[210:211], v[52:53]
	v_pk_fma_f32 v[54:55], v[162:163], v[212:213], v[54:55]
	v_pk_fma_f32 v[64:65], v[172:173], v[210:211], v[64:65]
	v_pk_fma_f32 v[66:67], v[174:175], v[212:213], v[66:67]
	v_pk_fma_f32 v[76:77], v[184:185], v[210:211], v[76:77]
	v_pk_fma_f32 v[78:79], v[186:187], v[212:213], v[78:79]
	v_pk_fma_f32 v[88:89], v[100:101], v[210:211], v[88:89]
	v_pk_fma_f32 v[90:91], v[102:103], v[212:213], v[90:91]
	ds_read_b128 v[210:213], v2 offset:55296
	s_waitcnt lgkmcnt(2)
	v_pk_fma_f32 v[8:9], v[116:117], v[214:215], v[8:9]
	v_pk_fma_f32 v[10:11], v[118:119], v[216:217], v[10:11]
	v_pk_fma_f32 v[20:21], v[128:129], v[214:215], v[20:21]
	v_pk_fma_f32 v[22:23], v[130:131], v[216:217], v[22:23]
	v_pk_fma_f32 v[32:33], v[140:141], v[214:215], v[32:33]
	v_pk_fma_f32 v[34:35], v[142:143], v[216:217], v[34:35]
	v_pk_fma_f32 v[44:45], v[152:153], v[214:215], v[44:45]
	v_pk_fma_f32 v[46:47], v[154:155], v[216:217], v[46:47]
	v_pk_fma_f32 v[56:57], v[164:165], v[214:215], v[56:57]
	v_pk_fma_f32 v[58:59], v[166:167], v[216:217], v[58:59]
	v_pk_fma_f32 v[68:69], v[176:177], v[214:215], v[68:69]
	v_pk_fma_f32 v[70:71], v[178:179], v[216:217], v[70:71]
	v_pk_fma_f32 v[80:81], v[188:189], v[214:215], v[80:81]
	v_pk_fma_f32 v[82:83], v[190:191], v[216:217], v[82:83]
	v_pk_fma_f32 v[92:93], v[104:105], v[214:215], v[92:93]
	v_pk_fma_f32 v[94:95], v[106:107], v[216:217], v[94:95]
	ds_read_b128 v[214:217], v2 offset:56320
	s_waitcnt lgkmcnt(2)
	v_pk_fma_f32 v[12:13], v[120:121], v[218:219], v[12:13]
	v_pk_fma_f32 v[14:15], v[122:123], v[220:221], v[14:15]
	v_pk_fma_f32 v[24:25], v[132:133], v[218:219], v[24:25]
	v_pk_fma_f32 v[26:27], v[134:135], v[220:221], v[26:27]
	v_pk_fma_f32 v[36:37], v[144:145], v[218:219], v[36:37]
	v_pk_fma_f32 v[38:39], v[146:147], v[220:221], v[38:39]
	v_pk_fma_f32 v[48:49], v[156:157], v[218:219], v[48:49]
	v_pk_fma_f32 v[50:51], v[158:159], v[220:221], v[50:51]
	v_pk_fma_f32 v[60:61], v[168:169], v[218:219], v[60:61]
	v_pk_fma_f32 v[62:63], v[170:171], v[220:221], v[62:63]
	v_pk_fma_f32 v[72:73], v[180:181], v[218:219], v[72:73]
	v_pk_fma_f32 v[74:75], v[182:183], v[220:221], v[74:75]
	v_pk_fma_f32 v[84:85], v[192:193], v[218:219], v[84:85]
	v_pk_fma_f32 v[86:87], v[194:195], v[220:221], v[86:87]
	v_pk_fma_f32 v[96:97], v[108:109], v[218:219], v[96:97]
	v_pk_fma_f32 v[98:99], v[110:111], v[220:221], v[98:99]
	ds_read_b128 v[218:221], v2 offset:57344
	s_waitcnt vmcnt(15)
	s_add_i32 s52, s41, -5
	s_cmp_lt_i32 s52, 0
	s_cbranch_scc1 .Lcv_z25_zero
	v_lshlrev_b32_e32 v112, 16, v228
	v_and_b32_e32 v113, 0xffff0000, v228
	v_lshlrev_b32_e32 v114, 16, v229
	v_and_b32_e32 v115, 0xffff0000, v229
	v_lshlrev_b32_e32 v116, 16, v230
	v_and_b32_e32 v117, 0xffff0000, v230
	v_lshlrev_b32_e32 v118, 16, v231
	v_and_b32_e32 v119, 0xffff0000, v231
	v_lshlrev_b32_e32 v120, 16, v232
	v_and_b32_e32 v121, 0xffff0000, v232
	v_lshlrev_b32_e32 v122, 16, v233
	v_and_b32_e32 v123, 0xffff0000, v233
	s_branch .Lcv_z25_done

.Lcv_z25_done:
	s_add_i32 s52, s41, 1
	s_mulk_i32 s52, 0x600
	v_add_u32_e32 v196, s52, v3
	global_load_dwordx2 v[228:229], v196, s[38:39]
	global_load_dwordx2 v[230:231], v196, s[38:39] offset:512
	global_load_dwordx2 v[232:233], v196, s[38:39] offset:1024
	s_waitcnt lgkmcnt(2)
	v_pk_fma_f32 v[4:5], v[124:125], v[210:211], v[4:5]
	v_pk_fma_f32 v[6:7], v[126:127], v[212:213], v[6:7]
	v_pk_fma_f32 v[16:17], v[136:137], v[210:211], v[16:17]
	v_pk_fma_f32 v[18:19], v[138:139], v[212:213], v[18:19]
	v_pk_fma_f32 v[28:29], v[148:149], v[210:211], v[28:29]
	v_pk_fma_f32 v[30:31], v[150:151], v[212:213], v[30:31]
	v_pk_fma_f32 v[40:41], v[160:161], v[210:211], v[40:41]
	v_pk_fma_f32 v[42:43], v[162:163], v[212:213], v[42:43]
	v_pk_fma_f32 v[52:53], v[172:173], v[210:211], v[52:53]
	v_pk_fma_f32 v[54:55], v[174:175], v[212:213], v[54:55]
	v_pk_fma_f32 v[64:65], v[184:185], v[210:211], v[64:65]
	v_pk_fma_f32 v[66:67], v[186:187], v[212:213], v[66:67]
	v_pk_fma_f32 v[76:77], v[100:101], v[210:211], v[76:77]
	v_pk_fma_f32 v[78:79], v[102:103], v[212:213], v[78:79]
	v_pk_fma_f32 v[88:89], v[112:113], v[210:211], v[88:89]
	v_pk_fma_f32 v[90:91], v[114:115], v[212:213], v[90:91]
	ds_read_b128 v[210:213], v2 offset:58368
	s_waitcnt lgkmcnt(2)
	v_pk_fma_f32 v[8:9], v[128:129], v[214:215], v[8:9]
	v_pk_fma_f32 v[10:11], v[130:131], v[216:217], v[10:11]
	v_pk_fma_f32 v[20:21], v[140:141], v[214:215], v[20:21]
	v_pk_fma_f32 v[22:23], v[142:143], v[216:217], v[22:23]
	v_pk_fma_f32 v[32:33], v[152:153], v[214:215], v[32:33]
	v_pk_fma_f32 v[34:35], v[154:155], v[216:217], v[34:35]
	v_pk_fma_f32 v[44:45], v[164:165], v[214:215], v[44:45]
	v_pk_fma_f32 v[46:47], v[166:167], v[216:217], v[46:47]
	v_pk_fma_f32 v[56:57], v[176:177], v[214:215], v[56:57]
	v_pk_fma_f32 v[58:59], v[178:179], v[216:217], v[58:59]
	v_pk_fma_f32 v[68:69], v[188:189], v[214:215], v[68:69]
	v_pk_fma_f32 v[70:71], v[190:191], v[216:217], v[70:71]
	v_pk_fma_f32 v[80:81], v[104:105], v[214:215], v[80:81]
	v_pk_fma_f32 v[82:83], v[106:107], v[216:217], v[82:83]
	v_pk_fma_f32 v[92:93], v[116:117], v[214:215], v[92:93]
	v_pk_fma_f32 v[94:95], v[118:119], v[216:217], v[94:95]
	ds_read_b128 v[214:217], v2 offset:59392
	s_waitcnt lgkmcnt(2)
	v_pk_fma_f32 v[12:13], v[132:133], v[218:219], v[12:13]
	v_pk_fma_f32 v[14:15], v[134:135], v[220:221], v[14:15]
	v_pk_fma_f32 v[24:25], v[144:145], v[218:219], v[24:25]
	v_pk_fma_f32 v[26:27], v[146:147], v[220:221], v[26:27]
	v_pk_fma_f32 v[36:37], v[156:157], v[218:219], v[36:37]
	v_pk_fma_f32 v[38:39], v[158:159], v[220:221], v[38:39]
	v_pk_fma_f32 v[48:49], v[168:169], v[218:219], v[48:49]
	v_pk_fma_f32 v[50:51], v[170:171], v[220:221], v[50:51]
	v_pk_fma_f32 v[60:61], v[180:181], v[218:219], v[60:61]
	v_pk_fma_f32 v[62:63], v[182:183], v[220:221], v[62:63]
	v_pk_fma_f32 v[72:73], v[192:193], v[218:219], v[72:73]
	v_pk_fma_f32 v[74:75], v[194:195], v[220:221], v[74:75]
	v_pk_fma_f32 v[84:85], v[108:109], v[218:219], v[84:85]
	v_pk_fma_f32 v[86:87], v[110:111], v[220:221], v[86:87]
	v_pk_fma_f32 v[96:97], v[120:121], v[218:219], v[96:97]
	v_pk_fma_f32 v[98:99], v[122:123], v[220:221], v[98:99]
	ds_read_b128 v[218:221], v2 offset:60416
	s_waitcnt vmcnt(15)
	s_add_i32 s52, s41, -4
	s_cmp_lt_i32 s52, 0
	s_cbranch_scc1 .Lcv_z26_zero
	v_lshlrev_b32_e32 v124, 16, v234
	v_and_b32_e32 v125, 0xffff0000, v234
	v_lshlrev_b32_e32 v126, 16, v235
	v_and_b32_e32 v127, 0xffff0000, v235
	v_lshlrev_b32_e32 v128, 16, v236
	v_and_b32_e32 v129, 0xffff0000, v236
	v_lshlrev_b32_e32 v130, 16, v237
	v_and_b32_e32 v131, 0xffff0000, v237
	v_lshlrev_b32_e32 v132, 16, v238
	v_and_b32_e32 v133, 0xffff0000, v238
	v_lshlrev_b32_e32 v134, 16, v239
	v_and_b32_e32 v135, 0xffff0000, v239
	s_branch .Lcv_z26_done

.Lcv_z26_done:
	s_add_i32 s52, s41, 2
	s_mulk_i32 s52, 0x600
	v_add_u32_e32 v196, s52, v3
	global_load_dwordx2 v[234:235], v196, s[38:39]
	global_load_dwordx2 v[236:237], v196, s[38:39] offset:512
	global_load_dwordx2 v[238:239], v196, s[38:39] offset:1024
	s_waitcnt lgkmcnt(2)
	v_pk_fma_f32 v[4:5], v[136:137], v[210:211], v[4:5]
	v_pk_fma_f32 v[6:7], v[138:139], v[212:213], v[6:7]
	v_pk_fma_f32 v[16:17], v[148:149], v[210:211], v[16:17]
	v_pk_fma_f32 v[18:19], v[150:151], v[212:213], v[18:19]
	v_pk_fma_f32 v[28:29], v[160:161], v[210:211], v[28:29]
	v_pk_fma_f32 v[30:31], v[162:163], v[212:213], v[30:31]
	v_pk_fma_f32 v[40:41], v[172:173], v[210:211], v[40:41]
	v_pk_fma_f32 v[42:43], v[174:175], v[212:213], v[42:43]
	v_pk_fma_f32 v[52:53], v[184:185], v[210:211], v[52:53]
	v_pk_fma_f32 v[54:55], v[186:187], v[212:213], v[54:55]
	v_pk_fma_f32 v[64:65], v[100:101], v[210:211], v[64:65]
	v_pk_fma_f32 v[66:67], v[102:103], v[212:213], v[66:67]
	v_pk_fma_f32 v[76:77], v[112:113], v[210:211], v[76:77]
	v_pk_fma_f32 v[78:79], v[114:115], v[212:213], v[78:79]
	v_pk_fma_f32 v[88:89], v[124:125], v[210:211], v[88:89]
	v_pk_fma_f32 v[90:91], v[126:127], v[212:213], v[90:91]
	ds_read_b128 v[210:213], v2 offset:61440
	s_waitcnt lgkmcnt(2)
	v_pk_fma_f32 v[8:9], v[140:141], v[214:215], v[8:9]
	v_pk_fma_f32 v[10:11], v[142:143], v[216:217], v[10:11]
	v_pk_fma_f32 v[20:21], v[152:153], v[214:215], v[20:21]
	v_pk_fma_f32 v[22:23], v[154:155], v[216:217], v[22:23]
	v_pk_fma_f32 v[32:33], v[164:165], v[214:215], v[32:33]
	v_pk_fma_f32 v[34:35], v[166:167], v[216:217], v[34:35]
	v_pk_fma_f32 v[44:45], v[176:177], v[214:215], v[44:45]
	v_pk_fma_f32 v[46:47], v[178:179], v[216:217], v[46:47]
	v_pk_fma_f32 v[56:57], v[188:189], v[214:215], v[56:57]
	v_pk_fma_f32 v[58:59], v[190:191], v[216:217], v[58:59]
	v_pk_fma_f32 v[68:69], v[104:105], v[214:215], v[68:69]
	v_pk_fma_f32 v[70:71], v[106:107], v[216:217], v[70:71]
	v_pk_fma_f32 v[80:81], v[116:117], v[214:215], v[80:81]
	v_pk_fma_f32 v[82:83], v[118:119], v[216:217], v[82:83]
	v_pk_fma_f32 v[92:93], v[128:129], v[214:215], v[92:93]
	v_pk_fma_f32 v[94:95], v[130:131], v[216:217], v[94:95]
	ds_read_b128 v[214:217], v2 offset:62464
	s_waitcnt lgkmcnt(2)
	v_pk_fma_f32 v[12:13], v[144:145], v[218:219], v[12:13]
	v_pk_fma_f32 v[14:15], v[146:147], v[220:221], v[14:15]
	v_pk_fma_f32 v[24:25], v[156:157], v[218:219], v[24:25]
	v_pk_fma_f32 v[26:27], v[158:159], v[220:221], v[26:27]
	v_pk_fma_f32 v[36:37], v[168:169], v[218:219], v[36:37]
	v_pk_fma_f32 v[38:39], v[170:171], v[220:221], v[38:39]
	v_pk_fma_f32 v[48:49], v[180:181], v[218:219], v[48:49]
	v_pk_fma_f32 v[50:51], v[182:183], v[220:221], v[50:51]
	v_pk_fma_f32 v[60:61], v[192:193], v[218:219], v[60:61]
	v_pk_fma_f32 v[62:63], v[194:195], v[220:221], v[62:63]
	v_pk_fma_f32 v[72:73], v[108:109], v[218:219], v[72:73]
	v_pk_fma_f32 v[74:75], v[110:111], v[220:221], v[74:75]
	v_pk_fma_f32 v[84:85], v[120:121], v[218:219], v[84:85]
	v_pk_fma_f32 v[86:87], v[122:123], v[220:221], v[86:87]
	v_pk_fma_f32 v[96:97], v[132:133], v[218:219], v[96:97]
	v_pk_fma_f32 v[98:99], v[134:135], v[220:221], v[98:99]
	ds_read_b128 v[218:221], v2 offset:63488
	s_waitcnt vmcnt(15)
	s_add_i32 s52, s41, -3
	s_cmp_lt_i32 s52, 0
	s_cbranch_scc1 .Lcv_z27_zero
	v_lshlrev_b32_e32 v136, 16, v240
	v_and_b32_e32 v137, 0xffff0000, v240
	v_lshlrev_b32_e32 v138, 16, v241
	v_and_b32_e32 v139, 0xffff0000, v241
	v_lshlrev_b32_e32 v140, 16, v242
	v_and_b32_e32 v141, 0xffff0000, v242
	v_lshlrev_b32_e32 v142, 16, v243
	v_and_b32_e32 v143, 0xffff0000, v243
	v_lshlrev_b32_e32 v144, 16, v244
	v_and_b32_e32 v145, 0xffff0000, v244
	v_lshlrev_b32_e32 v146, 16, v245
	v_and_b32_e32 v147, 0xffff0000, v245
	s_branch .Lcv_z27_done

.Lcv_z27_done:
	s_add_i32 s52, s41, 3
	s_mulk_i32 s52, 0x600
	v_add_u32_e32 v196, s52, v3
	global_load_dwordx2 v[240:241], v196, s[38:39]
	global_load_dwordx2 v[242:243], v196, s[38:39] offset:512
	global_load_dwordx2 v[244:245], v196, s[38:39] offset:1024
	s_waitcnt lgkmcnt(2)
	v_pk_fma_f32 v[4:5], v[148:149], v[210:211], v[4:5]
	v_pk_fma_f32 v[6:7], v[150:151], v[212:213], v[6:7]
	v_pk_fma_f32 v[16:17], v[160:161], v[210:211], v[16:17]
	v_pk_fma_f32 v[18:19], v[162:163], v[212:213], v[18:19]
	v_pk_fma_f32 v[28:29], v[172:173], v[210:211], v[28:29]
	v_pk_fma_f32 v[30:31], v[174:175], v[212:213], v[30:31]
	v_pk_fma_f32 v[40:41], v[184:185], v[210:211], v[40:41]
	v_pk_fma_f32 v[42:43], v[186:187], v[212:213], v[42:43]
	v_pk_fma_f32 v[52:53], v[100:101], v[210:211], v[52:53]
	v_pk_fma_f32 v[54:55], v[102:103], v[212:213], v[54:55]
	v_pk_fma_f32 v[64:65], v[112:113], v[210:211], v[64:65]
	v_pk_fma_f32 v[66:67], v[114:115], v[212:213], v[66:67]
	v_pk_fma_f32 v[76:77], v[124:125], v[210:211], v[76:77]
	v_pk_fma_f32 v[78:79], v[126:127], v[212:213], v[78:79]
	v_pk_fma_f32 v[88:89], v[136:137], v[210:211], v[88:89]
	v_pk_fma_f32 v[90:91], v[138:139], v[212:213], v[90:91]
	ds_read_b128 v[210:213], v2 offset:64512
	s_waitcnt lgkmcnt(2)
	v_pk_fma_f32 v[8:9], v[152:153], v[214:215], v[8:9]
	v_pk_fma_f32 v[10:11], v[154:155], v[216:217], v[10:11]
	v_pk_fma_f32 v[20:21], v[164:165], v[214:215], v[20:21]
	v_pk_fma_f32 v[22:23], v[166:167], v[216:217], v[22:23]
	v_pk_fma_f32 v[32:33], v[176:177], v[214:215], v[32:33]
	v_pk_fma_f32 v[34:35], v[178:179], v[216:217], v[34:35]
	v_pk_fma_f32 v[44:45], v[188:189], v[214:215], v[44:45]
	v_pk_fma_f32 v[46:47], v[190:191], v[216:217], v[46:47]
	v_pk_fma_f32 v[56:57], v[104:105], v[214:215], v[56:57]
	v_pk_fma_f32 v[58:59], v[106:107], v[216:217], v[58:59]
	v_pk_fma_f32 v[68:69], v[116:117], v[214:215], v[68:69]
	v_pk_fma_f32 v[70:71], v[118:119], v[216:217], v[70:71]
	v_pk_fma_f32 v[80:81], v[128:129], v[214:215], v[80:81]
	v_pk_fma_f32 v[82:83], v[130:131], v[216:217], v[82:83]
	v_pk_fma_f32 v[92:93], v[140:141], v[214:215], v[92:93]
	v_pk_fma_f32 v[94:95], v[142:143], v[216:217], v[94:95]
	ds_read_b128 v[214:217], v208
	s_waitcnt lgkmcnt(2)
	v_pk_fma_f32 v[12:13], v[156:157], v[218:219], v[12:13]
	v_pk_fma_f32 v[14:15], v[158:159], v[220:221], v[14:15]
	v_pk_fma_f32 v[24:25], v[168:169], v[218:219], v[24:25]
	v_pk_fma_f32 v[26:27], v[170:171], v[220:221], v[26:27]
	v_pk_fma_f32 v[36:37], v[180:181], v[218:219], v[36:37]
	v_pk_fma_f32 v[38:39], v[182:183], v[220:221], v[38:39]
	v_pk_fma_f32 v[48:49], v[192:193], v[218:219], v[48:49]
	v_pk_fma_f32 v[50:51], v[194:195], v[220:221], v[50:51]
	v_pk_fma_f32 v[60:61], v[108:109], v[218:219], v[60:61]
	v_pk_fma_f32 v[62:63], v[110:111], v[220:221], v[62:63]
	v_pk_fma_f32 v[72:73], v[120:121], v[218:219], v[72:73]
	v_pk_fma_f32 v[74:75], v[122:123], v[220:221], v[74:75]
	v_pk_fma_f32 v[84:85], v[132:133], v[218:219], v[84:85]
	v_pk_fma_f32 v[86:87], v[134:135], v[220:221], v[86:87]
	v_pk_fma_f32 v[96:97], v[144:145], v[218:219], v[96:97]
	v_pk_fma_f32 v[98:99], v[146:147], v[220:221], v[98:99]
	ds_read_b128 v[218:221], v208 offset:1024
	s_waitcnt vmcnt(15)
	s_add_i32 s52, s41, -2
	s_cmp_lt_i32 s52, 0
	s_cbranch_scc1 .Lcv_z28_zero
	v_lshlrev_b32_e32 v148, 16, v246
	v_and_b32_e32 v149, 0xffff0000, v246
	v_lshlrev_b32_e32 v150, 16, v247
	v_and_b32_e32 v151, 0xffff0000, v247
	v_lshlrev_b32_e32 v152, 16, v248
	v_and_b32_e32 v153, 0xffff0000, v248
	v_lshlrev_b32_e32 v154, 16, v249
	v_and_b32_e32 v155, 0xffff0000, v249
	v_lshlrev_b32_e32 v156, 16, v250
	v_and_b32_e32 v157, 0xffff0000, v250
	v_lshlrev_b32_e32 v158, 16, v251
	v_and_b32_e32 v159, 0xffff0000, v251
	s_branch .Lcv_z28_done

.Lcv_z28_done:
	s_add_i32 s52, s41, 4
	s_mulk_i32 s52, 0x600
	v_add_u32_e32 v196, s52, v3
	global_load_dwordx2 v[246:247], v196, s[38:39]
	global_load_dwordx2 v[248:249], v196, s[38:39] offset:512
	global_load_dwordx2 v[250:251], v196, s[38:39] offset:1024
	s_waitcnt lgkmcnt(2)
	v_pk_fma_f32 v[4:5], v[160:161], v[210:211], v[4:5]
	v_pk_fma_f32 v[6:7], v[162:163], v[212:213], v[6:7]
	v_pk_fma_f32 v[16:17], v[172:173], v[210:211], v[16:17]
	v_pk_fma_f32 v[18:19], v[174:175], v[212:213], v[18:19]
	v_pk_fma_f32 v[28:29], v[184:185], v[210:211], v[28:29]
	v_pk_fma_f32 v[30:31], v[186:187], v[212:213], v[30:31]
	v_pk_fma_f32 v[40:41], v[100:101], v[210:211], v[40:41]
	v_pk_fma_f32 v[42:43], v[102:103], v[212:213], v[42:43]
	v_pk_fma_f32 v[52:53], v[112:113], v[210:211], v[52:53]
	v_pk_fma_f32 v[54:55], v[114:115], v[212:213], v[54:55]
	v_pk_fma_f32 v[64:65], v[124:125], v[210:211], v[64:65]
	v_pk_fma_f32 v[66:67], v[126:127], v[212:213], v[66:67]
	v_pk_fma_f32 v[76:77], v[136:137], v[210:211], v[76:77]
	v_pk_fma_f32 v[78:79], v[138:139], v[212:213], v[78:79]
	v_pk_fma_f32 v[88:89], v[148:149], v[210:211], v[88:89]
	v_pk_fma_f32 v[90:91], v[150:151], v[212:213], v[90:91]
	ds_read_b128 v[210:213], v208 offset:2048
	s_waitcnt lgkmcnt(2)
	v_pk_fma_f32 v[8:9], v[164:165], v[214:215], v[8:9]
	v_pk_fma_f32 v[10:11], v[166:167], v[216:217], v[10:11]
	v_pk_fma_f32 v[20:21], v[176:177], v[214:215], v[20:21]
	v_pk_fma_f32 v[22:23], v[178:179], v[216:217], v[22:23]
	v_pk_fma_f32 v[32:33], v[188:189], v[214:215], v[32:33]
	v_pk_fma_f32 v[34:35], v[190:191], v[216:217], v[34:35]
	v_pk_fma_f32 v[44:45], v[104:105], v[214:215], v[44:45]
	v_pk_fma_f32 v[46:47], v[106:107], v[216:217], v[46:47]
	v_pk_fma_f32 v[56:57], v[116:117], v[214:215], v[56:57]
	v_pk_fma_f32 v[58:59], v[118:119], v[216:217], v[58:59]
	v_pk_fma_f32 v[68:69], v[128:129], v[214:215], v[68:69]
	v_pk_fma_f32 v[70:71], v[130:131], v[216:217], v[70:71]
	v_pk_fma_f32 v[80:81], v[140:141], v[214:215], v[80:81]
	v_pk_fma_f32 v[82:83], v[142:143], v[216:217], v[82:83]
	v_pk_fma_f32 v[92:93], v[152:153], v[214:215], v[92:93]
	v_pk_fma_f32 v[94:95], v[154:155], v[216:217], v[94:95]
	ds_read_b128 v[214:217], v208 offset:3072
	s_waitcnt lgkmcnt(2)
	v_pk_fma_f32 v[12:13], v[168:169], v[218:219], v[12:13]
	v_pk_fma_f32 v[14:15], v[170:171], v[220:221], v[14:15]
	v_pk_fma_f32 v[24:25], v[180:181], v[218:219], v[24:25]
	v_pk_fma_f32 v[26:27], v[182:183], v[220:221], v[26:27]
	v_pk_fma_f32 v[36:37], v[192:193], v[218:219], v[36:37]
	v_pk_fma_f32 v[38:39], v[194:195], v[220:221], v[38:39]
	v_pk_fma_f32 v[48:49], v[108:109], v[218:219], v[48:49]
	v_pk_fma_f32 v[50:51], v[110:111], v[220:221], v[50:51]
	v_pk_fma_f32 v[60:61], v[120:121], v[218:219], v[60:61]
	v_pk_fma_f32 v[62:63], v[122:123], v[220:221], v[62:63]
	v_pk_fma_f32 v[72:73], v[132:133], v[218:219], v[72:73]
	v_pk_fma_f32 v[74:75], v[134:135], v[220:221], v[74:75]
	v_pk_fma_f32 v[84:85], v[144:145], v[218:219], v[84:85]
	v_pk_fma_f32 v[86:87], v[146:147], v[220:221], v[86:87]
	v_pk_fma_f32 v[96:97], v[156:157], v[218:219], v[96:97]
	v_pk_fma_f32 v[98:99], v[158:159], v[220:221], v[98:99]
	ds_read_b128 v[218:221], v208 offset:4096
	s_waitcnt vmcnt(15)
	s_add_i32 s52, s41, -1
	s_cmp_lt_i32 s52, 0
	s_cbranch_scc1 .Lcv_z29_zero
	v_lshlrev_b32_e32 v160, 16, v204
	v_and_b32_e32 v161, 0xffff0000, v204
	v_lshlrev_b32_e32 v162, 16, v205
	v_and_b32_e32 v163, 0xffff0000, v205
	v_lshlrev_b32_e32 v164, 16, v206
	v_and_b32_e32 v165, 0xffff0000, v206
	v_lshlrev_b32_e32 v166, 16, v207
	v_and_b32_e32 v167, 0xffff0000, v207
	v_lshlrev_b32_e32 v168, 16, v252
	v_and_b32_e32 v169, 0xffff0000, v252
	v_lshlrev_b32_e32 v170, 16, v253
	v_and_b32_e32 v171, 0xffff0000, v253
	s_branch .Lcv_z29_done

.Lcv_z29_done:
	s_add_i32 s52, s41, 5
	s_mulk_i32 s52, 0x600
	v_add_u32_e32 v196, s52, v3
	global_load_dwordx2 v[204:205], v196, s[38:39]
	global_load_dwordx2 v[206:207], v196, s[38:39] offset:512
	global_load_dwordx2 v[252:253], v196, s[38:39] offset:1024
	s_waitcnt lgkmcnt(2)
	v_pk_fma_f32 v[4:5], v[172:173], v[210:211], v[4:5]
	v_pk_fma_f32 v[6:7], v[174:175], v[212:213], v[6:7]
	v_pk_fma_f32 v[16:17], v[184:185], v[210:211], v[16:17]
	v_pk_fma_f32 v[18:19], v[186:187], v[212:213], v[18:19]
	v_pk_fma_f32 v[28:29], v[100:101], v[210:211], v[28:29]
	v_pk_fma_f32 v[30:31], v[102:103], v[212:213], v[30:31]
	v_pk_fma_f32 v[40:41], v[112:113], v[210:211], v[40:41]
	v_pk_fma_f32 v[42:43], v[114:115], v[212:213], v[42:43]
	v_pk_fma_f32 v[52:53], v[124:125], v[210:211], v[52:53]
	v_pk_fma_f32 v[54:55], v[126:127], v[212:213], v[54:55]
	v_pk_fma_f32 v[64:65], v[136:137], v[210:211], v[64:65]
	v_pk_fma_f32 v[66:67], v[138:139], v[212:213], v[66:67]
	v_pk_fma_f32 v[76:77], v[148:149], v[210:211], v[76:77]
	v_pk_fma_f32 v[78:79], v[150:151], v[212:213], v[78:79]
	v_pk_fma_f32 v[88:89], v[160:161], v[210:211], v[88:89]
	v_pk_fma_f32 v[90:91], v[162:163], v[212:213], v[90:91]
	ds_read_b128 v[210:213], v208 offset:5120
	s_waitcnt lgkmcnt(2)
	v_pk_fma_f32 v[8:9], v[176:177], v[214:215], v[8:9]
	v_pk_fma_f32 v[10:11], v[178:179], v[216:217], v[10:11]
	v_pk_fma_f32 v[20:21], v[188:189], v[214:215], v[20:21]
	v_pk_fma_f32 v[22:23], v[190:191], v[216:217], v[22:23]
	v_pk_fma_f32 v[32:33], v[104:105], v[214:215], v[32:33]
	v_pk_fma_f32 v[34:35], v[106:107], v[216:217], v[34:35]
	v_pk_fma_f32 v[44:45], v[116:117], v[214:215], v[44:45]
	v_pk_fma_f32 v[46:47], v[118:119], v[216:217], v[46:47]
	v_pk_fma_f32 v[56:57], v[128:129], v[214:215], v[56:57]
	v_pk_fma_f32 v[58:59], v[130:131], v[216:217], v[58:59]
	v_pk_fma_f32 v[68:69], v[140:141], v[214:215], v[68:69]
	v_pk_fma_f32 v[70:71], v[142:143], v[216:217], v[70:71]
	v_pk_fma_f32 v[80:81], v[152:153], v[214:215], v[80:81]
	v_pk_fma_f32 v[82:83], v[154:155], v[216:217], v[82:83]
	v_pk_fma_f32 v[92:93], v[164:165], v[214:215], v[92:93]
	v_pk_fma_f32 v[94:95], v[166:167], v[216:217], v[94:95]
	ds_read_b128 v[214:217], v208 offset:6144
	s_waitcnt lgkmcnt(2)
	v_pk_fma_f32 v[12:13], v[180:181], v[218:219], v[12:13]
	v_pk_fma_f32 v[14:15], v[182:183], v[220:221], v[14:15]
	v_pk_fma_f32 v[24:25], v[192:193], v[218:219], v[24:25]
	v_pk_fma_f32 v[26:27], v[194:195], v[220:221], v[26:27]
	v_pk_fma_f32 v[36:37], v[108:109], v[218:219], v[36:37]
	v_pk_fma_f32 v[38:39], v[110:111], v[220:221], v[38:39]
	v_pk_fma_f32 v[48:49], v[120:121], v[218:219], v[48:49]
	v_pk_fma_f32 v[50:51], v[122:123], v[220:221], v[50:51]
	v_pk_fma_f32 v[60:61], v[132:133], v[218:219], v[60:61]
	v_pk_fma_f32 v[62:63], v[134:135], v[220:221], v[62:63]
	v_pk_fma_f32 v[72:73], v[144:145], v[218:219], v[72:73]
	v_pk_fma_f32 v[74:75], v[146:147], v[220:221], v[74:75]
	v_pk_fma_f32 v[84:85], v[156:157], v[218:219], v[84:85]
	v_pk_fma_f32 v[86:87], v[158:159], v[220:221], v[86:87]
	v_pk_fma_f32 v[96:97], v[168:169], v[218:219], v[96:97]
	v_pk_fma_f32 v[98:99], v[170:171], v[220:221], v[98:99]
	ds_read_b128 v[218:221], v208 offset:7168
	s_waitcnt vmcnt(15)
	v_lshlrev_b32_e32 v172, 16, v222
	v_and_b32_e32 v173, 0xffff0000, v222
	v_lshlrev_b32_e32 v174, 16, v223
	v_and_b32_e32 v175, 0xffff0000, v223
	v_lshlrev_b32_e32 v176, 16, v224
	v_and_b32_e32 v177, 0xffff0000, v224
	v_lshlrev_b32_e32 v178, 16, v225
	v_and_b32_e32 v179, 0xffff0000, v225
	v_lshlrev_b32_e32 v180, 16, v226
	v_and_b32_e32 v181, 0xffff0000, v226
	v_lshlrev_b32_e32 v182, 16, v227
	v_and_b32_e32 v183, 0xffff0000, v227
	s_add_i32 s52, s41, 6
	s_mulk_i32 s52, 0x600
	v_add_u32_e32 v196, s52, v3
	global_load_dwordx2 v[222:223], v196, s[38:39]
	global_load_dwordx2 v[224:225], v196, s[38:39] offset:512
	global_load_dwordx2 v[226:227], v196, s[38:39] offset:1024
	s_waitcnt lgkmcnt(2)
	v_pk_fma_f32 v[4:5], v[184:185], v[210:211], v[4:5]
	v_pk_fma_f32 v[6:7], v[186:187], v[212:213], v[6:7]
	v_pk_fma_f32 v[16:17], v[100:101], v[210:211], v[16:17]
	v_pk_fma_f32 v[18:19], v[102:103], v[212:213], v[18:19]
	v_pk_fma_f32 v[28:29], v[112:113], v[210:211], v[28:29]
	v_pk_fma_f32 v[30:31], v[114:115], v[212:213], v[30:31]
	v_pk_fma_f32 v[40:41], v[124:125], v[210:211], v[40:41]
	v_pk_fma_f32 v[42:43], v[126:127], v[212:213], v[42:43]
	v_pk_fma_f32 v[52:53], v[136:137], v[210:211], v[52:53]
	v_pk_fma_f32 v[54:55], v[138:139], v[212:213], v[54:55]
	v_pk_fma_f32 v[64:65], v[148:149], v[210:211], v[64:65]
	v_pk_fma_f32 v[66:67], v[150:151], v[212:213], v[66:67]
	v_pk_fma_f32 v[76:77], v[160:161], v[210:211], v[76:77]
	v_pk_fma_f32 v[78:79], v[162:163], v[212:213], v[78:79]
	v_pk_fma_f32 v[88:89], v[172:173], v[210:211], v[88:89]
	v_pk_fma_f32 v[90:91], v[174:175], v[212:213], v[90:91]
	ds_read_b128 v[210:213], v208 offset:8192
	s_waitcnt lgkmcnt(2)
	v_pk_fma_f32 v[8:9], v[188:189], v[214:215], v[8:9]
	v_pk_fma_f32 v[10:11], v[190:191], v[216:217], v[10:11]
	v_pk_fma_f32 v[20:21], v[104:105], v[214:215], v[20:21]
	v_pk_fma_f32 v[22:23], v[106:107], v[216:217], v[22:23]
	v_pk_fma_f32 v[32:33], v[116:117], v[214:215], v[32:33]
	v_pk_fma_f32 v[34:35], v[118:119], v[216:217], v[34:35]
	v_pk_fma_f32 v[44:45], v[128:129], v[214:215], v[44:45]
	v_pk_fma_f32 v[46:47], v[130:131], v[216:217], v[46:47]
	v_pk_fma_f32 v[56:57], v[140:141], v[214:215], v[56:57]
	v_pk_fma_f32 v[58:59], v[142:143], v[216:217], v[58:59]
	v_pk_fma_f32 v[68:69], v[152:153], v[214:215], v[68:69]
	v_pk_fma_f32 v[70:71], v[154:155], v[216:217], v[70:71]
	v_pk_fma_f32 v[80:81], v[164:165], v[214:215], v[80:81]
	v_pk_fma_f32 v[82:83], v[166:167], v[216:217], v[82:83]
	v_pk_fma_f32 v[92:93], v[176:177], v[214:215], v[92:93]
	v_pk_fma_f32 v[94:95], v[178:179], v[216:217], v[94:95]
	ds_read_b128 v[214:217], v208 offset:9216
	s_waitcnt lgkmcnt(2)
	v_pk_fma_f32 v[12:13], v[192:193], v[218:219], v[12:13]
	v_pk_fma_f32 v[14:15], v[194:195], v[220:221], v[14:15]
	v_pk_fma_f32 v[24:25], v[108:109], v[218:219], v[24:25]
	v_pk_fma_f32 v[26:27], v[110:111], v[220:221], v[26:27]
	v_pk_fma_f32 v[36:37], v[120:121], v[218:219], v[36:37]
	v_pk_fma_f32 v[38:39], v[122:123], v[220:221], v[38:39]
	v_pk_fma_f32 v[48:49], v[132:133], v[218:219], v[48:49]
	v_pk_fma_f32 v[50:51], v[134:135], v[220:221], v[50:51]
	v_pk_fma_f32 v[60:61], v[144:145], v[218:219], v[60:61]
	v_pk_fma_f32 v[62:63], v[146:147], v[220:221], v[62:63]
	v_pk_fma_f32 v[72:73], v[156:157], v[218:219], v[72:73]
	v_pk_fma_f32 v[74:75], v[158:159], v[220:221], v[74:75]
	v_pk_fma_f32 v[84:85], v[168:169], v[218:219], v[84:85]
	v_pk_fma_f32 v[86:87], v[170:171], v[220:221], v[86:87]
	v_pk_fma_f32 v[96:97], v[180:181], v[218:219], v[96:97]
	v_pk_fma_f32 v[98:99], v[182:183], v[220:221], v[98:99]
	ds_read_b128 v[218:221], v208 offset:10240
	s_waitcnt vmcnt(15)
	v_lshlrev_b32_e32 v184, 16, v228
	v_and_b32_e32 v185, 0xffff0000, v228
	v_lshlrev_b32_e32 v186, 16, v229
	v_and_b32_e32 v187, 0xffff0000, v229
	v_lshlrev_b32_e32 v188, 16, v230
	v_and_b32_e32 v189, 0xffff0000, v230
	v_lshlrev_b32_e32 v190, 16, v231
	v_and_b32_e32 v191, 0xffff0000, v231
	v_lshlrev_b32_e32 v192, 16, v232
	v_and_b32_e32 v193, 0xffff0000, v232
	v_lshlrev_b32_e32 v194, 16, v233
	v_and_b32_e32 v195, 0xffff0000, v233
	s_add_i32 s52, s41, 7
	s_mulk_i32 s52, 0x600
	v_add_u32_e32 v196, s52, v3
	global_load_dwordx2 v[228:229], v196, s[38:39]
	global_load_dwordx2 v[230:231], v196, s[38:39] offset:512
	global_load_dwordx2 v[232:233], v196, s[38:39] offset:1024
	s_waitcnt lgkmcnt(2)
	v_pk_fma_f32 v[4:5], v[100:101], v[210:211], v[4:5]
	v_pk_fma_f32 v[6:7], v[102:103], v[212:213], v[6:7]
	v_pk_fma_f32 v[16:17], v[112:113], v[210:211], v[16:17]
	v_pk_fma_f32 v[18:19], v[114:115], v[212:213], v[18:19]
	v_pk_fma_f32 v[28:29], v[124:125], v[210:211], v[28:29]
	v_pk_fma_f32 v[30:31], v[126:127], v[212:213], v[30:31]
	v_pk_fma_f32 v[40:41], v[136:137], v[210:211], v[40:41]
	v_pk_fma_f32 v[42:43], v[138:139], v[212:213], v[42:43]
	v_pk_fma_f32 v[52:53], v[148:149], v[210:211], v[52:53]
	v_pk_fma_f32 v[54:55], v[150:151], v[212:213], v[54:55]
	v_pk_fma_f32 v[64:65], v[160:161], v[210:211], v[64:65]
	v_pk_fma_f32 v[66:67], v[162:163], v[212:213], v[66:67]
	v_pk_fma_f32 v[76:77], v[172:173], v[210:211], v[76:77]
	v_pk_fma_f32 v[78:79], v[174:175], v[212:213], v[78:79]
	v_pk_fma_f32 v[88:89], v[184:185], v[210:211], v[88:89]
	v_pk_fma_f32 v[90:91], v[186:187], v[212:213], v[90:91]
	ds_read_b128 v[210:213], v208 offset:11264
	s_waitcnt lgkmcnt(2)
	v_pk_fma_f32 v[8:9], v[104:105], v[214:215], v[8:9]
	v_pk_fma_f32 v[10:11], v[106:107], v[216:217], v[10:11]
	v_pk_fma_f32 v[20:21], v[116:117], v[214:215], v[20:21]
	v_pk_fma_f32 v[22:23], v[118:119], v[216:217], v[22:23]
	v_pk_fma_f32 v[32:33], v[128:129], v[214:215], v[32:33]
	v_pk_fma_f32 v[34:35], v[130:131], v[216:217], v[34:35]
	v_pk_fma_f32 v[44:45], v[140:141], v[214:215], v[44:45]
	v_pk_fma_f32 v[46:47], v[142:143], v[216:217], v[46:47]
	v_pk_fma_f32 v[56:57], v[152:153], v[214:215], v[56:57]
	v_pk_fma_f32 v[58:59], v[154:155], v[216:217], v[58:59]
	v_pk_fma_f32 v[68:69], v[164:165], v[214:215], v[68:69]
	v_pk_fma_f32 v[70:71], v[166:167], v[216:217], v[70:71]
	v_pk_fma_f32 v[80:81], v[176:177], v[214:215], v[80:81]
	v_pk_fma_f32 v[82:83], v[178:179], v[216:217], v[82:83]
	v_pk_fma_f32 v[92:93], v[188:189], v[214:215], v[92:93]
	v_pk_fma_f32 v[94:95], v[190:191], v[216:217], v[94:95]
	ds_read_b128 v[214:217], v208 offset:12288
	s_waitcnt lgkmcnt(2)
	v_pk_fma_f32 v[12:13], v[108:109], v[218:219], v[12:13]
	v_pk_fma_f32 v[14:15], v[110:111], v[220:221], v[14:15]
	v_pk_fma_f32 v[24:25], v[120:121], v[218:219], v[24:25]
	v_pk_fma_f32 v[26:27], v[122:123], v[220:221], v[26:27]
	v_pk_fma_f32 v[36:37], v[132:133], v[218:219], v[36:37]
	v_pk_fma_f32 v[38:39], v[134:135], v[220:221], v[38:39]
	v_pk_fma_f32 v[48:49], v[144:145], v[218:219], v[48:49]
	v_pk_fma_f32 v[50:51], v[146:147], v[220:221], v[50:51]
	v_pk_fma_f32 v[60:61], v[156:157], v[218:219], v[60:61]
	v_pk_fma_f32 v[62:63], v[158:159], v[220:221], v[62:63]
	v_pk_fma_f32 v[72:73], v[168:169], v[218:219], v[72:73]
	v_pk_fma_f32 v[74:75], v[170:171], v[220:221], v[74:75]
	v_pk_fma_f32 v[84:85], v[180:181], v[218:219], v[84:85]
	v_pk_fma_f32 v[86:87], v[182:183], v[220:221], v[86:87]
	v_pk_fma_f32 v[96:97], v[192:193], v[218:219], v[96:97]
	v_pk_fma_f32 v[98:99], v[194:195], v[220:221], v[98:99]
	ds_read_b128 v[218:221], v208 offset:13312
	s_waitcnt vmcnt(15)
	v_lshlrev_b32_e32 v100, 16, v234
	v_and_b32_e32 v101, 0xffff0000, v234
	v_lshlrev_b32_e32 v102, 16, v235
	v_and_b32_e32 v103, 0xffff0000, v235
	v_lshlrev_b32_e32 v104, 16, v236
	v_and_b32_e32 v105, 0xffff0000, v236
	v_lshlrev_b32_e32 v106, 16, v237
	v_and_b32_e32 v107, 0xffff0000, v237
	v_lshlrev_b32_e32 v108, 16, v238
	v_and_b32_e32 v109, 0xffff0000, v238
	v_lshlrev_b32_e32 v110, 16, v239
	v_and_b32_e32 v111, 0xffff0000, v239
	s_waitcnt lgkmcnt(2)
	v_pk_fma_f32 v[4:5], v[112:113], v[210:211], v[4:5]
	v_pk_fma_f32 v[6:7], v[114:115], v[212:213], v[6:7]
	v_pk_fma_f32 v[16:17], v[124:125], v[210:211], v[16:17]
	v_pk_fma_f32 v[18:19], v[126:127], v[212:213], v[18:19]
	v_pk_fma_f32 v[28:29], v[136:137], v[210:211], v[28:29]
	v_pk_fma_f32 v[30:31], v[138:139], v[212:213], v[30:31]
	v_pk_fma_f32 v[40:41], v[148:149], v[210:211], v[40:41]
	v_pk_fma_f32 v[42:43], v[150:151], v[212:213], v[42:43]
	v_pk_fma_f32 v[52:53], v[160:161], v[210:211], v[52:53]
	v_pk_fma_f32 v[54:55], v[162:163], v[212:213], v[54:55]
	v_pk_fma_f32 v[64:65], v[172:173], v[210:211], v[64:65]
	v_pk_fma_f32 v[66:67], v[174:175], v[212:213], v[66:67]
	v_pk_fma_f32 v[76:77], v[184:185], v[210:211], v[76:77]
	v_pk_fma_f32 v[78:79], v[186:187], v[212:213], v[78:79]
	v_pk_fma_f32 v[88:89], v[100:101], v[210:211], v[88:89]
	v_pk_fma_f32 v[90:91], v[102:103], v[212:213], v[90:91]
	ds_read_b128 v[210:213], v208 offset:14336
	s_waitcnt lgkmcnt(2)
	v_pk_fma_f32 v[8:9], v[116:117], v[214:215], v[8:9]
	v_pk_fma_f32 v[10:11], v[118:119], v[216:217], v[10:11]
	v_pk_fma_f32 v[20:21], v[128:129], v[214:215], v[20:21]
	v_pk_fma_f32 v[22:23], v[130:131], v[216:217], v[22:23]
	v_pk_fma_f32 v[32:33], v[140:141], v[214:215], v[32:33]
	v_pk_fma_f32 v[34:35], v[142:143], v[216:217], v[34:35]
	v_pk_fma_f32 v[44:45], v[152:153], v[214:215], v[44:45]
	v_pk_fma_f32 v[46:47], v[154:155], v[216:217], v[46:47]
	v_pk_fma_f32 v[56:57], v[164:165], v[214:215], v[56:57]
	v_pk_fma_f32 v[58:59], v[166:167], v[216:217], v[58:59]
	v_pk_fma_f32 v[68:69], v[176:177], v[214:215], v[68:69]
	v_pk_fma_f32 v[70:71], v[178:179], v[216:217], v[70:71]
	v_pk_fma_f32 v[80:81], v[188:189], v[214:215], v[80:81]
	v_pk_fma_f32 v[82:83], v[190:191], v[216:217], v[82:83]
	v_pk_fma_f32 v[92:93], v[104:105], v[214:215], v[92:93]
	v_pk_fma_f32 v[94:95], v[106:107], v[216:217], v[94:95]
	ds_read_b128 v[214:217], v208 offset:15360
	s_waitcnt lgkmcnt(2)
	v_pk_fma_f32 v[12:13], v[120:121], v[218:219], v[12:13]
	v_pk_fma_f32 v[14:15], v[122:123], v[220:221], v[14:15]
	v_pk_fma_f32 v[24:25], v[132:133], v[218:219], v[24:25]
	v_pk_fma_f32 v[26:27], v[134:135], v[220:221], v[26:27]
	v_pk_fma_f32 v[36:37], v[144:145], v[218:219], v[36:37]
	v_pk_fma_f32 v[38:39], v[146:147], v[220:221], v[38:39]
	v_pk_fma_f32 v[48:49], v[156:157], v[218:219], v[48:49]
	v_pk_fma_f32 v[50:51], v[158:159], v[220:221], v[50:51]
	v_pk_fma_f32 v[60:61], v[168:169], v[218:219], v[60:61]
	v_pk_fma_f32 v[62:63], v[170:171], v[220:221], v[62:63]
	v_pk_fma_f32 v[72:73], v[180:181], v[218:219], v[72:73]
	v_pk_fma_f32 v[74:75], v[182:183], v[220:221], v[74:75]
	v_pk_fma_f32 v[84:85], v[192:193], v[218:219], v[84:85]
	v_pk_fma_f32 v[86:87], v[194:195], v[220:221], v[86:87]
	v_pk_fma_f32 v[96:97], v[108:109], v[218:219], v[96:97]
	v_pk_fma_f32 v[98:99], v[110:111], v[220:221], v[98:99]
	ds_read_b128 v[218:221], v208 offset:16384
	s_waitcnt vmcnt(12)
	v_lshlrev_b32_e32 v112, 16, v240
	v_and_b32_e32 v113, 0xffff0000, v240
	v_lshlrev_b32_e32 v114, 16, v241
	v_and_b32_e32 v115, 0xffff0000, v241
	v_lshlrev_b32_e32 v116, 16, v242
	v_and_b32_e32 v117, 0xffff0000, v242
	v_lshlrev_b32_e32 v118, 16, v243
	v_and_b32_e32 v119, 0xffff0000, v243
	v_lshlrev_b32_e32 v120, 16, v244
	v_and_b32_e32 v121, 0xffff0000, v244
	v_lshlrev_b32_e32 v122, 16, v245
	v_and_b32_e32 v123, 0xffff0000, v245
	s_waitcnt lgkmcnt(2)
	v_pk_fma_f32 v[4:5], v[124:125], v[210:211], v[4:5]
	v_pk_fma_f32 v[6:7], v[126:127], v[212:213], v[6:7]
	v_pk_fma_f32 v[16:17], v[136:137], v[210:211], v[16:17]
	v_pk_fma_f32 v[18:19], v[138:139], v[212:213], v[18:19]
	v_pk_fma_f32 v[28:29], v[148:149], v[210:211], v[28:29]
	v_pk_fma_f32 v[30:31], v[150:151], v[212:213], v[30:31]
	v_pk_fma_f32 v[40:41], v[160:161], v[210:211], v[40:41]
	v_pk_fma_f32 v[42:43], v[162:163], v[212:213], v[42:43]
	v_pk_fma_f32 v[52:53], v[172:173], v[210:211], v[52:53]
	v_pk_fma_f32 v[54:55], v[174:175], v[212:213], v[54:55]
	v_pk_fma_f32 v[64:65], v[184:185], v[210:211], v[64:65]
	v_pk_fma_f32 v[66:67], v[186:187], v[212:213], v[66:67]
	v_pk_fma_f32 v[76:77], v[100:101], v[210:211], v[76:77]
	v_pk_fma_f32 v[78:79], v[102:103], v[212:213], v[78:79]
	v_pk_fma_f32 v[88:89], v[112:113], v[210:211], v[88:89]
	v_pk_fma_f32 v[90:91], v[114:115], v[212:213], v[90:91]
	ds_read_b128 v[210:213], v208 offset:17408
	s_waitcnt lgkmcnt(2)
	v_pk_fma_f32 v[8:9], v[128:129], v[214:215], v[8:9]
	v_pk_fma_f32 v[10:11], v[130:131], v[216:217], v[10:11]
	v_pk_fma_f32 v[20:21], v[140:141], v[214:215], v[20:21]
	v_pk_fma_f32 v[22:23], v[142:143], v[216:217], v[22:23]
	v_pk_fma_f32 v[32:33], v[152:153], v[214:215], v[32:33]
	v_pk_fma_f32 v[34:35], v[154:155], v[216:217], v[34:35]
	v_pk_fma_f32 v[44:45], v[164:165], v[214:215], v[44:45]
	v_pk_fma_f32 v[46:47], v[166:167], v[216:217], v[46:47]
	v_pk_fma_f32 v[56:57], v[176:177], v[214:215], v[56:57]
	v_pk_fma_f32 v[58:59], v[178:179], v[216:217], v[58:59]
	v_pk_fma_f32 v[68:69], v[188:189], v[214:215], v[68:69]
	v_pk_fma_f32 v[70:71], v[190:191], v[216:217], v[70:71]
	v_pk_fma_f32 v[80:81], v[104:105], v[214:215], v[80:81]
	v_pk_fma_f32 v[82:83], v[106:107], v[216:217], v[82:83]
	v_pk_fma_f32 v[92:93], v[116:117], v[214:215], v[92:93]
	v_pk_fma_f32 v[94:95], v[118:119], v[216:217], v[94:95]
	ds_read_b128 v[214:217], v208 offset:18432
	s_waitcnt lgkmcnt(2)
	v_pk_fma_f32 v[12:13], v[132:133], v[218:219], v[12:13]
	v_pk_fma_f32 v[14:15], v[134:135], v[220:221], v[14:15]
	v_pk_fma_f32 v[24:25], v[144:145], v[218:219], v[24:25]
	v_pk_fma_f32 v[26:27], v[146:147], v[220:221], v[26:27]
	v_pk_fma_f32 v[36:37], v[156:157], v[218:219], v[36:37]
	v_pk_fma_f32 v[38:39], v[158:159], v[220:221], v[38:39]
	v_pk_fma_f32 v[48:49], v[168:169], v[218:219], v[48:49]
	v_pk_fma_f32 v[50:51], v[170:171], v[220:221], v[50:51]
	v_pk_fma_f32 v[60:61], v[180:181], v[218:219], v[60:61]
	v_pk_fma_f32 v[62:63], v[182:183], v[220:221], v[62:63]
	v_pk_fma_f32 v[72:73], v[192:193], v[218:219], v[72:73]
	v_pk_fma_f32 v[74:75], v[194:195], v[220:221], v[74:75]
	v_pk_fma_f32 v[84:85], v[108:109], v[218:219], v[84:85]
	v_pk_fma_f32 v[86:87], v[110:111], v[220:221], v[86:87]
	v_pk_fma_f32 v[96:97], v[120:121], v[218:219], v[96:97]
	v_pk_fma_f32 v[98:99], v[122:123], v[220:221], v[98:99]
	ds_read_b128 v[218:221], v208 offset:19456
	s_waitcnt vmcnt(9)
	v_lshlrev_b32_e32 v124, 16, v246
	v_and_b32_e32 v125, 0xffff0000, v246
	v_lshlrev_b32_e32 v126, 16, v247
	v_and_b32_e32 v127, 0xffff0000, v247
	v_lshlrev_b32_e32 v128, 16, v248
	v_and_b32_e32 v129, 0xffff0000, v248
	v_lshlrev_b32_e32 v130, 16, v249
	v_and_b32_e32 v131, 0xffff0000, v249
	v_lshlrev_b32_e32 v132, 16, v250
	v_and_b32_e32 v133, 0xffff0000, v250
	v_lshlrev_b32_e32 v134, 16, v251
	v_and_b32_e32 v135, 0xffff0000, v251
	s_waitcnt lgkmcnt(2)
	v_pk_fma_f32 v[4:5], v[136:137], v[210:211], v[4:5]
	v_pk_fma_f32 v[6:7], v[138:139], v[212:213], v[6:7]
	v_pk_fma_f32 v[16:17], v[148:149], v[210:211], v[16:17]
	v_pk_fma_f32 v[18:19], v[150:151], v[212:213], v[18:19]
	v_pk_fma_f32 v[28:29], v[160:161], v[210:211], v[28:29]
	v_pk_fma_f32 v[30:31], v[162:163], v[212:213], v[30:31]
	v_pk_fma_f32 v[40:41], v[172:173], v[210:211], v[40:41]
	v_pk_fma_f32 v[42:43], v[174:175], v[212:213], v[42:43]
	v_pk_fma_f32 v[52:53], v[184:185], v[210:211], v[52:53]
	v_pk_fma_f32 v[54:55], v[186:187], v[212:213], v[54:55]
	v_pk_fma_f32 v[64:65], v[100:101], v[210:211], v[64:65]
	v_pk_fma_f32 v[66:67], v[102:103], v[212:213], v[66:67]
	v_pk_fma_f32 v[76:77], v[112:113], v[210:211], v[76:77]
	v_pk_fma_f32 v[78:79], v[114:115], v[212:213], v[78:79]
	v_pk_fma_f32 v[88:89], v[124:125], v[210:211], v[88:89]
	v_pk_fma_f32 v[90:91], v[126:127], v[212:213], v[90:91]
	ds_read_b128 v[210:213], v208 offset:20480
	s_waitcnt lgkmcnt(2)
	v_pk_fma_f32 v[8:9], v[140:141], v[214:215], v[8:9]
	v_pk_fma_f32 v[10:11], v[142:143], v[216:217], v[10:11]
	v_pk_fma_f32 v[20:21], v[152:153], v[214:215], v[20:21]
	v_pk_fma_f32 v[22:23], v[154:155], v[216:217], v[22:23]
	v_pk_fma_f32 v[32:33], v[164:165], v[214:215], v[32:33]
	v_pk_fma_f32 v[34:35], v[166:167], v[216:217], v[34:35]
	v_pk_fma_f32 v[44:45], v[176:177], v[214:215], v[44:45]
	v_pk_fma_f32 v[46:47], v[178:179], v[216:217], v[46:47]
	v_pk_fma_f32 v[56:57], v[188:189], v[214:215], v[56:57]
	v_pk_fma_f32 v[58:59], v[190:191], v[216:217], v[58:59]
	v_pk_fma_f32 v[68:69], v[104:105], v[214:215], v[68:69]
	v_pk_fma_f32 v[70:71], v[106:107], v[216:217], v[70:71]
	v_pk_fma_f32 v[80:81], v[116:117], v[214:215], v[80:81]
	v_pk_fma_f32 v[82:83], v[118:119], v[216:217], v[82:83]
	v_pk_fma_f32 v[92:93], v[128:129], v[214:215], v[92:93]
	v_pk_fma_f32 v[94:95], v[130:131], v[216:217], v[94:95]
	ds_read_b128 v[214:217], v208 offset:21504
	s_waitcnt lgkmcnt(2)
	v_pk_fma_f32 v[12:13], v[144:145], v[218:219], v[12:13]
	v_pk_fma_f32 v[14:15], v[146:147], v[220:221], v[14:15]
	v_pk_fma_f32 v[24:25], v[156:157], v[218:219], v[24:25]
	v_pk_fma_f32 v[26:27], v[158:159], v[220:221], v[26:27]
	v_pk_fma_f32 v[36:37], v[168:169], v[218:219], v[36:37]
	v_pk_fma_f32 v[38:39], v[170:171], v[220:221], v[38:39]
	v_pk_fma_f32 v[48:49], v[180:181], v[218:219], v[48:49]
	v_pk_fma_f32 v[50:51], v[182:183], v[220:221], v[50:51]
	v_pk_fma_f32 v[60:61], v[192:193], v[218:219], v[60:61]
	v_pk_fma_f32 v[62:63], v[194:195], v[220:221], v[62:63]
	v_pk_fma_f32 v[72:73], v[108:109], v[218:219], v[72:73]
	v_pk_fma_f32 v[74:75], v[110:111], v[220:221], v[74:75]
	v_pk_fma_f32 v[84:85], v[120:121], v[218:219], v[84:85]
	v_pk_fma_f32 v[86:87], v[122:123], v[220:221], v[86:87]
	v_pk_fma_f32 v[96:97], v[132:133], v[218:219], v[96:97]
	v_pk_fma_f32 v[98:99], v[134:135], v[220:221], v[98:99]
	ds_read_b128 v[218:221], v208 offset:22528
	s_waitcnt vmcnt(6)
	v_lshlrev_b32_e32 v136, 16, v204
	v_and_b32_e32 v137, 0xffff0000, v204
	v_lshlrev_b32_e32 v138, 16, v205
	v_and_b32_e32 v139, 0xffff0000, v205
	v_lshlrev_b32_e32 v140, 16, v206
	v_and_b32_e32 v141, 0xffff0000, v206
	v_lshlrev_b32_e32 v142, 16, v207
	v_and_b32_e32 v143, 0xffff0000, v207
	v_lshlrev_b32_e32 v144, 16, v252
	v_and_b32_e32 v145, 0xffff0000, v252
	v_lshlrev_b32_e32 v146, 16, v253
	v_and_b32_e32 v147, 0xffff0000, v253
	s_waitcnt lgkmcnt(2)
	v_pk_fma_f32 v[4:5], v[148:149], v[210:211], v[4:5]
	v_pk_fma_f32 v[6:7], v[150:151], v[212:213], v[6:7]
	v_pk_fma_f32 v[16:17], v[160:161], v[210:211], v[16:17]
	v_pk_fma_f32 v[18:19], v[162:163], v[212:213], v[18:19]
	v_pk_fma_f32 v[28:29], v[172:173], v[210:211], v[28:29]
	v_pk_fma_f32 v[30:31], v[174:175], v[212:213], v[30:31]
	v_pk_fma_f32 v[40:41], v[184:185], v[210:211], v[40:41]
	v_pk_fma_f32 v[42:43], v[186:187], v[212:213], v[42:43]
	v_pk_fma_f32 v[52:53], v[100:101], v[210:211], v[52:53]
	v_pk_fma_f32 v[54:55], v[102:103], v[212:213], v[54:55]
	v_pk_fma_f32 v[64:65], v[112:113], v[210:211], v[64:65]
	v_pk_fma_f32 v[66:67], v[114:115], v[212:213], v[66:67]
	v_pk_fma_f32 v[76:77], v[124:125], v[210:211], v[76:77]
	v_pk_fma_f32 v[78:79], v[126:127], v[212:213], v[78:79]
	v_pk_fma_f32 v[88:89], v[136:137], v[210:211], v[88:89]
	v_pk_fma_f32 v[90:91], v[138:139], v[212:213], v[90:91]
	ds_read_b128 v[210:213], v208 offset:23552
	s_waitcnt lgkmcnt(2)
	v_pk_fma_f32 v[8:9], v[152:153], v[214:215], v[8:9]
	v_pk_fma_f32 v[10:11], v[154:155], v[216:217], v[10:11]
	v_pk_fma_f32 v[20:21], v[164:165], v[214:215], v[20:21]
	v_pk_fma_f32 v[22:23], v[166:167], v[216:217], v[22:23]
	v_pk_fma_f32 v[32:33], v[176:177], v[214:215], v[32:33]
	v_pk_fma_f32 v[34:35], v[178:179], v[216:217], v[34:35]
	v_pk_fma_f32 v[44:45], v[188:189], v[214:215], v[44:45]
	v_pk_fma_f32 v[46:47], v[190:191], v[216:217], v[46:47]
	v_pk_fma_f32 v[56:57], v[104:105], v[214:215], v[56:57]
	v_pk_fma_f32 v[58:59], v[106:107], v[216:217], v[58:59]
	v_pk_fma_f32 v[68:69], v[116:117], v[214:215], v[68:69]
	v_pk_fma_f32 v[70:71], v[118:119], v[216:217], v[70:71]
	v_pk_fma_f32 v[80:81], v[128:129], v[214:215], v[80:81]
	v_pk_fma_f32 v[82:83], v[130:131], v[216:217], v[82:83]
	v_pk_fma_f32 v[92:93], v[140:141], v[214:215], v[92:93]
	v_pk_fma_f32 v[94:95], v[142:143], v[216:217], v[94:95]
	ds_read_b128 v[214:217], v208 offset:24576
	s_waitcnt lgkmcnt(2)
	v_pk_fma_f32 v[12:13], v[156:157], v[218:219], v[12:13]
	v_pk_fma_f32 v[14:15], v[158:159], v[220:221], v[14:15]
	v_pk_fma_f32 v[24:25], v[168:169], v[218:219], v[24:25]
	v_pk_fma_f32 v[26:27], v[170:171], v[220:221], v[26:27]
	v_pk_fma_f32 v[36:37], v[180:181], v[218:219], v[36:37]
	v_pk_fma_f32 v[38:39], v[182:183], v[220:221], v[38:39]
	v_pk_fma_f32 v[48:49], v[192:193], v[218:219], v[48:49]
	v_pk_fma_f32 v[50:51], v[194:195], v[220:221], v[50:51]
	v_pk_fma_f32 v[60:61], v[108:109], v[218:219], v[60:61]
	v_pk_fma_f32 v[62:63], v[110:111], v[220:221], v[62:63]
	v_pk_fma_f32 v[72:73], v[120:121], v[218:219], v[72:73]
	v_pk_fma_f32 v[74:75], v[122:123], v[220:221], v[74:75]
	v_pk_fma_f32 v[84:85], v[132:133], v[218:219], v[84:85]
	v_pk_fma_f32 v[86:87], v[134:135], v[220:221], v[86:87]
	v_pk_fma_f32 v[96:97], v[144:145], v[218:219], v[96:97]
	v_pk_fma_f32 v[98:99], v[146:147], v[220:221], v[98:99]
	ds_read_b128 v[218:221], v208 offset:25600
	s_waitcnt vmcnt(3)
	v_lshlrev_b32_e32 v148, 16, v222
	v_and_b32_e32 v149, 0xffff0000, v222
	v_lshlrev_b32_e32 v150, 16, v223
	v_and_b32_e32 v151, 0xffff0000, v223
	v_lshlrev_b32_e32 v152, 16, v224
	v_and_b32_e32 v153, 0xffff0000, v224
	v_lshlrev_b32_e32 v154, 16, v225
	v_and_b32_e32 v155, 0xffff0000, v225
	v_lshlrev_b32_e32 v156, 16, v226
	v_and_b32_e32 v157, 0xffff0000, v226
	v_lshlrev_b32_e32 v158, 16, v227
	v_and_b32_e32 v159, 0xffff0000, v227
	s_waitcnt lgkmcnt(2)
	v_pk_fma_f32 v[4:5], v[160:161], v[210:211], v[4:5]
	v_pk_fma_f32 v[6:7], v[162:163], v[212:213], v[6:7]
	v_pk_fma_f32 v[16:17], v[172:173], v[210:211], v[16:17]
	v_pk_fma_f32 v[18:19], v[174:175], v[212:213], v[18:19]
	v_pk_fma_f32 v[28:29], v[184:185], v[210:211], v[28:29]
	v_pk_fma_f32 v[30:31], v[186:187], v[212:213], v[30:31]
	v_pk_fma_f32 v[40:41], v[100:101], v[210:211], v[40:41]
	v_pk_fma_f32 v[42:43], v[102:103], v[212:213], v[42:43]
	v_pk_fma_f32 v[52:53], v[112:113], v[210:211], v[52:53]
	v_pk_fma_f32 v[54:55], v[114:115], v[212:213], v[54:55]
	v_pk_fma_f32 v[64:65], v[124:125], v[210:211], v[64:65]
	v_pk_fma_f32 v[66:67], v[126:127], v[212:213], v[66:67]
	v_pk_fma_f32 v[76:77], v[136:137], v[210:211], v[76:77]
	v_pk_fma_f32 v[78:79], v[138:139], v[212:213], v[78:79]
	v_pk_fma_f32 v[88:89], v[148:149], v[210:211], v[88:89]
	v_pk_fma_f32 v[90:91], v[150:151], v[212:213], v[90:91]
	ds_read_b128 v[210:213], v208 offset:26624
	s_waitcnt lgkmcnt(2)
	v_pk_fma_f32 v[8:9], v[164:165], v[214:215], v[8:9]
	v_pk_fma_f32 v[10:11], v[166:167], v[216:217], v[10:11]
	v_pk_fma_f32 v[20:21], v[176:177], v[214:215], v[20:21]
	v_pk_fma_f32 v[22:23], v[178:179], v[216:217], v[22:23]
	v_pk_fma_f32 v[32:33], v[188:189], v[214:215], v[32:33]
	v_pk_fma_f32 v[34:35], v[190:191], v[216:217], v[34:35]
	v_pk_fma_f32 v[44:45], v[104:105], v[214:215], v[44:45]
	v_pk_fma_f32 v[46:47], v[106:107], v[216:217], v[46:47]
	v_pk_fma_f32 v[56:57], v[116:117], v[214:215], v[56:57]
	v_pk_fma_f32 v[58:59], v[118:119], v[216:217], v[58:59]
	v_pk_fma_f32 v[68:69], v[128:129], v[214:215], v[68:69]
	v_pk_fma_f32 v[70:71], v[130:131], v[216:217], v[70:71]
	v_pk_fma_f32 v[80:81], v[140:141], v[214:215], v[80:81]
	v_pk_fma_f32 v[82:83], v[142:143], v[216:217], v[82:83]
	v_pk_fma_f32 v[92:93], v[152:153], v[214:215], v[92:93]
	v_pk_fma_f32 v[94:95], v[154:155], v[216:217], v[94:95]
	ds_read_b128 v[214:217], v208 offset:27648
	s_waitcnt lgkmcnt(2)
	v_pk_fma_f32 v[12:13], v[168:169], v[218:219], v[12:13]
	v_pk_fma_f32 v[14:15], v[170:171], v[220:221], v[14:15]
	v_pk_fma_f32 v[24:25], v[180:181], v[218:219], v[24:25]
	v_pk_fma_f32 v[26:27], v[182:183], v[220:221], v[26:27]
	v_pk_fma_f32 v[36:37], v[192:193], v[218:219], v[36:37]
	v_pk_fma_f32 v[38:39], v[194:195], v[220:221], v[38:39]
	v_pk_fma_f32 v[48:49], v[108:109], v[218:219], v[48:49]
	v_pk_fma_f32 v[50:51], v[110:111], v[220:221], v[50:51]
	v_pk_fma_f32 v[60:61], v[120:121], v[218:219], v[60:61]
	v_pk_fma_f32 v[62:63], v[122:123], v[220:221], v[62:63]
	v_pk_fma_f32 v[72:73], v[132:133], v[218:219], v[72:73]
	v_pk_fma_f32 v[74:75], v[134:135], v[220:221], v[74:75]
	v_pk_fma_f32 v[84:85], v[144:145], v[218:219], v[84:85]
	v_pk_fma_f32 v[86:87], v[146:147], v[220:221], v[86:87]
	v_pk_fma_f32 v[96:97], v[156:157], v[218:219], v[96:97]
	v_pk_fma_f32 v[98:99], v[158:159], v[220:221], v[98:99]
	ds_read_b128 v[218:221], v208 offset:28672
	s_waitcnt vmcnt(0)
	v_lshlrev_b32_e32 v160, 16, v228
	v_and_b32_e32 v161, 0xffff0000, v228
	v_lshlrev_b32_e32 v162, 16, v229
	v_and_b32_e32 v163, 0xffff0000, v229
	v_lshlrev_b32_e32 v164, 16, v230
	v_and_b32_e32 v165, 0xffff0000, v230
	v_lshlrev_b32_e32 v166, 16, v231
	v_and_b32_e32 v167, 0xffff0000, v231
	v_lshlrev_b32_e32 v168, 16, v232
	v_and_b32_e32 v169, 0xffff0000, v232
	v_lshlrev_b32_e32 v170, 16, v233
	v_and_b32_e32 v171, 0xffff0000, v233
	global_load_dwordx4 v[222:225], v2, s[66:67]
	global_load_dwordx4 v[226:229], v2, s[66:67] offset:1024
	global_load_dwordx4 v[230:233], v2, s[66:67] offset:2048
	global_load_dwordx4 v[234:237], v2, s[42:43]
	global_load_dwordx4 v[238:241], v2, s[42:43] offset:1024
	global_load_dwordx4 v[242:245], v2, s[42:43] offset:2048
	s_waitcnt lgkmcnt(2)
	v_pk_fma_f32 v[4:5], v[172:173], v[210:211], v[4:5]
	v_pk_fma_f32 v[6:7], v[174:175], v[212:213], v[6:7]
	v_pk_fma_f32 v[16:17], v[184:185], v[210:211], v[16:17]
	v_pk_fma_f32 v[18:19], v[186:187], v[212:213], v[18:19]
	v_pk_fma_f32 v[28:29], v[100:101], v[210:211], v[28:29]
	v_pk_fma_f32 v[30:31], v[102:103], v[212:213], v[30:31]
	v_pk_fma_f32 v[40:41], v[112:113], v[210:211], v[40:41]
	v_pk_fma_f32 v[42:43], v[114:115], v[212:213], v[42:43]
	v_pk_fma_f32 v[52:53], v[124:125], v[210:211], v[52:53]
	v_pk_fma_f32 v[54:55], v[126:127], v[212:213], v[54:55]
	v_pk_fma_f32 v[64:65], v[136:137], v[210:211], v[64:65]
	v_pk_fma_f32 v[66:67], v[138:139], v[212:213], v[66:67]
	v_pk_fma_f32 v[76:77], v[148:149], v[210:211], v[76:77]
	v_pk_fma_f32 v[78:79], v[150:151], v[212:213], v[78:79]
	v_pk_fma_f32 v[88:89], v[160:161], v[210:211], v[88:89]
	v_pk_fma_f32 v[90:91], v[162:163], v[212:213], v[90:91]
	s_waitcnt lgkmcnt(1)
	v_pk_fma_f32 v[8:9], v[176:177], v[214:215], v[8:9]
	v_pk_fma_f32 v[10:11], v[178:179], v[216:217], v[10:11]
	v_pk_fma_f32 v[20:21], v[188:189], v[214:215], v[20:21]
	v_pk_fma_f32 v[22:23], v[190:191], v[216:217], v[22:23]
	v_pk_fma_f32 v[32:33], v[104:105], v[214:215], v[32:33]
	v_pk_fma_f32 v[34:35], v[106:107], v[216:217], v[34:35]
	v_pk_fma_f32 v[44:45], v[116:117], v[214:215], v[44:45]
	v_pk_fma_f32 v[46:47], v[118:119], v[216:217], v[46:47]
	v_pk_fma_f32 v[56:57], v[128:129], v[214:215], v[56:57]
	v_pk_fma_f32 v[58:59], v[130:131], v[216:217], v[58:59]
	v_pk_fma_f32 v[68:69], v[140:141], v[214:215], v[68:69]
	v_pk_fma_f32 v[70:71], v[142:143], v[216:217], v[70:71]
	v_pk_fma_f32 v[80:81], v[152:153], v[214:215], v[80:81]
	v_pk_fma_f32 v[82:83], v[154:155], v[216:217], v[82:83]
	v_pk_fma_f32 v[92:93], v[164:165], v[214:215], v[92:93]
	v_pk_fma_f32 v[94:95], v[166:167], v[216:217], v[94:95]
	s_waitcnt lgkmcnt(0)
	v_pk_fma_f32 v[12:13], v[180:181], v[218:219], v[12:13]
	v_pk_fma_f32 v[14:15], v[182:183], v[220:221], v[14:15]
	v_pk_fma_f32 v[24:25], v[192:193], v[218:219], v[24:25]
	v_pk_fma_f32 v[26:27], v[194:195], v[220:221], v[26:27]
	v_pk_fma_f32 v[36:37], v[108:109], v[218:219], v[36:37]
	v_pk_fma_f32 v[38:39], v[110:111], v[220:221], v[38:39]
	v_pk_fma_f32 v[48:49], v[120:121], v[218:219], v[48:49]
	v_pk_fma_f32 v[50:51], v[122:123], v[220:221], v[50:51]
	v_pk_fma_f32 v[60:61], v[132:133], v[218:219], v[60:61]
	v_pk_fma_f32 v[62:63], v[134:135], v[220:221], v[62:63]
	v_pk_fma_f32 v[72:73], v[144:145], v[218:219], v[72:73]
	v_pk_fma_f32 v[74:75], v[146:147], v[220:221], v[74:75]
	v_pk_fma_f32 v[84:85], v[156:157], v[218:219], v[84:85]
	v_pk_fma_f32 v[86:87], v[158:159], v[220:221], v[86:87]
	v_pk_fma_f32 v[96:97], v[168:169], v[218:219], v[96:97]
	v_pk_fma_f32 v[98:99], v[170:171], v[220:221], v[98:99]
	s_waitcnt vmcnt(0)
	v_mov_b32_e32 v197, 0x3727c5ac
	v_add_f32_e32 v100, v4, v5
	v_add_f32_e32 v100, v100, v6
	v_add_f32_e32 v100, v100, v7
	v_add_f32_e32 v100, v100, v8
	v_add_f32_e32 v100, v100, v9
	v_add_f32_e32 v100, v100, v10
	v_add_f32_e32 v100, v100, v11
	v_add_f32_e32 v100, v100, v12
	v_add_f32_e32 v100, v100, v13
	v_add_f32_e32 v100, v100, v14
	v_add_f32_e32 v100, v100, v15
	s_nop 1
	v_add_f32_dpp v100, v100, v100 row_shr:1 row_mask:0xf bank_mask:0xf bound_ctrl:1
	s_nop 1
	v_add_f32_dpp v100, v100, v100 row_shr:2 row_mask:0xf bank_mask:0xf bound_ctrl:1
	s_nop 1
	v_add_f32_dpp v100, v100, v100 row_shr:4 row_mask:0xf bank_mask:0xf bound_ctrl:1
	s_nop 1
	v_add_f32_dpp v100, v100, v100 row_shr:8 row_mask:0xf bank_mask:0xf bound_ctrl:1
	s_nop 1
	v_add_f32_dpp v100, v100, v100 row_bcast:15 row_mask:0xa bank_mask:0xf
	s_nop 1
	v_add_f32_dpp v100, v100, v100 row_bcast:31 row_mask:0xc bank_mask:0xf
	s_nop 0
	v_readlane_b32 s53, v100, 63
	s_nop 1
	v_mov_b32_e32 v101, s53
	v_fmac_f32_e32 v4, 0xbaaaaaab, v101
	v_fmac_f32_e32 v5, 0xbaaaaaab, v101
	v_fmac_f32_e32 v6, 0xbaaaaaab, v101
	v_fmac_f32_e32 v7, 0xbaaaaaab, v101
	v_fmac_f32_e32 v8, 0xbaaaaaab, v101
	v_fmac_f32_e32 v9, 0xbaaaaaab, v101
	v_fmac_f32_e32 v10, 0xbaaaaaab, v101
	v_fmac_f32_e32 v11, 0xbaaaaaab, v101
	v_fmac_f32_e32 v12, 0xbaaaaaab, v101
	v_fmac_f32_e32 v13, 0xbaaaaaab, v101
	v_fmac_f32_e32 v14, 0xbaaaaaab, v101
	v_fmac_f32_e32 v15, 0xbaaaaaab, v101
	v_mul_f32_e32 v102, v4, v4
	v_fmac_f32_e32 v102, v5, v5
	v_fmac_f32_e32 v102, v6, v6
	v_fmac_f32_e32 v102, v7, v7
	v_fmac_f32_e32 v102, v8, v8
	v_fmac_f32_e32 v102, v9, v9
	v_fmac_f32_e32 v102, v10, v10
	v_fmac_f32_e32 v102, v11, v11
	v_fmac_f32_e32 v102, v12, v12
	v_fmac_f32_e32 v102, v13, v13
	v_fmac_f32_e32 v102, v14, v14
	v_fmac_f32_e32 v102, v15, v15
	s_nop 1
	v_add_f32_dpp v102, v102, v102 row_shr:1 row_mask:0xf bank_mask:0xf bound_ctrl:1
	s_nop 1
	v_add_f32_dpp v102, v102, v102 row_shr:2 row_mask:0xf bank_mask:0xf bound_ctrl:1
	s_nop 1
	v_add_f32_dpp v102, v102, v102 row_shr:4 row_mask:0xf bank_mask:0xf bound_ctrl:1
	s_nop 1
	v_add_f32_dpp v102, v102, v102 row_shr:8 row_mask:0xf bank_mask:0xf bound_ctrl:1
	s_nop 1
	v_add_f32_dpp v102, v102, v102 row_bcast:15 row_mask:0xa bank_mask:0xf
	s_nop 1
	v_add_f32_dpp v102, v102, v102 row_bcast:31 row_mask:0xc bank_mask:0xf
	s_nop 0
	v_readlane_b32 s53, v102, 63
	s_nop 1
	v_mov_b32_e32 v101, s53
	v_fmamk_f32 v101, v101, 0x3aaaaaab, v197
	v_rsq_f32_e32 v103, v101
	s_nop 0
	v_mul_f32_e32 v4, v4, v103
	v_mul_f32_e32 v5, v5, v103
	v_mul_f32_e32 v6, v6, v103
	v_mul_f32_e32 v7, v7, v103
	v_mul_f32_e32 v8, v8, v103
	v_mul_f32_e32 v9, v9, v103
	v_mul_f32_e32 v10, v10, v103
	v_mul_f32_e32 v11, v11, v103
	v_mul_f32_e32 v12, v12, v103
	v_mul_f32_e32 v13, v13, v103
	v_mul_f32_e32 v14, v14, v103
	v_mul_f32_e32 v15, v15, v103
	v_fma_f32 v4, v222, v4, v234
	v_fma_f32 v5, v223, v5, v235
	v_fma_f32 v6, v224, v6, v236
	v_fma_f32 v7, v225, v7, v237
	v_fma_f32 v8, v226, v8, v238
	v_fma_f32 v9, v227, v9, v239
	v_fma_f32 v10, v228, v10, v240
	v_fma_f32 v11, v229, v11, v241
	v_fma_f32 v12, v230, v12, v242
	v_fma_f32 v13, v231, v13, v243
	v_fma_f32 v14, v232, v14, v244
	v_fma_f32 v15, v233, v15, v245
	s_lshl_b32 s52, s41, 11
	s_add_i32 s52, s52, 0
	v_add_u32_e32 v196, s52, v3
	v_mul_f32_e32 v108, 0xbfb8aa3b, v4
	v_exp_f32_e32 v109, v108
	s_nop 0
	v_add_f32_e32 v110, 1.0, v109
	v_div_scale_f32 v111, s[54:55], v110, v110, 1.0
	v_rcp_f32_e32 v112, v111
	v_div_scale_f32 v113, vcc, 1.0, v110, 1.0
	v_fma_f32 v115, -v111, v112, 1.0
	v_fmac_f32_e32 v112, v115, v112
	v_mul_f32_e32 v114, v113, v112
	v_fma_f32 v115, -v111, v114, v113
	v_fmac_f32_e32 v114, v115, v112
	v_fma_f32 v115, -v111, v114, v113
	v_div_fmas_f32 v115, v115, v112, v114
	v_div_fixup_f32 v115, v115, v110, 1.0
	v_mul_f32_e32 v120, v4, v115
	v_mul_f32_e32 v108, 0xbfb8aa3b, v5
	v_exp_f32_e32 v109, v108
	s_nop 0
	v_add_f32_e32 v110, 1.0, v109
	v_div_scale_f32 v111, s[54:55], v110, v110, 1.0
	v_rcp_f32_e32 v112, v111
	v_div_scale_f32 v113, vcc, 1.0, v110, 1.0
	v_fma_f32 v115, -v111, v112, 1.0
	v_fmac_f32_e32 v112, v115, v112
	v_mul_f32_e32 v114, v113, v112
	v_fma_f32 v115, -v111, v114, v113
	v_fmac_f32_e32 v114, v115, v112
	v_fma_f32 v115, -v111, v114, v113
	v_div_fmas_f32 v115, v115, v112, v114
	v_div_fixup_f32 v115, v115, v110, 1.0
	v_mul_f32_e32 v121, v5, v115
	v_mul_f32_e32 v108, 0xbfb8aa3b, v6
	v_exp_f32_e32 v109, v108
	s_nop 0
	v_add_f32_e32 v110, 1.0, v109
	v_div_scale_f32 v111, s[54:55], v110, v110, 1.0
	v_rcp_f32_e32 v112, v111
	v_div_scale_f32 v113, vcc, 1.0, v110, 1.0
	v_fma_f32 v115, -v111, v112, 1.0
	v_fmac_f32_e32 v112, v115, v112
	v_mul_f32_e32 v114, v113, v112
	v_fma_f32 v115, -v111, v114, v113
	v_fmac_f32_e32 v114, v115, v112
	v_fma_f32 v115, -v111, v114, v113
	v_div_fmas_f32 v115, v115, v112, v114
	v_div_fixup_f32 v115, v115, v110, 1.0
	v_mul_f32_e32 v122, v6, v115
	v_mul_f32_e32 v108, 0xbfb8aa3b, v7
	v_exp_f32_e32 v109, v108
	s_nop 0
	v_add_f32_e32 v110, 1.0, v109
	v_div_scale_f32 v111, s[54:55], v110, v110, 1.0
	v_rcp_f32_e32 v112, v111
	v_div_scale_f32 v113, vcc, 1.0, v110, 1.0
	v_fma_f32 v115, -v111, v112, 1.0
	v_fmac_f32_e32 v112, v115, v112
	v_mul_f32_e32 v114, v113, v112
	v_fma_f32 v115, -v111, v114, v113
	v_fmac_f32_e32 v114, v115, v112
	v_fma_f32 v115, -v111, v114, v113
	v_div_fmas_f32 v115, v115, v112, v114
	v_div_fixup_f32 v115, v115, v110, 1.0
	v_mul_f32_e32 v123, v7, v115
	v_cvt_pk_bf16_f32 v124, v120, v121
	v_cvt_pk_bf16_f32 v125, v122, v123
	global_store_dwordx2 v196, v[124:125], s[44:45]
	v_mul_f32_e32 v108, 0xbfb8aa3b, v8
	v_exp_f32_e32 v109, v108
	s_nop 0
	v_add_f32_e32 v110, 1.0, v109
	v_div_scale_f32 v111, s[54:55], v110, v110, 1.0
	v_rcp_f32_e32 v112, v111
	v_div_scale_f32 v113, vcc, 1.0, v110, 1.0
	v_fma_f32 v115, -v111, v112, 1.0
	v_fmac_f32_e32 v112, v115, v112
	v_mul_f32_e32 v114, v113, v112
	v_fma_f32 v115, -v111, v114, v113
	v_fmac_f32_e32 v114, v115, v112
	v_fma_f32 v115, -v111, v114, v113
	v_div_fmas_f32 v115, v115, v112, v114
	v_div_fixup_f32 v115, v115, v110, 1.0
	v_mul_f32_e32 v120, v8, v115
	v_mul_f32_e32 v108, 0xbfb8aa3b, v9
	v_exp_f32_e32 v109, v108
	s_nop 0
	v_add_f32_e32 v110, 1.0, v109
	v_div_scale_f32 v111, s[54:55], v110, v110, 1.0
	v_rcp_f32_e32 v112, v111
	v_div_scale_f32 v113, vcc, 1.0, v110, 1.0
	v_fma_f32 v115, -v111, v112, 1.0
	v_fmac_f32_e32 v112, v115, v112
	v_mul_f32_e32 v114, v113, v112
	v_fma_f32 v115, -v111, v114, v113
	v_fmac_f32_e32 v114, v115, v112
	v_fma_f32 v115, -v111, v114, v113
	v_div_fmas_f32 v115, v115, v112, v114
	v_div_fixup_f32 v115, v115, v110, 1.0
	v_mul_f32_e32 v121, v9, v115
	v_mul_f32_e32 v108, 0xbfb8aa3b, v10
	v_exp_f32_e32 v109, v108
	s_nop 0
	v_add_f32_e32 v110, 1.0, v109
	v_div_scale_f32 v111, s[54:55], v110, v110, 1.0
	v_rcp_f32_e32 v112, v111
	v_div_scale_f32 v113, vcc, 1.0, v110, 1.0
	v_fma_f32 v115, -v111, v112, 1.0
	v_fmac_f32_e32 v112, v115, v112
	v_mul_f32_e32 v114, v113, v112
	v_fma_f32 v115, -v111, v114, v113
	v_fmac_f32_e32 v114, v115, v112
	v_fma_f32 v115, -v111, v114, v113
	v_div_fmas_f32 v115, v115, v112, v114
	v_div_fixup_f32 v115, v115, v110, 1.0
	v_mul_f32_e32 v122, v10, v115
	v_mul_f32_e32 v108, 0xbfb8aa3b, v11
	v_exp_f32_e32 v109, v108
	s_nop 0
	v_add_f32_e32 v110, 1.0, v109
	v_div_scale_f32 v111, s[54:55], v110, v110, 1.0
	v_rcp_f32_e32 v112, v111
	v_div_scale_f32 v113, vcc, 1.0, v110, 1.0
	v_fma_f32 v115, -v111, v112, 1.0
	v_fmac_f32_e32 v112, v115, v112
	v_mul_f32_e32 v114, v113, v112
	v_fma_f32 v115, -v111, v114, v113
	v_fmac_f32_e32 v114, v115, v112
	v_fma_f32 v115, -v111, v114, v113
	v_div_fmas_f32 v115, v115, v112, v114
	v_div_fixup_f32 v115, v115, v110, 1.0
	v_mul_f32_e32 v123, v11, v115
	v_cvt_pk_bf16_f32 v124, v120, v121
	v_cvt_pk_bf16_f32 v125, v122, v123
	global_store_dwordx2 v196, v[124:125], s[44:45] offset:512
	v_mul_f32_e32 v108, 0xbfb8aa3b, v12
	v_exp_f32_e32 v109, v108
	s_nop 0
	v_add_f32_e32 v110, 1.0, v109
	v_div_scale_f32 v111, s[54:55], v110, v110, 1.0
	v_rcp_f32_e32 v112, v111
	v_div_scale_f32 v113, vcc, 1.0, v110, 1.0
	v_fma_f32 v115, -v111, v112, 1.0
	v_fmac_f32_e32 v112, v115, v112
	v_mul_f32_e32 v114, v113, v112
	v_fma_f32 v115, -v111, v114, v113
	v_fmac_f32_e32 v114, v115, v112
	v_fma_f32 v115, -v111, v114, v113
	v_div_fmas_f32 v115, v115, v112, v114
	v_div_fixup_f32 v115, v115, v110, 1.0
	v_mul_f32_e32 v120, v12, v115
	v_mul_f32_e32 v108, 0xbfb8aa3b, v13
	v_exp_f32_e32 v109, v108
	s_nop 0
	v_add_f32_e32 v110, 1.0, v109
	v_div_scale_f32 v111, s[54:55], v110, v110, 1.0
	v_rcp_f32_e32 v112, v111
	v_div_scale_f32 v113, vcc, 1.0, v110, 1.0
	v_fma_f32 v115, -v111, v112, 1.0
	v_fmac_f32_e32 v112, v115, v112
	v_mul_f32_e32 v114, v113, v112
	v_fma_f32 v115, -v111, v114, v113
	v_fmac_f32_e32 v114, v115, v112
	v_fma_f32 v115, -v111, v114, v113
	v_div_fmas_f32 v115, v115, v112, v114
	v_div_fixup_f32 v115, v115, v110, 1.0
	v_mul_f32_e32 v121, v13, v115
	v_mul_f32_e32 v108, 0xbfb8aa3b, v14
	v_exp_f32_e32 v109, v108
	s_nop 0
	v_add_f32_e32 v110, 1.0, v109
	v_div_scale_f32 v111, s[54:55], v110, v110, 1.0
	v_rcp_f32_e32 v112, v111
	v_div_scale_f32 v113, vcc, 1.0, v110, 1.0
	v_fma_f32 v115, -v111, v112, 1.0
	v_fmac_f32_e32 v112, v115, v112
	v_mul_f32_e32 v114, v113, v112
	v_fma_f32 v115, -v111, v114, v113
	v_fmac_f32_e32 v114, v115, v112
	v_fma_f32 v115, -v111, v114, v113
	v_div_fmas_f32 v115, v115, v112, v114
	v_div_fixup_f32 v115, v115, v110, 1.0
	v_mul_f32_e32 v122, v14, v115
	v_mul_f32_e32 v108, 0xbfb8aa3b, v15
	v_exp_f32_e32 v109, v108
	s_nop 0
	v_add_f32_e32 v110, 1.0, v109
	v_div_scale_f32 v111, s[54:55], v110, v110, 1.0
	v_rcp_f32_e32 v112, v111
	v_div_scale_f32 v113, vcc, 1.0, v110, 1.0
	v_fma_f32 v115, -v111, v112, 1.0
	v_fmac_f32_e32 v112, v115, v112
	v_mul_f32_e32 v114, v113, v112
	v_fma_f32 v115, -v111, v114, v113
	v_fmac_f32_e32 v114, v115, v112
	v_fma_f32 v115, -v111, v114, v113
	v_div_fmas_f32 v115, v115, v112, v114
	v_div_fixup_f32 v115, v115, v110, 1.0
	v_mul_f32_e32 v123, v15, v115
	v_cvt_pk_bf16_f32 v124, v120, v121
	v_cvt_pk_bf16_f32 v125, v122, v123
	global_store_dwordx2 v196, v[124:125], s[44:45] offset:1024
	v_add_f32_e32 v100, v16, v17
	v_add_f32_e32 v100, v100, v18
	v_add_f32_e32 v100, v100, v19
	v_add_f32_e32 v100, v100, v20
	v_add_f32_e32 v100, v100, v21
	v_add_f32_e32 v100, v100, v22
	v_add_f32_e32 v100, v100, v23
	v_add_f32_e32 v100, v100, v24
	v_add_f32_e32 v100, v100, v25
	v_add_f32_e32 v100, v100, v26
	v_add_f32_e32 v100, v100, v27
	s_nop 1
	v_add_f32_dpp v100, v100, v100 row_shr:1 row_mask:0xf bank_mask:0xf bound_ctrl:1
	s_nop 1
	v_add_f32_dpp v100, v100, v100 row_shr:2 row_mask:0xf bank_mask:0xf bound_ctrl:1
	s_nop 1
	v_add_f32_dpp v100, v100, v100 row_shr:4 row_mask:0xf bank_mask:0xf bound_ctrl:1
	s_nop 1
	v_add_f32_dpp v100, v100, v100 row_shr:8 row_mask:0xf bank_mask:0xf bound_ctrl:1
	s_nop 1
	v_add_f32_dpp v100, v100, v100 row_bcast:15 row_mask:0xa bank_mask:0xf
	s_nop 1
	v_add_f32_dpp v100, v100, v100 row_bcast:31 row_mask:0xc bank_mask:0xf
	s_nop 0
	v_readlane_b32 s53, v100, 63
	s_nop 1
	v_mov_b32_e32 v101, s53
	v_fmac_f32_e32 v16, 0xbaaaaaab, v101
	v_fmac_f32_e32 v17, 0xbaaaaaab, v101
	v_fmac_f32_e32 v18, 0xbaaaaaab, v101
	v_fmac_f32_e32 v19, 0xbaaaaaab, v101
	v_fmac_f32_e32 v20, 0xbaaaaaab, v101
	v_fmac_f32_e32 v21, 0xbaaaaaab, v101
	v_fmac_f32_e32 v22, 0xbaaaaaab, v101
	v_fmac_f32_e32 v23, 0xbaaaaaab, v101
	v_fmac_f32_e32 v24, 0xbaaaaaab, v101
	v_fmac_f32_e32 v25, 0xbaaaaaab, v101
	v_fmac_f32_e32 v26, 0xbaaaaaab, v101
	v_fmac_f32_e32 v27, 0xbaaaaaab, v101
	v_mul_f32_e32 v102, v16, v16
	v_fmac_f32_e32 v102, v17, v17
	v_fmac_f32_e32 v102, v18, v18
	v_fmac_f32_e32 v102, v19, v19
	v_fmac_f32_e32 v102, v20, v20
	v_fmac_f32_e32 v102, v21, v21
	v_fmac_f32_e32 v102, v22, v22
	v_fmac_f32_e32 v102, v23, v23
	v_fmac_f32_e32 v102, v24, v24
	v_fmac_f32_e32 v102, v25, v25
	v_fmac_f32_e32 v102, v26, v26
	v_fmac_f32_e32 v102, v27, v27
	s_nop 1
	v_add_f32_dpp v102, v102, v102 row_shr:1 row_mask:0xf bank_mask:0xf bound_ctrl:1
	s_nop 1
	v_add_f32_dpp v102, v102, v102 row_shr:2 row_mask:0xf bank_mask:0xf bound_ctrl:1
	s_nop 1
	v_add_f32_dpp v102, v102, v102 row_shr:4 row_mask:0xf bank_mask:0xf bound_ctrl:1
	s_nop 1
	v_add_f32_dpp v102, v102, v102 row_shr:8 row_mask:0xf bank_mask:0xf bound_ctrl:1
	s_nop 1
	v_add_f32_dpp v102, v102, v102 row_bcast:15 row_mask:0xa bank_mask:0xf
	s_nop 1
	v_add_f32_dpp v102, v102, v102 row_bcast:31 row_mask:0xc bank_mask:0xf
	s_nop 0
	v_readlane_b32 s53, v102, 63
	s_nop 1
	v_mov_b32_e32 v101, s53
	v_fmamk_f32 v101, v101, 0x3aaaaaab, v197
	v_rsq_f32_e32 v103, v101
	s_nop 0
	v_mul_f32_e32 v16, v16, v103
	v_mul_f32_e32 v17, v17, v103
	v_mul_f32_e32 v18, v18, v103
	v_mul_f32_e32 v19, v19, v103
	v_mul_f32_e32 v20, v20, v103
	v_mul_f32_e32 v21, v21, v103
	v_mul_f32_e32 v22, v22, v103
	v_mul_f32_e32 v23, v23, v103
	v_mul_f32_e32 v24, v24, v103
	v_mul_f32_e32 v25, v25, v103
	v_mul_f32_e32 v26, v26, v103
	v_mul_f32_e32 v27, v27, v103
	v_fma_f32 v16, v222, v16, v234
	v_fma_f32 v17, v223, v17, v235
	v_fma_f32 v18, v224, v18, v236
	v_fma_f32 v19, v225, v19, v237
	v_fma_f32 v20, v226, v20, v238
	v_fma_f32 v21, v227, v21, v239
	v_fma_f32 v22, v228, v22, v240
	v_fma_f32 v23, v229, v23, v241
	v_fma_f32 v24, v230, v24, v242
	v_fma_f32 v25, v231, v25, v243
	v_fma_f32 v26, v232, v26, v244
	v_fma_f32 v27, v233, v27, v245
	s_lshl_b32 s52, s41, 11
	s_add_i32 s52, s52, 2048
	v_add_u32_e32 v196, s52, v3
	v_mul_f32_e32 v108, 0xbfb8aa3b, v16
	v_exp_f32_e32 v109, v108
	s_nop 0
	v_add_f32_e32 v110, 1.0, v109
	v_div_scale_f32 v111, s[54:55], v110, v110, 1.0
	v_rcp_f32_e32 v112, v111
	v_div_scale_f32 v113, vcc, 1.0, v110, 1.0
	v_fma_f32 v115, -v111, v112, 1.0
	v_fmac_f32_e32 v112, v115, v112
	v_mul_f32_e32 v114, v113, v112
	v_fma_f32 v115, -v111, v114, v113
	v_fmac_f32_e32 v114, v115, v112
	v_fma_f32 v115, -v111, v114, v113
	v_div_fmas_f32 v115, v115, v112, v114
	v_div_fixup_f32 v115, v115, v110, 1.0
	v_mul_f32_e32 v120, v16, v115
	v_mul_f32_e32 v108, 0xbfb8aa3b, v17
	v_exp_f32_e32 v109, v108
	s_nop 0
	v_add_f32_e32 v110, 1.0, v109
	v_div_scale_f32 v111, s[54:55], v110, v110, 1.0
	v_rcp_f32_e32 v112, v111
	v_div_scale_f32 v113, vcc, 1.0, v110, 1.0
	v_fma_f32 v115, -v111, v112, 1.0
	v_fmac_f32_e32 v112, v115, v112
	v_mul_f32_e32 v114, v113, v112
	v_fma_f32 v115, -v111, v114, v113
	v_fmac_f32_e32 v114, v115, v112
	v_fma_f32 v115, -v111, v114, v113
	v_div_fmas_f32 v115, v115, v112, v114
	v_div_fixup_f32 v115, v115, v110, 1.0
	v_mul_f32_e32 v121, v17, v115
	v_mul_f32_e32 v108, 0xbfb8aa3b, v18
	v_exp_f32_e32 v109, v108
	s_nop 0
	v_add_f32_e32 v110, 1.0, v109
	v_div_scale_f32 v111, s[54:55], v110, v110, 1.0
	v_rcp_f32_e32 v112, v111
	v_div_scale_f32 v113, vcc, 1.0, v110, 1.0
	v_fma_f32 v115, -v111, v112, 1.0
	v_fmac_f32_e32 v112, v115, v112
	v_mul_f32_e32 v114, v113, v112
	v_fma_f32 v115, -v111, v114, v113
	v_fmac_f32_e32 v114, v115, v112
	v_fma_f32 v115, -v111, v114, v113
	v_div_fmas_f32 v115, v115, v112, v114
	v_div_fixup_f32 v115, v115, v110, 1.0
	v_mul_f32_e32 v122, v18, v115
	v_mul_f32_e32 v108, 0xbfb8aa3b, v19
	v_exp_f32_e32 v109, v108
	s_nop 0
	v_add_f32_e32 v110, 1.0, v109
	v_div_scale_f32 v111, s[54:55], v110, v110, 1.0
	v_rcp_f32_e32 v112, v111
	v_div_scale_f32 v113, vcc, 1.0, v110, 1.0
	v_fma_f32 v115, -v111, v112, 1.0
	v_fmac_f32_e32 v112, v115, v112
	v_mul_f32_e32 v114, v113, v112
	v_fma_f32 v115, -v111, v114, v113
	v_fmac_f32_e32 v114, v115, v112
	v_fma_f32 v115, -v111, v114, v113
	v_div_fmas_f32 v115, v115, v112, v114
	v_div_fixup_f32 v115, v115, v110, 1.0
	v_mul_f32_e32 v123, v19, v115
	v_cvt_pk_bf16_f32 v124, v120, v121
	v_cvt_pk_bf16_f32 v125, v122, v123
	global_store_dwordx2 v196, v[124:125], s[44:45]
	v_mul_f32_e32 v108, 0xbfb8aa3b, v20
	v_exp_f32_e32 v109, v108
	s_nop 0
	v_add_f32_e32 v110, 1.0, v109
	v_div_scale_f32 v111, s[54:55], v110, v110, 1.0
	v_rcp_f32_e32 v112, v111
	v_div_scale_f32 v113, vcc, 1.0, v110, 1.0
	v_fma_f32 v115, -v111, v112, 1.0
	v_fmac_f32_e32 v112, v115, v112
	v_mul_f32_e32 v114, v113, v112
	v_fma_f32 v115, -v111, v114, v113
	v_fmac_f32_e32 v114, v115, v112
	v_fma_f32 v115, -v111, v114, v113
	v_div_fmas_f32 v115, v115, v112, v114
	v_div_fixup_f32 v115, v115, v110, 1.0
	v_mul_f32_e32 v120, v20, v115
	v_mul_f32_e32 v108, 0xbfb8aa3b, v21
	v_exp_f32_e32 v109, v108
	s_nop 0
	v_add_f32_e32 v110, 1.0, v109
	v_div_scale_f32 v111, s[54:55], v110, v110, 1.0
	v_rcp_f32_e32 v112, v111
	v_div_scale_f32 v113, vcc, 1.0, v110, 1.0
	v_fma_f32 v115, -v111, v112, 1.0
	v_fmac_f32_e32 v112, v115, v112
	v_mul_f32_e32 v114, v113, v112
	v_fma_f32 v115, -v111, v114, v113
	v_fmac_f32_e32 v114, v115, v112
	v_fma_f32 v115, -v111, v114, v113
	v_div_fmas_f32 v115, v115, v112, v114
	v_div_fixup_f32 v115, v115, v110, 1.0
	v_mul_f32_e32 v121, v21, v115
	v_mul_f32_e32 v108, 0xbfb8aa3b, v22
	v_exp_f32_e32 v109, v108
	s_nop 0
	v_add_f32_e32 v110, 1.0, v109
	v_div_scale_f32 v111, s[54:55], v110, v110, 1.0
	v_rcp_f32_e32 v112, v111
	v_div_scale_f32 v113, vcc, 1.0, v110, 1.0
	v_fma_f32 v115, -v111, v112, 1.0
	v_fmac_f32_e32 v112, v115, v112
	v_mul_f32_e32 v114, v113, v112
	v_fma_f32 v115, -v111, v114, v113
	v_fmac_f32_e32 v114, v115, v112
	v_fma_f32 v115, -v111, v114, v113
	v_div_fmas_f32 v115, v115, v112, v114
	v_div_fixup_f32 v115, v115, v110, 1.0
	v_mul_f32_e32 v122, v22, v115
	v_mul_f32_e32 v108, 0xbfb8aa3b, v23
	v_exp_f32_e32 v109, v108
	s_nop 0
	v_add_f32_e32 v110, 1.0, v109
	v_div_scale_f32 v111, s[54:55], v110, v110, 1.0
	v_rcp_f32_e32 v112, v111
	v_div_scale_f32 v113, vcc, 1.0, v110, 1.0
	v_fma_f32 v115, -v111, v112, 1.0
	v_fmac_f32_e32 v112, v115, v112
	v_mul_f32_e32 v114, v113, v112
	v_fma_f32 v115, -v111, v114, v113
	v_fmac_f32_e32 v114, v115, v112
	v_fma_f32 v115, -v111, v114, v113
	v_div_fmas_f32 v115, v115, v112, v114
	v_div_fixup_f32 v115, v115, v110, 1.0
	v_mul_f32_e32 v123, v23, v115
	v_cvt_pk_bf16_f32 v124, v120, v121
	v_cvt_pk_bf16_f32 v125, v122, v123
	global_store_dwordx2 v196, v[124:125], s[44:45] offset:512
	v_mul_f32_e32 v108, 0xbfb8aa3b, v24
	v_exp_f32_e32 v109, v108
	s_nop 0
	v_add_f32_e32 v110, 1.0, v109
	v_div_scale_f32 v111, s[54:55], v110, v110, 1.0
	v_rcp_f32_e32 v112, v111
	v_div_scale_f32 v113, vcc, 1.0, v110, 1.0
	v_fma_f32 v115, -v111, v112, 1.0
	v_fmac_f32_e32 v112, v115, v112
	v_mul_f32_e32 v114, v113, v112
	v_fma_f32 v115, -v111, v114, v113
	v_fmac_f32_e32 v114, v115, v112
	v_fma_f32 v115, -v111, v114, v113
	v_div_fmas_f32 v115, v115, v112, v114
	v_div_fixup_f32 v115, v115, v110, 1.0
	v_mul_f32_e32 v120, v24, v115
	v_mul_f32_e32 v108, 0xbfb8aa3b, v25
	v_exp_f32_e32 v109, v108
	s_nop 0
	v_add_f32_e32 v110, 1.0, v109
	v_div_scale_f32 v111, s[54:55], v110, v110, 1.0
	v_rcp_f32_e32 v112, v111
	v_div_scale_f32 v113, vcc, 1.0, v110, 1.0
	v_fma_f32 v115, -v111, v112, 1.0
	v_fmac_f32_e32 v112, v115, v112
	v_mul_f32_e32 v114, v113, v112
	v_fma_f32 v115, -v111, v114, v113
	v_fmac_f32_e32 v114, v115, v112
	v_fma_f32 v115, -v111, v114, v113
	v_div_fmas_f32 v115, v115, v112, v114
	v_div_fixup_f32 v115, v115, v110, 1.0
	v_mul_f32_e32 v121, v25, v115
	v_mul_f32_e32 v108, 0xbfb8aa3b, v26
	v_exp_f32_e32 v109, v108
	s_nop 0
	v_add_f32_e32 v110, 1.0, v109
	v_div_scale_f32 v111, s[54:55], v110, v110, 1.0
	v_rcp_f32_e32 v112, v111
	v_div_scale_f32 v113, vcc, 1.0, v110, 1.0
	v_fma_f32 v115, -v111, v112, 1.0
	v_fmac_f32_e32 v112, v115, v112
	v_mul_f32_e32 v114, v113, v112
	v_fma_f32 v115, -v111, v114, v113
	v_fmac_f32_e32 v114, v115, v112
	v_fma_f32 v115, -v111, v114, v113
	v_div_fmas_f32 v115, v115, v112, v114
	v_div_fixup_f32 v115, v115, v110, 1.0
	v_mul_f32_e32 v122, v26, v115
	v_mul_f32_e32 v108, 0xbfb8aa3b, v27
	v_exp_f32_e32 v109, v108
	s_nop 0
	v_add_f32_e32 v110, 1.0, v109
	v_div_scale_f32 v111, s[54:55], v110, v110, 1.0
	v_rcp_f32_e32 v112, v111
	v_div_scale_f32 v113, vcc, 1.0, v110, 1.0
	v_fma_f32 v115, -v111, v112, 1.0
	v_fmac_f32_e32 v112, v115, v112
	v_mul_f32_e32 v114, v113, v112
	v_fma_f32 v115, -v111, v114, v113
	v_fmac_f32_e32 v114, v115, v112
	v_fma_f32 v115, -v111, v114, v113
	v_div_fmas_f32 v115, v115, v112, v114
	v_div_fixup_f32 v115, v115, v110, 1.0
	v_mul_f32_e32 v123, v27, v115
	v_cvt_pk_bf16_f32 v124, v120, v121
	v_cvt_pk_bf16_f32 v125, v122, v123
	global_store_dwordx2 v196, v[124:125], s[44:45] offset:1024
	v_add_f32_e32 v100, v28, v29
	v_add_f32_e32 v100, v100, v30
	v_add_f32_e32 v100, v100, v31
	v_add_f32_e32 v100, v100, v32
	v_add_f32_e32 v100, v100, v33
	v_add_f32_e32 v100, v100, v34
	v_add_f32_e32 v100, v100, v35
	v_add_f32_e32 v100, v100, v36
	v_add_f32_e32 v100, v100, v37
	v_add_f32_e32 v100, v100, v38
	v_add_f32_e32 v100, v100, v39
	s_nop 1
	v_add_f32_dpp v100, v100, v100 row_shr:1 row_mask:0xf bank_mask:0xf bound_ctrl:1
	s_nop 1
	v_add_f32_dpp v100, v100, v100 row_shr:2 row_mask:0xf bank_mask:0xf bound_ctrl:1
	s_nop 1
	v_add_f32_dpp v100, v100, v100 row_shr:4 row_mask:0xf bank_mask:0xf bound_ctrl:1
	s_nop 1
	v_add_f32_dpp v100, v100, v100 row_shr:8 row_mask:0xf bank_mask:0xf bound_ctrl:1
	s_nop 1
	v_add_f32_dpp v100, v100, v100 row_bcast:15 row_mask:0xa bank_mask:0xf
	s_nop 1
	v_add_f32_dpp v100, v100, v100 row_bcast:31 row_mask:0xc bank_mask:0xf
	s_nop 0
	v_readlane_b32 s53, v100, 63
	s_nop 1
	v_mov_b32_e32 v101, s53
	v_fmac_f32_e32 v28, 0xbaaaaaab, v101
	v_fmac_f32_e32 v29, 0xbaaaaaab, v101
	v_fmac_f32_e32 v30, 0xbaaaaaab, v101
	v_fmac_f32_e32 v31, 0xbaaaaaab, v101
	v_fmac_f32_e32 v32, 0xbaaaaaab, v101
	v_fmac_f32_e32 v33, 0xbaaaaaab, v101
	v_fmac_f32_e32 v34, 0xbaaaaaab, v101
	v_fmac_f32_e32 v35, 0xbaaaaaab, v101
	v_fmac_f32_e32 v36, 0xbaaaaaab, v101
	v_fmac_f32_e32 v37, 0xbaaaaaab, v101
	v_fmac_f32_e32 v38, 0xbaaaaaab, v101
	v_fmac_f32_e32 v39, 0xbaaaaaab, v101
	v_mul_f32_e32 v102, v28, v28
	v_fmac_f32_e32 v102, v29, v29
	v_fmac_f32_e32 v102, v30, v30
	v_fmac_f32_e32 v102, v31, v31
	v_fmac_f32_e32 v102, v32, v32
	v_fmac_f32_e32 v102, v33, v33
	v_fmac_f32_e32 v102, v34, v34
	v_fmac_f32_e32 v102, v35, v35
	v_fmac_f32_e32 v102, v36, v36
	v_fmac_f32_e32 v102, v37, v37
	v_fmac_f32_e32 v102, v38, v38
	v_fmac_f32_e32 v102, v39, v39
	s_nop 1
	v_add_f32_dpp v102, v102, v102 row_shr:1 row_mask:0xf bank_mask:0xf bound_ctrl:1
	s_nop 1
	v_add_f32_dpp v102, v102, v102 row_shr:2 row_mask:0xf bank_mask:0xf bound_ctrl:1
	s_nop 1
	v_add_f32_dpp v102, v102, v102 row_shr:4 row_mask:0xf bank_mask:0xf bound_ctrl:1
	s_nop 1
	v_add_f32_dpp v102, v102, v102 row_shr:8 row_mask:0xf bank_mask:0xf bound_ctrl:1
	s_nop 1
	v_add_f32_dpp v102, v102, v102 row_bcast:15 row_mask:0xa bank_mask:0xf
	s_nop 1
	v_add_f32_dpp v102, v102, v102 row_bcast:31 row_mask:0xc bank_mask:0xf
	s_nop 0
	v_readlane_b32 s53, v102, 63
	s_nop 1
	v_mov_b32_e32 v101, s53
	v_fmamk_f32 v101, v101, 0x3aaaaaab, v197
	v_rsq_f32_e32 v103, v101
	s_nop 0
	v_mul_f32_e32 v28, v28, v103
	v_mul_f32_e32 v29, v29, v103
	v_mul_f32_e32 v30, v30, v103
	v_mul_f32_e32 v31, v31, v103
	v_mul_f32_e32 v32, v32, v103
	v_mul_f32_e32 v33, v33, v103
	v_mul_f32_e32 v34, v34, v103
	v_mul_f32_e32 v35, v35, v103
	v_mul_f32_e32 v36, v36, v103
	v_mul_f32_e32 v37, v37, v103
	v_mul_f32_e32 v38, v38, v103
	v_mul_f32_e32 v39, v39, v103
	v_fma_f32 v28, v222, v28, v234
	v_fma_f32 v29, v223, v29, v235
	v_fma_f32 v30, v224, v30, v236
	v_fma_f32 v31, v225, v31, v237
	v_fma_f32 v32, v226, v32, v238
	v_fma_f32 v33, v227, v33, v239
	v_fma_f32 v34, v228, v34, v240
	v_fma_f32 v35, v229, v35, v241
	v_fma_f32 v36, v230, v36, v242
	v_fma_f32 v37, v231, v37, v243
	v_fma_f32 v38, v232, v38, v244
	v_fma_f32 v39, v233, v39, v245
	s_lshl_b32 s52, s41, 11
	s_add_i32 s52, s52, 4096
	v_add_u32_e32 v196, s52, v3
	v_mul_f32_e32 v108, 0xbfb8aa3b, v28
	v_exp_f32_e32 v109, v108
	s_nop 0
	v_add_f32_e32 v110, 1.0, v109
	v_div_scale_f32 v111, s[54:55], v110, v110, 1.0
	v_rcp_f32_e32 v112, v111
	v_div_scale_f32 v113, vcc, 1.0, v110, 1.0
	v_fma_f32 v115, -v111, v112, 1.0
	v_fmac_f32_e32 v112, v115, v112
	v_mul_f32_e32 v114, v113, v112
	v_fma_f32 v115, -v111, v114, v113
	v_fmac_f32_e32 v114, v115, v112
	v_fma_f32 v115, -v111, v114, v113
	v_div_fmas_f32 v115, v115, v112, v114
	v_div_fixup_f32 v115, v115, v110, 1.0
	v_mul_f32_e32 v120, v28, v115
	v_mul_f32_e32 v108, 0xbfb8aa3b, v29
	v_exp_f32_e32 v109, v108
	s_nop 0
	v_add_f32_e32 v110, 1.0, v109
	v_div_scale_f32 v111, s[54:55], v110, v110, 1.0
	v_rcp_f32_e32 v112, v111
	v_div_scale_f32 v113, vcc, 1.0, v110, 1.0
	v_fma_f32 v115, -v111, v112, 1.0
	v_fmac_f32_e32 v112, v115, v112
	v_mul_f32_e32 v114, v113, v112
	v_fma_f32 v115, -v111, v114, v113
	v_fmac_f32_e32 v114, v115, v112
	v_fma_f32 v115, -v111, v114, v113
	v_div_fmas_f32 v115, v115, v112, v114
	v_div_fixup_f32 v115, v115, v110, 1.0
	v_mul_f32_e32 v121, v29, v115
	v_mul_f32_e32 v108, 0xbfb8aa3b, v30
	v_exp_f32_e32 v109, v108
	s_nop 0
	v_add_f32_e32 v110, 1.0, v109
	v_div_scale_f32 v111, s[54:55], v110, v110, 1.0
	v_rcp_f32_e32 v112, v111
	v_div_scale_f32 v113, vcc, 1.0, v110, 1.0
	v_fma_f32 v115, -v111, v112, 1.0
	v_fmac_f32_e32 v112, v115, v112
	v_mul_f32_e32 v114, v113, v112
	v_fma_f32 v115, -v111, v114, v113
	v_fmac_f32_e32 v114, v115, v112
	v_fma_f32 v115, -v111, v114, v113
	v_div_fmas_f32 v115, v115, v112, v114
	v_div_fixup_f32 v115, v115, v110, 1.0
	v_mul_f32_e32 v122, v30, v115
	v_mul_f32_e32 v108, 0xbfb8aa3b, v31
	v_exp_f32_e32 v109, v108
	s_nop 0
	v_add_f32_e32 v110, 1.0, v109
	v_div_scale_f32 v111, s[54:55], v110, v110, 1.0
	v_rcp_f32_e32 v112, v111
	v_div_scale_f32 v113, vcc, 1.0, v110, 1.0
	v_fma_f32 v115, -v111, v112, 1.0
	v_fmac_f32_e32 v112, v115, v112
	v_mul_f32_e32 v114, v113, v112
	v_fma_f32 v115, -v111, v114, v113
	v_fmac_f32_e32 v114, v115, v112
	v_fma_f32 v115, -v111, v114, v113
	v_div_fmas_f32 v115, v115, v112, v114
	v_div_fixup_f32 v115, v115, v110, 1.0
	v_mul_f32_e32 v123, v31, v115
	v_cvt_pk_bf16_f32 v124, v120, v121
	v_cvt_pk_bf16_f32 v125, v122, v123
	global_store_dwordx2 v196, v[124:125], s[44:45]
	v_mul_f32_e32 v108, 0xbfb8aa3b, v32
	v_exp_f32_e32 v109, v108
	s_nop 0
	v_add_f32_e32 v110, 1.0, v109
	v_div_scale_f32 v111, s[54:55], v110, v110, 1.0
	v_rcp_f32_e32 v112, v111
	v_div_scale_f32 v113, vcc, 1.0, v110, 1.0
	v_fma_f32 v115, -v111, v112, 1.0
	v_fmac_f32_e32 v112, v115, v112
	v_mul_f32_e32 v114, v113, v112
	v_fma_f32 v115, -v111, v114, v113
	v_fmac_f32_e32 v114, v115, v112
	v_fma_f32 v115, -v111, v114, v113
	v_div_fmas_f32 v115, v115, v112, v114
	v_div_fixup_f32 v115, v115, v110, 1.0
	v_mul_f32_e32 v120, v32, v115
	v_mul_f32_e32 v108, 0xbfb8aa3b, v33
	v_exp_f32_e32 v109, v108
	s_nop 0
	v_add_f32_e32 v110, 1.0, v109
	v_div_scale_f32 v111, s[54:55], v110, v110, 1.0
	v_rcp_f32_e32 v112, v111
	v_div_scale_f32 v113, vcc, 1.0, v110, 1.0
	v_fma_f32 v115, -v111, v112, 1.0
	v_fmac_f32_e32 v112, v115, v112
	v_mul_f32_e32 v114, v113, v112
	v_fma_f32 v115, -v111, v114, v113
	v_fmac_f32_e32 v114, v115, v112
	v_fma_f32 v115, -v111, v114, v113
	v_div_fmas_f32 v115, v115, v112, v114
	v_div_fixup_f32 v115, v115, v110, 1.0
	v_mul_f32_e32 v121, v33, v115
	v_mul_f32_e32 v108, 0xbfb8aa3b, v34
	v_exp_f32_e32 v109, v108
	s_nop 0
	v_add_f32_e32 v110, 1.0, v109
	v_div_scale_f32 v111, s[54:55], v110, v110, 1.0
	v_rcp_f32_e32 v112, v111
	v_div_scale_f32 v113, vcc, 1.0, v110, 1.0
	v_fma_f32 v115, -v111, v112, 1.0
	v_fmac_f32_e32 v112, v115, v112
	v_mul_f32_e32 v114, v113, v112
	v_fma_f32 v115, -v111, v114, v113
	v_fmac_f32_e32 v114, v115, v112
	v_fma_f32 v115, -v111, v114, v113
	v_div_fmas_f32 v115, v115, v112, v114
	v_div_fixup_f32 v115, v115, v110, 1.0
	v_mul_f32_e32 v122, v34, v115
	v_mul_f32_e32 v108, 0xbfb8aa3b, v35
	v_exp_f32_e32 v109, v108
	s_nop 0
	v_add_f32_e32 v110, 1.0, v109
	v_div_scale_f32 v111, s[54:55], v110, v110, 1.0
	v_rcp_f32_e32 v112, v111
	v_div_scale_f32 v113, vcc, 1.0, v110, 1.0
	v_fma_f32 v115, -v111, v112, 1.0
	v_fmac_f32_e32 v112, v115, v112
	v_mul_f32_e32 v114, v113, v112
	v_fma_f32 v115, -v111, v114, v113
	v_fmac_f32_e32 v114, v115, v112
	v_fma_f32 v115, -v111, v114, v113
	v_div_fmas_f32 v115, v115, v112, v114
	v_div_fixup_f32 v115, v115, v110, 1.0
	v_mul_f32_e32 v123, v35, v115
	v_cvt_pk_bf16_f32 v124, v120, v121
	v_cvt_pk_bf16_f32 v125, v122, v123
	global_store_dwordx2 v196, v[124:125], s[44:45] offset:512
	v_mul_f32_e32 v108, 0xbfb8aa3b, v36
	v_exp_f32_e32 v109, v108
	s_nop 0
	v_add_f32_e32 v110, 1.0, v109
	v_div_scale_f32 v111, s[54:55], v110, v110, 1.0
	v_rcp_f32_e32 v112, v111
	v_div_scale_f32 v113, vcc, 1.0, v110, 1.0
	v_fma_f32 v115, -v111, v112, 1.0
	v_fmac_f32_e32 v112, v115, v112
	v_mul_f32_e32 v114, v113, v112
	v_fma_f32 v115, -v111, v114, v113
	v_fmac_f32_e32 v114, v115, v112
	v_fma_f32 v115, -v111, v114, v113
	v_div_fmas_f32 v115, v115, v112, v114
	v_div_fixup_f32 v115, v115, v110, 1.0
	v_mul_f32_e32 v120, v36, v115
	v_mul_f32_e32 v108, 0xbfb8aa3b, v37
	v_exp_f32_e32 v109, v108
	s_nop 0
	v_add_f32_e32 v110, 1.0, v109
	v_div_scale_f32 v111, s[54:55], v110, v110, 1.0
	v_rcp_f32_e32 v112, v111
	v_div_scale_f32 v113, vcc, 1.0, v110, 1.0
	v_fma_f32 v115, -v111, v112, 1.0
	v_fmac_f32_e32 v112, v115, v112
	v_mul_f32_e32 v114, v113, v112
	v_fma_f32 v115, -v111, v114, v113
	v_fmac_f32_e32 v114, v115, v112
	v_fma_f32 v115, -v111, v114, v113
	v_div_fmas_f32 v115, v115, v112, v114
	v_div_fixup_f32 v115, v115, v110, 1.0
	v_mul_f32_e32 v121, v37, v115
	v_mul_f32_e32 v108, 0xbfb8aa3b, v38
	v_exp_f32_e32 v109, v108
	s_nop 0
	v_add_f32_e32 v110, 1.0, v109
	v_div_scale_f32 v111, s[54:55], v110, v110, 1.0
	v_rcp_f32_e32 v112, v111
	v_div_scale_f32 v113, vcc, 1.0, v110, 1.0
	v_fma_f32 v115, -v111, v112, 1.0
	v_fmac_f32_e32 v112, v115, v112
	v_mul_f32_e32 v114, v113, v112
	v_fma_f32 v115, -v111, v114, v113
	v_fmac_f32_e32 v114, v115, v112
	v_fma_f32 v115, -v111, v114, v113
	v_div_fmas_f32 v115, v115, v112, v114
	v_div_fixup_f32 v115, v115, v110, 1.0
	v_mul_f32_e32 v122, v38, v115
	v_mul_f32_e32 v108, 0xbfb8aa3b, v39
	v_exp_f32_e32 v109, v108
	s_nop 0
	v_add_f32_e32 v110, 1.0, v109
	v_div_scale_f32 v111, s[54:55], v110, v110, 1.0
	v_rcp_f32_e32 v112, v111
	v_div_scale_f32 v113, vcc, 1.0, v110, 1.0
	v_fma_f32 v115, -v111, v112, 1.0
	v_fmac_f32_e32 v112, v115, v112
	v_mul_f32_e32 v114, v113, v112
	v_fma_f32 v115, -v111, v114, v113
	v_fmac_f32_e32 v114, v115, v112
	v_fma_f32 v115, -v111, v114, v113
	v_div_fmas_f32 v115, v115, v112, v114
	v_div_fixup_f32 v115, v115, v110, 1.0
	v_mul_f32_e32 v123, v39, v115
	v_cvt_pk_bf16_f32 v124, v120, v121
	v_cvt_pk_bf16_f32 v125, v122, v123
	global_store_dwordx2 v196, v[124:125], s[44:45] offset:1024
	v_add_f32_e32 v100, v40, v41
	v_add_f32_e32 v100, v100, v42
	v_add_f32_e32 v100, v100, v43
	v_add_f32_e32 v100, v100, v44
	v_add_f32_e32 v100, v100, v45
	v_add_f32_e32 v100, v100, v46
	v_add_f32_e32 v100, v100, v47
	v_add_f32_e32 v100, v100, v48
	v_add_f32_e32 v100, v100, v49
	v_add_f32_e32 v100, v100, v50
	v_add_f32_e32 v100, v100, v51
	s_nop 1
	v_add_f32_dpp v100, v100, v100 row_shr:1 row_mask:0xf bank_mask:0xf bound_ctrl:1
	s_nop 1
	v_add_f32_dpp v100, v100, v100 row_shr:2 row_mask:0xf bank_mask:0xf bound_ctrl:1
	s_nop 1
	v_add_f32_dpp v100, v100, v100 row_shr:4 row_mask:0xf bank_mask:0xf bound_ctrl:1
	s_nop 1
	v_add_f32_dpp v100, v100, v100 row_shr:8 row_mask:0xf bank_mask:0xf bound_ctrl:1
	s_nop 1
	v_add_f32_dpp v100, v100, v100 row_bcast:15 row_mask:0xa bank_mask:0xf
	s_nop 1
	v_add_f32_dpp v100, v100, v100 row_bcast:31 row_mask:0xc bank_mask:0xf
	s_nop 0
	v_readlane_b32 s53, v100, 63
	s_nop 1
	v_mov_b32_e32 v101, s53
	v_fmac_f32_e32 v40, 0xbaaaaaab, v101
	v_fmac_f32_e32 v41, 0xbaaaaaab, v101
	v_fmac_f32_e32 v42, 0xbaaaaaab, v101
	v_fmac_f32_e32 v43, 0xbaaaaaab, v101
	v_fmac_f32_e32 v44, 0xbaaaaaab, v101
	v_fmac_f32_e32 v45, 0xbaaaaaab, v101
	v_fmac_f32_e32 v46, 0xbaaaaaab, v101
	v_fmac_f32_e32 v47, 0xbaaaaaab, v101
	v_fmac_f32_e32 v48, 0xbaaaaaab, v101
	v_fmac_f32_e32 v49, 0xbaaaaaab, v101
	v_fmac_f32_e32 v50, 0xbaaaaaab, v101
	v_fmac_f32_e32 v51, 0xbaaaaaab, v101
	v_mul_f32_e32 v102, v40, v40
	v_fmac_f32_e32 v102, v41, v41
	v_fmac_f32_e32 v102, v42, v42
	v_fmac_f32_e32 v102, v43, v43
	v_fmac_f32_e32 v102, v44, v44
	v_fmac_f32_e32 v102, v45, v45
	v_fmac_f32_e32 v102, v46, v46
	v_fmac_f32_e32 v102, v47, v47
	v_fmac_f32_e32 v102, v48, v48
	v_fmac_f32_e32 v102, v49, v49
	v_fmac_f32_e32 v102, v50, v50
	v_fmac_f32_e32 v102, v51, v51
	s_nop 1
	v_add_f32_dpp v102, v102, v102 row_shr:1 row_mask:0xf bank_mask:0xf bound_ctrl:1
	s_nop 1
	v_add_f32_dpp v102, v102, v102 row_shr:2 row_mask:0xf bank_mask:0xf bound_ctrl:1
	s_nop 1
	v_add_f32_dpp v102, v102, v102 row_shr:4 row_mask:0xf bank_mask:0xf bound_ctrl:1
	s_nop 1
	v_add_f32_dpp v102, v102, v102 row_shr:8 row_mask:0xf bank_mask:0xf bound_ctrl:1
	s_nop 1
	v_add_f32_dpp v102, v102, v102 row_bcast:15 row_mask:0xa bank_mask:0xf
	s_nop 1
	v_add_f32_dpp v102, v102, v102 row_bcast:31 row_mask:0xc bank_mask:0xf
	s_nop 0
	v_readlane_b32 s53, v102, 63
	s_nop 1
	v_mov_b32_e32 v101, s53
	v_fmamk_f32 v101, v101, 0x3aaaaaab, v197
	v_rsq_f32_e32 v103, v101
	s_nop 0
	v_mul_f32_e32 v40, v40, v103
	v_mul_f32_e32 v41, v41, v103
	v_mul_f32_e32 v42, v42, v103
	v_mul_f32_e32 v43, v43, v103
	v_mul_f32_e32 v44, v44, v103
	v_mul_f32_e32 v45, v45, v103
	v_mul_f32_e32 v46, v46, v103
	v_mul_f32_e32 v47, v47, v103
	v_mul_f32_e32 v48, v48, v103
	v_mul_f32_e32 v49, v49, v103
	v_mul_f32_e32 v50, v50, v103
	v_mul_f32_e32 v51, v51, v103
	v_fma_f32 v40, v222, v40, v234
	v_fma_f32 v41, v223, v41, v235
	v_fma_f32 v42, v224, v42, v236
	v_fma_f32 v43, v225, v43, v237
	v_fma_f32 v44, v226, v44, v238
	v_fma_f32 v45, v227, v45, v239
	v_fma_f32 v46, v228, v46, v240
	v_fma_f32 v47, v229, v47, v241
	v_fma_f32 v48, v230, v48, v242
	v_fma_f32 v49, v231, v49, v243
	v_fma_f32 v50, v232, v50, v244
	v_fma_f32 v51, v233, v51, v245
	s_lshl_b32 s52, s41, 11
	s_add_i32 s52, s52, 6144
	v_add_u32_e32 v196, s52, v3
	v_mul_f32_e32 v108, 0xbfb8aa3b, v40
	v_exp_f32_e32 v109, v108
	s_nop 0
	v_add_f32_e32 v110, 1.0, v109
	v_div_scale_f32 v111, s[54:55], v110, v110, 1.0
	v_rcp_f32_e32 v112, v111
	v_div_scale_f32 v113, vcc, 1.0, v110, 1.0
	v_fma_f32 v115, -v111, v112, 1.0
	v_fmac_f32_e32 v112, v115, v112
	v_mul_f32_e32 v114, v113, v112
	v_fma_f32 v115, -v111, v114, v113
	v_fmac_f32_e32 v114, v115, v112
	v_fma_f32 v115, -v111, v114, v113
	v_div_fmas_f32 v115, v115, v112, v114
	v_div_fixup_f32 v115, v115, v110, 1.0
	v_mul_f32_e32 v120, v40, v115
	v_mul_f32_e32 v108, 0xbfb8aa3b, v41
	v_exp_f32_e32 v109, v108
	s_nop 0
	v_add_f32_e32 v110, 1.0, v109
	v_div_scale_f32 v111, s[54:55], v110, v110, 1.0
	v_rcp_f32_e32 v112, v111
	v_div_scale_f32 v113, vcc, 1.0, v110, 1.0
	v_fma_f32 v115, -v111, v112, 1.0
	v_fmac_f32_e32 v112, v115, v112
	v_mul_f32_e32 v114, v113, v112
	v_fma_f32 v115, -v111, v114, v113
	v_fmac_f32_e32 v114, v115, v112
	v_fma_f32 v115, -v111, v114, v113
	v_div_fmas_f32 v115, v115, v112, v114
	v_div_fixup_f32 v115, v115, v110, 1.0
	v_mul_f32_e32 v121, v41, v115
	v_mul_f32_e32 v108, 0xbfb8aa3b, v42
	v_exp_f32_e32 v109, v108
	s_nop 0
	v_add_f32_e32 v110, 1.0, v109
	v_div_scale_f32 v111, s[54:55], v110, v110, 1.0
	v_rcp_f32_e32 v112, v111
	v_div_scale_f32 v113, vcc, 1.0, v110, 1.0
	v_fma_f32 v115, -v111, v112, 1.0
	v_fmac_f32_e32 v112, v115, v112
	v_mul_f32_e32 v114, v113, v112
	v_fma_f32 v115, -v111, v114, v113
	v_fmac_f32_e32 v114, v115, v112
	v_fma_f32 v115, -v111, v114, v113
	v_div_fmas_f32 v115, v115, v112, v114
	v_div_fixup_f32 v115, v115, v110, 1.0
	v_mul_f32_e32 v122, v42, v115
	v_mul_f32_e32 v108, 0xbfb8aa3b, v43
	v_exp_f32_e32 v109, v108
	s_nop 0
	v_add_f32_e32 v110, 1.0, v109
	v_div_scale_f32 v111, s[54:55], v110, v110, 1.0
	v_rcp_f32_e32 v112, v111
	v_div_scale_f32 v113, vcc, 1.0, v110, 1.0
	v_fma_f32 v115, -v111, v112, 1.0
	v_fmac_f32_e32 v112, v115, v112
	v_mul_f32_e32 v114, v113, v112
	v_fma_f32 v115, -v111, v114, v113
	v_fmac_f32_e32 v114, v115, v112
	v_fma_f32 v115, -v111, v114, v113
	v_div_fmas_f32 v115, v115, v112, v114
	v_div_fixup_f32 v115, v115, v110, 1.0
	v_mul_f32_e32 v123, v43, v115
	v_cvt_pk_bf16_f32 v124, v120, v121
	v_cvt_pk_bf16_f32 v125, v122, v123
	global_store_dwordx2 v196, v[124:125], s[44:45]
	v_mul_f32_e32 v108, 0xbfb8aa3b, v44
	v_exp_f32_e32 v109, v108
	s_nop 0
	v_add_f32_e32 v110, 1.0, v109
	v_div_scale_f32 v111, s[54:55], v110, v110, 1.0
	v_rcp_f32_e32 v112, v111
	v_div_scale_f32 v113, vcc, 1.0, v110, 1.0
	v_fma_f32 v115, -v111, v112, 1.0
	v_fmac_f32_e32 v112, v115, v112
	v_mul_f32_e32 v114, v113, v112
	v_fma_f32 v115, -v111, v114, v113
	v_fmac_f32_e32 v114, v115, v112
	v_fma_f32 v115, -v111, v114, v113
	v_div_fmas_f32 v115, v115, v112, v114
	v_div_fixup_f32 v115, v115, v110, 1.0
	v_mul_f32_e32 v120, v44, v115
	v_mul_f32_e32 v108, 0xbfb8aa3b, v45
	v_exp_f32_e32 v109, v108
	s_nop 0
	v_add_f32_e32 v110, 1.0, v109
	v_div_scale_f32 v111, s[54:55], v110, v110, 1.0
	v_rcp_f32_e32 v112, v111
	v_div_scale_f32 v113, vcc, 1.0, v110, 1.0
	v_fma_f32 v115, -v111, v112, 1.0
	v_fmac_f32_e32 v112, v115, v112
	v_mul_f32_e32 v114, v113, v112
	v_fma_f32 v115, -v111, v114, v113
	v_fmac_f32_e32 v114, v115, v112
	v_fma_f32 v115, -v111, v114, v113
	v_div_fmas_f32 v115, v115, v112, v114
	v_div_fixup_f32 v115, v115, v110, 1.0
	v_mul_f32_e32 v121, v45, v115
	v_mul_f32_e32 v108, 0xbfb8aa3b, v46
	v_exp_f32_e32 v109, v108
	s_nop 0
	v_add_f32_e32 v110, 1.0, v109
	v_div_scale_f32 v111, s[54:55], v110, v110, 1.0
	v_rcp_f32_e32 v112, v111
	v_div_scale_f32 v113, vcc, 1.0, v110, 1.0
	v_fma_f32 v115, -v111, v112, 1.0
	v_fmac_f32_e32 v112, v115, v112
	v_mul_f32_e32 v114, v113, v112
	v_fma_f32 v115, -v111, v114, v113
	v_fmac_f32_e32 v114, v115, v112
	v_fma_f32 v115, -v111, v114, v113
	v_div_fmas_f32 v115, v115, v112, v114
	v_div_fixup_f32 v115, v115, v110, 1.0
	v_mul_f32_e32 v122, v46, v115
	v_mul_f32_e32 v108, 0xbfb8aa3b, v47
	v_exp_f32_e32 v109, v108
	s_nop 0
	v_add_f32_e32 v110, 1.0, v109
	v_div_scale_f32 v111, s[54:55], v110, v110, 1.0
	v_rcp_f32_e32 v112, v111
	v_div_scale_f32 v113, vcc, 1.0, v110, 1.0
	v_fma_f32 v115, -v111, v112, 1.0
	v_fmac_f32_e32 v112, v115, v112
	v_mul_f32_e32 v114, v113, v112
	v_fma_f32 v115, -v111, v114, v113
	v_fmac_f32_e32 v114, v115, v112
	v_fma_f32 v115, -v111, v114, v113
	v_div_fmas_f32 v115, v115, v112, v114
	v_div_fixup_f32 v115, v115, v110, 1.0
	v_mul_f32_e32 v123, v47, v115
	v_cvt_pk_bf16_f32 v124, v120, v121
	v_cvt_pk_bf16_f32 v125, v122, v123
	global_store_dwordx2 v196, v[124:125], s[44:45] offset:512
	v_mul_f32_e32 v108, 0xbfb8aa3b, v48
	v_exp_f32_e32 v109, v108
	s_nop 0
	v_add_f32_e32 v110, 1.0, v109
	v_div_scale_f32 v111, s[54:55], v110, v110, 1.0
	v_rcp_f32_e32 v112, v111
	v_div_scale_f32 v113, vcc, 1.0, v110, 1.0
	v_fma_f32 v115, -v111, v112, 1.0
	v_fmac_f32_e32 v112, v115, v112
	v_mul_f32_e32 v114, v113, v112
	v_fma_f32 v115, -v111, v114, v113
	v_fmac_f32_e32 v114, v115, v112
	v_fma_f32 v115, -v111, v114, v113
	v_div_fmas_f32 v115, v115, v112, v114
	v_div_fixup_f32 v115, v115, v110, 1.0
	v_mul_f32_e32 v120, v48, v115
	v_mul_f32_e32 v108, 0xbfb8aa3b, v49
	v_exp_f32_e32 v109, v108
	s_nop 0
	v_add_f32_e32 v110, 1.0, v109
	v_div_scale_f32 v111, s[54:55], v110, v110, 1.0
	v_rcp_f32_e32 v112, v111
	v_div_scale_f32 v113, vcc, 1.0, v110, 1.0
	v_fma_f32 v115, -v111, v112, 1.0
	v_fmac_f32_e32 v112, v115, v112
	v_mul_f32_e32 v114, v113, v112
	v_fma_f32 v115, -v111, v114, v113
	v_fmac_f32_e32 v114, v115, v112
	v_fma_f32 v115, -v111, v114, v113
	v_div_fmas_f32 v115, v115, v112, v114
	v_div_fixup_f32 v115, v115, v110, 1.0
	v_mul_f32_e32 v121, v49, v115
	v_mul_f32_e32 v108, 0xbfb8aa3b, v50
	v_exp_f32_e32 v109, v108
	s_nop 0
	v_add_f32_e32 v110, 1.0, v109
	v_div_scale_f32 v111, s[54:55], v110, v110, 1.0
	v_rcp_f32_e32 v112, v111
	v_div_scale_f32 v113, vcc, 1.0, v110, 1.0
	v_fma_f32 v115, -v111, v112, 1.0
	v_fmac_f32_e32 v112, v115, v112
	v_mul_f32_e32 v114, v113, v112
	v_fma_f32 v115, -v111, v114, v113
	v_fmac_f32_e32 v114, v115, v112
	v_fma_f32 v115, -v111, v114, v113
	v_div_fmas_f32 v115, v115, v112, v114
	v_div_fixup_f32 v115, v115, v110, 1.0
	v_mul_f32_e32 v122, v50, v115
	v_mul_f32_e32 v108, 0xbfb8aa3b, v51
	v_exp_f32_e32 v109, v108
	s_nop 0
	v_add_f32_e32 v110, 1.0, v109
	v_div_scale_f32 v111, s[54:55], v110, v110, 1.0
	v_rcp_f32_e32 v112, v111
	v_div_scale_f32 v113, vcc, 1.0, v110, 1.0
	v_fma_f32 v115, -v111, v112, 1.0
	v_fmac_f32_e32 v112, v115, v112
	v_mul_f32_e32 v114, v113, v112
	v_fma_f32 v115, -v111, v114, v113
	v_fmac_f32_e32 v114, v115, v112
	v_fma_f32 v115, -v111, v114, v113
	v_div_fmas_f32 v115, v115, v112, v114
	v_div_fixup_f32 v115, v115, v110, 1.0
	v_mul_f32_e32 v123, v51, v115
	v_cvt_pk_bf16_f32 v124, v120, v121
	v_cvt_pk_bf16_f32 v125, v122, v123
	global_store_dwordx2 v196, v[124:125], s[44:45] offset:1024
	v_add_f32_e32 v100, v52, v53
	v_add_f32_e32 v100, v100, v54
	v_add_f32_e32 v100, v100, v55
	v_add_f32_e32 v100, v100, v56
	v_add_f32_e32 v100, v100, v57
	v_add_f32_e32 v100, v100, v58
	v_add_f32_e32 v100, v100, v59
	v_add_f32_e32 v100, v100, v60
	v_add_f32_e32 v100, v100, v61
	v_add_f32_e32 v100, v100, v62
	v_add_f32_e32 v100, v100, v63
	s_nop 1
	v_add_f32_dpp v100, v100, v100 row_shr:1 row_mask:0xf bank_mask:0xf bound_ctrl:1
	s_nop 1
	v_add_f32_dpp v100, v100, v100 row_shr:2 row_mask:0xf bank_mask:0xf bound_ctrl:1
	s_nop 1
	v_add_f32_dpp v100, v100, v100 row_shr:4 row_mask:0xf bank_mask:0xf bound_ctrl:1
	s_nop 1
	v_add_f32_dpp v100, v100, v100 row_shr:8 row_mask:0xf bank_mask:0xf bound_ctrl:1
	s_nop 1
	v_add_f32_dpp v100, v100, v100 row_bcast:15 row_mask:0xa bank_mask:0xf
	s_nop 1
	v_add_f32_dpp v100, v100, v100 row_bcast:31 row_mask:0xc bank_mask:0xf
	s_nop 0
	v_readlane_b32 s53, v100, 63
	s_nop 1
	v_mov_b32_e32 v101, s53
	v_fmac_f32_e32 v52, 0xbaaaaaab, v101
	v_fmac_f32_e32 v53, 0xbaaaaaab, v101
	v_fmac_f32_e32 v54, 0xbaaaaaab, v101
	v_fmac_f32_e32 v55, 0xbaaaaaab, v101
	v_fmac_f32_e32 v56, 0xbaaaaaab, v101
	v_fmac_f32_e32 v57, 0xbaaaaaab, v101
	v_fmac_f32_e32 v58, 0xbaaaaaab, v101
	v_fmac_f32_e32 v59, 0xbaaaaaab, v101
	v_fmac_f32_e32 v60, 0xbaaaaaab, v101
	v_fmac_f32_e32 v61, 0xbaaaaaab, v101
	v_fmac_f32_e32 v62, 0xbaaaaaab, v101
	v_fmac_f32_e32 v63, 0xbaaaaaab, v101
	v_mul_f32_e32 v102, v52, v52
	v_fmac_f32_e32 v102, v53, v53
	v_fmac_f32_e32 v102, v54, v54
	v_fmac_f32_e32 v102, v55, v55
	v_fmac_f32_e32 v102, v56, v56
	v_fmac_f32_e32 v102, v57, v57
	v_fmac_f32_e32 v102, v58, v58
	v_fmac_f32_e32 v102, v59, v59
	v_fmac_f32_e32 v102, v60, v60
	v_fmac_f32_e32 v102, v61, v61
	v_fmac_f32_e32 v102, v62, v62
	v_fmac_f32_e32 v102, v63, v63
	s_nop 1
	v_add_f32_dpp v102, v102, v102 row_shr:1 row_mask:0xf bank_mask:0xf bound_ctrl:1
	s_nop 1
	v_add_f32_dpp v102, v102, v102 row_shr:2 row_mask:0xf bank_mask:0xf bound_ctrl:1
	s_nop 1
	v_add_f32_dpp v102, v102, v102 row_shr:4 row_mask:0xf bank_mask:0xf bound_ctrl:1
	s_nop 1
	v_add_f32_dpp v102, v102, v102 row_shr:8 row_mask:0xf bank_mask:0xf bound_ctrl:1
	s_nop 1
	v_add_f32_dpp v102, v102, v102 row_bcast:15 row_mask:0xa bank_mask:0xf
	s_nop 1
	v_add_f32_dpp v102, v102, v102 row_bcast:31 row_mask:0xc bank_mask:0xf
	s_nop 0
	v_readlane_b32 s53, v102, 63
	s_nop 1
	v_mov_b32_e32 v101, s53
	v_fmamk_f32 v101, v101, 0x3aaaaaab, v197
	v_rsq_f32_e32 v103, v101
	s_nop 0
	v_mul_f32_e32 v52, v52, v103
	v_mul_f32_e32 v53, v53, v103
	v_mul_f32_e32 v54, v54, v103
	v_mul_f32_e32 v55, v55, v103
	v_mul_f32_e32 v56, v56, v103
	v_mul_f32_e32 v57, v57, v103
	v_mul_f32_e32 v58, v58, v103
	v_mul_f32_e32 v59, v59, v103
	v_mul_f32_e32 v60, v60, v103
	v_mul_f32_e32 v61, v61, v103
	v_mul_f32_e32 v62, v62, v103
	v_mul_f32_e32 v63, v63, v103
	v_fma_f32 v52, v222, v52, v234
	v_fma_f32 v53, v223, v53, v235
	v_fma_f32 v54, v224, v54, v236
	v_fma_f32 v55, v225, v55, v237
	v_fma_f32 v56, v226, v56, v238
	v_fma_f32 v57, v227, v57, v239
	v_fma_f32 v58, v228, v58, v240
	v_fma_f32 v59, v229, v59, v241
	v_fma_f32 v60, v230, v60, v242
	v_fma_f32 v61, v231, v61, v243
	v_fma_f32 v62, v232, v62, v244
	v_fma_f32 v63, v233, v63, v245
	s_lshl_b32 s52, s41, 11
	s_add_i32 s52, s52, 8192
	v_add_u32_e32 v196, s52, v3
	v_mul_f32_e32 v108, 0xbfb8aa3b, v52
	v_exp_f32_e32 v109, v108
	s_nop 0
	v_add_f32_e32 v110, 1.0, v109
	v_div_scale_f32 v111, s[54:55], v110, v110, 1.0
	v_rcp_f32_e32 v112, v111
	v_div_scale_f32 v113, vcc, 1.0, v110, 1.0
	v_fma_f32 v115, -v111, v112, 1.0
	v_fmac_f32_e32 v112, v115, v112
	v_mul_f32_e32 v114, v113, v112
	v_fma_f32 v115, -v111, v114, v113
	v_fmac_f32_e32 v114, v115, v112
	v_fma_f32 v115, -v111, v114, v113
	v_div_fmas_f32 v115, v115, v112, v114
	v_div_fixup_f32 v115, v115, v110, 1.0
	v_mul_f32_e32 v120, v52, v115
	v_mul_f32_e32 v108, 0xbfb8aa3b, v53
	v_exp_f32_e32 v109, v108
	s_nop 0
	v_add_f32_e32 v110, 1.0, v109
	v_div_scale_f32 v111, s[54:55], v110, v110, 1.0
	v_rcp_f32_e32 v112, v111
	v_div_scale_f32 v113, vcc, 1.0, v110, 1.0
	v_fma_f32 v115, -v111, v112, 1.0
	v_fmac_f32_e32 v112, v115, v112
	v_mul_f32_e32 v114, v113, v112
	v_fma_f32 v115, -v111, v114, v113
	v_fmac_f32_e32 v114, v115, v112
	v_fma_f32 v115, -v111, v114, v113
	v_div_fmas_f32 v115, v115, v112, v114
	v_div_fixup_f32 v115, v115, v110, 1.0
	v_mul_f32_e32 v121, v53, v115
	v_mul_f32_e32 v108, 0xbfb8aa3b, v54
	v_exp_f32_e32 v109, v108
	s_nop 0
	v_add_f32_e32 v110, 1.0, v109
	v_div_scale_f32 v111, s[54:55], v110, v110, 1.0
	v_rcp_f32_e32 v112, v111
	v_div_scale_f32 v113, vcc, 1.0, v110, 1.0
	v_fma_f32 v115, -v111, v112, 1.0
	v_fmac_f32_e32 v112, v115, v112
	v_mul_f32_e32 v114, v113, v112
	v_fma_f32 v115, -v111, v114, v113
	v_fmac_f32_e32 v114, v115, v112
	v_fma_f32 v115, -v111, v114, v113
	v_div_fmas_f32 v115, v115, v112, v114
	v_div_fixup_f32 v115, v115, v110, 1.0
	v_mul_f32_e32 v122, v54, v115
	v_mul_f32_e32 v108, 0xbfb8aa3b, v55
	v_exp_f32_e32 v109, v108
	s_nop 0
	v_add_f32_e32 v110, 1.0, v109
	v_div_scale_f32 v111, s[54:55], v110, v110, 1.0
	v_rcp_f32_e32 v112, v111
	v_div_scale_f32 v113, vcc, 1.0, v110, 1.0
	v_fma_f32 v115, -v111, v112, 1.0
	v_fmac_f32_e32 v112, v115, v112
	v_mul_f32_e32 v114, v113, v112
	v_fma_f32 v115, -v111, v114, v113
	v_fmac_f32_e32 v114, v115, v112
	v_fma_f32 v115, -v111, v114, v113
	v_div_fmas_f32 v115, v115, v112, v114
	v_div_fixup_f32 v115, v115, v110, 1.0
	v_mul_f32_e32 v123, v55, v115
	v_cvt_pk_bf16_f32 v124, v120, v121
	v_cvt_pk_bf16_f32 v125, v122, v123
	global_store_dwordx2 v196, v[124:125], s[44:45]
	v_mul_f32_e32 v108, 0xbfb8aa3b, v56
	v_exp_f32_e32 v109, v108
	s_nop 0
	v_add_f32_e32 v110, 1.0, v109
	v_div_scale_f32 v111, s[54:55], v110, v110, 1.0
	v_rcp_f32_e32 v112, v111
	v_div_scale_f32 v113, vcc, 1.0, v110, 1.0
	v_fma_f32 v115, -v111, v112, 1.0
	v_fmac_f32_e32 v112, v115, v112
	v_mul_f32_e32 v114, v113, v112
	v_fma_f32 v115, -v111, v114, v113
	v_fmac_f32_e32 v114, v115, v112
	v_fma_f32 v115, -v111, v114, v113
	v_div_fmas_f32 v115, v115, v112, v114
	v_div_fixup_f32 v115, v115, v110, 1.0
	v_mul_f32_e32 v120, v56, v115
	v_mul_f32_e32 v108, 0xbfb8aa3b, v57
	v_exp_f32_e32 v109, v108
	s_nop 0
	v_add_f32_e32 v110, 1.0, v109
	v_div_scale_f32 v111, s[54:55], v110, v110, 1.0
	v_rcp_f32_e32 v112, v111
	v_div_scale_f32 v113, vcc, 1.0, v110, 1.0
	v_fma_f32 v115, -v111, v112, 1.0
	v_fmac_f32_e32 v112, v115, v112
	v_mul_f32_e32 v114, v113, v112
	v_fma_f32 v115, -v111, v114, v113
	v_fmac_f32_e32 v114, v115, v112
	v_fma_f32 v115, -v111, v114, v113
	v_div_fmas_f32 v115, v115, v112, v114
	v_div_fixup_f32 v115, v115, v110, 1.0
	v_mul_f32_e32 v121, v57, v115
	v_mul_f32_e32 v108, 0xbfb8aa3b, v58
	v_exp_f32_e32 v109, v108
	s_nop 0
	v_add_f32_e32 v110, 1.0, v109
	v_div_scale_f32 v111, s[54:55], v110, v110, 1.0
	v_rcp_f32_e32 v112, v111
	v_div_scale_f32 v113, vcc, 1.0, v110, 1.0
	v_fma_f32 v115, -v111, v112, 1.0
	v_fmac_f32_e32 v112, v115, v112
	v_mul_f32_e32 v114, v113, v112
	v_fma_f32 v115, -v111, v114, v113
	v_fmac_f32_e32 v114, v115, v112
	v_fma_f32 v115, -v111, v114, v113
	v_div_fmas_f32 v115, v115, v112, v114
	v_div_fixup_f32 v115, v115, v110, 1.0
	v_mul_f32_e32 v122, v58, v115
	v_mul_f32_e32 v108, 0xbfb8aa3b, v59
	v_exp_f32_e32 v109, v108
	s_nop 0
	v_add_f32_e32 v110, 1.0, v109
	v_div_scale_f32 v111, s[54:55], v110, v110, 1.0
	v_rcp_f32_e32 v112, v111
	v_div_scale_f32 v113, vcc, 1.0, v110, 1.0
	v_fma_f32 v115, -v111, v112, 1.0
	v_fmac_f32_e32 v112, v115, v112
	v_mul_f32_e32 v114, v113, v112
	v_fma_f32 v115, -v111, v114, v113
	v_fmac_f32_e32 v114, v115, v112
	v_fma_f32 v115, -v111, v114, v113
	v_div_fmas_f32 v115, v115, v112, v114
	v_div_fixup_f32 v115, v115, v110, 1.0
	v_mul_f32_e32 v123, v59, v115
	v_cvt_pk_bf16_f32 v124, v120, v121
	v_cvt_pk_bf16_f32 v125, v122, v123
	global_store_dwordx2 v196, v[124:125], s[44:45] offset:512
	v_mul_f32_e32 v108, 0xbfb8aa3b, v60
	v_exp_f32_e32 v109, v108
	s_nop 0
	v_add_f32_e32 v110, 1.0, v109
	v_div_scale_f32 v111, s[54:55], v110, v110, 1.0
	v_rcp_f32_e32 v112, v111
	v_div_scale_f32 v113, vcc, 1.0, v110, 1.0
	v_fma_f32 v115, -v111, v112, 1.0
	v_fmac_f32_e32 v112, v115, v112
	v_mul_f32_e32 v114, v113, v112
	v_fma_f32 v115, -v111, v114, v113
	v_fmac_f32_e32 v114, v115, v112
	v_fma_f32 v115, -v111, v114, v113
	v_div_fmas_f32 v115, v115, v112, v114
	v_div_fixup_f32 v115, v115, v110, 1.0
	v_mul_f32_e32 v120, v60, v115
	v_mul_f32_e32 v108, 0xbfb8aa3b, v61
	v_exp_f32_e32 v109, v108
	s_nop 0
	v_add_f32_e32 v110, 1.0, v109
	v_div_scale_f32 v111, s[54:55], v110, v110, 1.0
	v_rcp_f32_e32 v112, v111
	v_div_scale_f32 v113, vcc, 1.0, v110, 1.0
	v_fma_f32 v115, -v111, v112, 1.0
	v_fmac_f32_e32 v112, v115, v112
	v_mul_f32_e32 v114, v113, v112
	v_fma_f32 v115, -v111, v114, v113
	v_fmac_f32_e32 v114, v115, v112
	v_fma_f32 v115, -v111, v114, v113
	v_div_fmas_f32 v115, v115, v112, v114
	v_div_fixup_f32 v115, v115, v110, 1.0
	v_mul_f32_e32 v121, v61, v115
	v_mul_f32_e32 v108, 0xbfb8aa3b, v62
	v_exp_f32_e32 v109, v108
	s_nop 0
	v_add_f32_e32 v110, 1.0, v109
	v_div_scale_f32 v111, s[54:55], v110, v110, 1.0
	v_rcp_f32_e32 v112, v111
	v_div_scale_f32 v113, vcc, 1.0, v110, 1.0
	v_fma_f32 v115, -v111, v112, 1.0
	v_fmac_f32_e32 v112, v115, v112
	v_mul_f32_e32 v114, v113, v112
	v_fma_f32 v115, -v111, v114, v113
	v_fmac_f32_e32 v114, v115, v112
	v_fma_f32 v115, -v111, v114, v113
	v_div_fmas_f32 v115, v115, v112, v114
	v_div_fixup_f32 v115, v115, v110, 1.0
	v_mul_f32_e32 v122, v62, v115
	v_mul_f32_e32 v108, 0xbfb8aa3b, v63
	v_exp_f32_e32 v109, v108
	s_nop 0
	v_add_f32_e32 v110, 1.0, v109
	v_div_scale_f32 v111, s[54:55], v110, v110, 1.0
	v_rcp_f32_e32 v112, v111
	v_div_scale_f32 v113, vcc, 1.0, v110, 1.0
	v_fma_f32 v115, -v111, v112, 1.0
	v_fmac_f32_e32 v112, v115, v112
	v_mul_f32_e32 v114, v113, v112
	v_fma_f32 v115, -v111, v114, v113
	v_fmac_f32_e32 v114, v115, v112
	v_fma_f32 v115, -v111, v114, v113
	v_div_fmas_f32 v115, v115, v112, v114
	v_div_fixup_f32 v115, v115, v110, 1.0
	v_mul_f32_e32 v123, v63, v115
	v_cvt_pk_bf16_f32 v124, v120, v121
	v_cvt_pk_bf16_f32 v125, v122, v123
	global_store_dwordx2 v196, v[124:125], s[44:45] offset:1024
	v_add_f32_e32 v100, v64, v65
	v_add_f32_e32 v100, v100, v66
	v_add_f32_e32 v100, v100, v67
	v_add_f32_e32 v100, v100, v68
	v_add_f32_e32 v100, v100, v69
	v_add_f32_e32 v100, v100, v70
	v_add_f32_e32 v100, v100, v71
	v_add_f32_e32 v100, v100, v72
	v_add_f32_e32 v100, v100, v73
	v_add_f32_e32 v100, v100, v74
	v_add_f32_e32 v100, v100, v75
	s_nop 1
	v_add_f32_dpp v100, v100, v100 row_shr:1 row_mask:0xf bank_mask:0xf bound_ctrl:1
	s_nop 1
	v_add_f32_dpp v100, v100, v100 row_shr:2 row_mask:0xf bank_mask:0xf bound_ctrl:1
	s_nop 1
	v_add_f32_dpp v100, v100, v100 row_shr:4 row_mask:0xf bank_mask:0xf bound_ctrl:1
	s_nop 1
	v_add_f32_dpp v100, v100, v100 row_shr:8 row_mask:0xf bank_mask:0xf bound_ctrl:1
	s_nop 1
	v_add_f32_dpp v100, v100, v100 row_bcast:15 row_mask:0xa bank_mask:0xf
	s_nop 1
	v_add_f32_dpp v100, v100, v100 row_bcast:31 row_mask:0xc bank_mask:0xf
	s_nop 0
	v_readlane_b32 s53, v100, 63
	s_nop 1
	v_mov_b32_e32 v101, s53
	v_fmac_f32_e32 v64, 0xbaaaaaab, v101
	v_fmac_f32_e32 v65, 0xbaaaaaab, v101
	v_fmac_f32_e32 v66, 0xbaaaaaab, v101
	v_fmac_f32_e32 v67, 0xbaaaaaab, v101
	v_fmac_f32_e32 v68, 0xbaaaaaab, v101
	v_fmac_f32_e32 v69, 0xbaaaaaab, v101
	v_fmac_f32_e32 v70, 0xbaaaaaab, v101
	v_fmac_f32_e32 v71, 0xbaaaaaab, v101
	v_fmac_f32_e32 v72, 0xbaaaaaab, v101
	v_fmac_f32_e32 v73, 0xbaaaaaab, v101
	v_fmac_f32_e32 v74, 0xbaaaaaab, v101
	v_fmac_f32_e32 v75, 0xbaaaaaab, v101
	v_mul_f32_e32 v102, v64, v64
	v_fmac_f32_e32 v102, v65, v65
	v_fmac_f32_e32 v102, v66, v66
	v_fmac_f32_e32 v102, v67, v67
	v_fmac_f32_e32 v102, v68, v68
	v_fmac_f32_e32 v102, v69, v69
	v_fmac_f32_e32 v102, v70, v70
	v_fmac_f32_e32 v102, v71, v71
	v_fmac_f32_e32 v102, v72, v72
	v_fmac_f32_e32 v102, v73, v73
	v_fmac_f32_e32 v102, v74, v74
	v_fmac_f32_e32 v102, v75, v75
	s_nop 1
	v_add_f32_dpp v102, v102, v102 row_shr:1 row_mask:0xf bank_mask:0xf bound_ctrl:1
	s_nop 1
	v_add_f32_dpp v102, v102, v102 row_shr:2 row_mask:0xf bank_mask:0xf bound_ctrl:1
	s_nop 1
	v_add_f32_dpp v102, v102, v102 row_shr:4 row_mask:0xf bank_mask:0xf bound_ctrl:1
	s_nop 1
	v_add_f32_dpp v102, v102, v102 row_shr:8 row_mask:0xf bank_mask:0xf bound_ctrl:1
	s_nop 1
	v_add_f32_dpp v102, v102, v102 row_bcast:15 row_mask:0xa bank_mask:0xf
	s_nop 1
	v_add_f32_dpp v102, v102, v102 row_bcast:31 row_mask:0xc bank_mask:0xf
	s_nop 0
	v_readlane_b32 s53, v102, 63
	s_nop 1
	v_mov_b32_e32 v101, s53
	v_fmamk_f32 v101, v101, 0x3aaaaaab, v197
	v_rsq_f32_e32 v103, v101
	s_nop 0
	v_mul_f32_e32 v64, v64, v103
	v_mul_f32_e32 v65, v65, v103
	v_mul_f32_e32 v66, v66, v103
	v_mul_f32_e32 v67, v67, v103
	v_mul_f32_e32 v68, v68, v103
	v_mul_f32_e32 v69, v69, v103
	v_mul_f32_e32 v70, v70, v103
	v_mul_f32_e32 v71, v71, v103
	v_mul_f32_e32 v72, v72, v103
	v_mul_f32_e32 v73, v73, v103
	v_mul_f32_e32 v74, v74, v103
	v_mul_f32_e32 v75, v75, v103
	v_fma_f32 v64, v222, v64, v234
	v_fma_f32 v65, v223, v65, v235
	v_fma_f32 v66, v224, v66, v236
	v_fma_f32 v67, v225, v67, v237
	v_fma_f32 v68, v226, v68, v238
	v_fma_f32 v69, v227, v69, v239
	v_fma_f32 v70, v228, v70, v240
	v_fma_f32 v71, v229, v71, v241
	v_fma_f32 v72, v230, v72, v242
	v_fma_f32 v73, v231, v73, v243
	v_fma_f32 v74, v232, v74, v244
	v_fma_f32 v75, v233, v75, v245
	s_lshl_b32 s52, s41, 11
	s_add_i32 s52, s52, 10240
	v_add_u32_e32 v196, s52, v3
	v_mul_f32_e32 v108, 0xbfb8aa3b, v64
	v_exp_f32_e32 v109, v108
	s_nop 0
	v_add_f32_e32 v110, 1.0, v109
	v_div_scale_f32 v111, s[54:55], v110, v110, 1.0
	v_rcp_f32_e32 v112, v111
	v_div_scale_f32 v113, vcc, 1.0, v110, 1.0
	v_fma_f32 v115, -v111, v112, 1.0
	v_fmac_f32_e32 v112, v115, v112
	v_mul_f32_e32 v114, v113, v112
	v_fma_f32 v115, -v111, v114, v113
	v_fmac_f32_e32 v114, v115, v112
	v_fma_f32 v115, -v111, v114, v113
	v_div_fmas_f32 v115, v115, v112, v114
	v_div_fixup_f32 v115, v115, v110, 1.0
	v_mul_f32_e32 v120, v64, v115
	v_mul_f32_e32 v108, 0xbfb8aa3b, v65
	v_exp_f32_e32 v109, v108
	s_nop 0
	v_add_f32_e32 v110, 1.0, v109
	v_div_scale_f32 v111, s[54:55], v110, v110, 1.0
	v_rcp_f32_e32 v112, v111
	v_div_scale_f32 v113, vcc, 1.0, v110, 1.0
	v_fma_f32 v115, -v111, v112, 1.0
	v_fmac_f32_e32 v112, v115, v112
	v_mul_f32_e32 v114, v113, v112
	v_fma_f32 v115, -v111, v114, v113
	v_fmac_f32_e32 v114, v115, v112
	v_fma_f32 v115, -v111, v114, v113
	v_div_fmas_f32 v115, v115, v112, v114
	v_div_fixup_f32 v115, v115, v110, 1.0
	v_mul_f32_e32 v121, v65, v115
	v_mul_f32_e32 v108, 0xbfb8aa3b, v66
	v_exp_f32_e32 v109, v108
	s_nop 0
	v_add_f32_e32 v110, 1.0, v109
	v_div_scale_f32 v111, s[54:55], v110, v110, 1.0
	v_rcp_f32_e32 v112, v111
	v_div_scale_f32 v113, vcc, 1.0, v110, 1.0
	v_fma_f32 v115, -v111, v112, 1.0
	v_fmac_f32_e32 v112, v115, v112
	v_mul_f32_e32 v114, v113, v112
	v_fma_f32 v115, -v111, v114, v113
	v_fmac_f32_e32 v114, v115, v112
	v_fma_f32 v115, -v111, v114, v113
	v_div_fmas_f32 v115, v115, v112, v114
	v_div_fixup_f32 v115, v115, v110, 1.0
	v_mul_f32_e32 v122, v66, v115
	v_mul_f32_e32 v108, 0xbfb8aa3b, v67
	v_exp_f32_e32 v109, v108
	s_nop 0
	v_add_f32_e32 v110, 1.0, v109
	v_div_scale_f32 v111, s[54:55], v110, v110, 1.0
	v_rcp_f32_e32 v112, v111
	v_div_scale_f32 v113, vcc, 1.0, v110, 1.0
	v_fma_f32 v115, -v111, v112, 1.0
	v_fmac_f32_e32 v112, v115, v112
	v_mul_f32_e32 v114, v113, v112
	v_fma_f32 v115, -v111, v114, v113
	v_fmac_f32_e32 v114, v115, v112
	v_fma_f32 v115, -v111, v114, v113
	v_div_fmas_f32 v115, v115, v112, v114
	v_div_fixup_f32 v115, v115, v110, 1.0
	v_mul_f32_e32 v123, v67, v115
	v_cvt_pk_bf16_f32 v124, v120, v121
	v_cvt_pk_bf16_f32 v125, v122, v123
	global_store_dwordx2 v196, v[124:125], s[44:45]
	v_mul_f32_e32 v108, 0xbfb8aa3b, v68
	v_exp_f32_e32 v109, v108
	s_nop 0
	v_add_f32_e32 v110, 1.0, v109
	v_div_scale_f32 v111, s[54:55], v110, v110, 1.0
	v_rcp_f32_e32 v112, v111
	v_div_scale_f32 v113, vcc, 1.0, v110, 1.0
	v_fma_f32 v115, -v111, v112, 1.0
	v_fmac_f32_e32 v112, v115, v112
	v_mul_f32_e32 v114, v113, v112
	v_fma_f32 v115, -v111, v114, v113
	v_fmac_f32_e32 v114, v115, v112
	v_fma_f32 v115, -v111, v114, v113
	v_div_fmas_f32 v115, v115, v112, v114
	v_div_fixup_f32 v115, v115, v110, 1.0
	v_mul_f32_e32 v120, v68, v115
	v_mul_f32_e32 v108, 0xbfb8aa3b, v69
	v_exp_f32_e32 v109, v108
	s_nop 0
	v_add_f32_e32 v110, 1.0, v109
	v_div_scale_f32 v111, s[54:55], v110, v110, 1.0
	v_rcp_f32_e32 v112, v111
	v_div_scale_f32 v113, vcc, 1.0, v110, 1.0
	v_fma_f32 v115, -v111, v112, 1.0
	v_fmac_f32_e32 v112, v115, v112
	v_mul_f32_e32 v114, v113, v112
	v_fma_f32 v115, -v111, v114, v113
	v_fmac_f32_e32 v114, v115, v112
	v_fma_f32 v115, -v111, v114, v113
	v_div_fmas_f32 v115, v115, v112, v114
	v_div_fixup_f32 v115, v115, v110, 1.0
	v_mul_f32_e32 v121, v69, v115
	v_mul_f32_e32 v108, 0xbfb8aa3b, v70
	v_exp_f32_e32 v109, v108
	s_nop 0
	v_add_f32_e32 v110, 1.0, v109
	v_div_scale_f32 v111, s[54:55], v110, v110, 1.0
	v_rcp_f32_e32 v112, v111
	v_div_scale_f32 v113, vcc, 1.0, v110, 1.0
	v_fma_f32 v115, -v111, v112, 1.0
	v_fmac_f32_e32 v112, v115, v112
	v_mul_f32_e32 v114, v113, v112
	v_fma_f32 v115, -v111, v114, v113
	v_fmac_f32_e32 v114, v115, v112
	v_fma_f32 v115, -v111, v114, v113
	v_div_fmas_f32 v115, v115, v112, v114
	v_div_fixup_f32 v115, v115, v110, 1.0
	v_mul_f32_e32 v122, v70, v115
	v_mul_f32_e32 v108, 0xbfb8aa3b, v71
	v_exp_f32_e32 v109, v108
	s_nop 0
	v_add_f32_e32 v110, 1.0, v109
	v_div_scale_f32 v111, s[54:55], v110, v110, 1.0
	v_rcp_f32_e32 v112, v111
	v_div_scale_f32 v113, vcc, 1.0, v110, 1.0
	v_fma_f32 v115, -v111, v112, 1.0
	v_fmac_f32_e32 v112, v115, v112
	v_mul_f32_e32 v114, v113, v112
	v_fma_f32 v115, -v111, v114, v113
	v_fmac_f32_e32 v114, v115, v112
	v_fma_f32 v115, -v111, v114, v113
	v_div_fmas_f32 v115, v115, v112, v114
	v_div_fixup_f32 v115, v115, v110, 1.0
	v_mul_f32_e32 v123, v71, v115
	v_cvt_pk_bf16_f32 v124, v120, v121
	v_cvt_pk_bf16_f32 v125, v122, v123
	global_store_dwordx2 v196, v[124:125], s[44:45] offset:512
	v_mul_f32_e32 v108, 0xbfb8aa3b, v72
	v_exp_f32_e32 v109, v108
	s_nop 0
	v_add_f32_e32 v110, 1.0, v109
	v_div_scale_f32 v111, s[54:55], v110, v110, 1.0
	v_rcp_f32_e32 v112, v111
	v_div_scale_f32 v113, vcc, 1.0, v110, 1.0
	v_fma_f32 v115, -v111, v112, 1.0
	v_fmac_f32_e32 v112, v115, v112
	v_mul_f32_e32 v114, v113, v112
	v_fma_f32 v115, -v111, v114, v113
	v_fmac_f32_e32 v114, v115, v112
	v_fma_f32 v115, -v111, v114, v113
	v_div_fmas_f32 v115, v115, v112, v114
	v_div_fixup_f32 v115, v115, v110, 1.0
	v_mul_f32_e32 v120, v72, v115
	v_mul_f32_e32 v108, 0xbfb8aa3b, v73
	v_exp_f32_e32 v109, v108
	s_nop 0
	v_add_f32_e32 v110, 1.0, v109
	v_div_scale_f32 v111, s[54:55], v110, v110, 1.0
	v_rcp_f32_e32 v112, v111
	v_div_scale_f32 v113, vcc, 1.0, v110, 1.0
	v_fma_f32 v115, -v111, v112, 1.0
	v_fmac_f32_e32 v112, v115, v112
	v_mul_f32_e32 v114, v113, v112
	v_fma_f32 v115, -v111, v114, v113
	v_fmac_f32_e32 v114, v115, v112
	v_fma_f32 v115, -v111, v114, v113
	v_div_fmas_f32 v115, v115, v112, v114
	v_div_fixup_f32 v115, v115, v110, 1.0
	v_mul_f32_e32 v121, v73, v115
	v_mul_f32_e32 v108, 0xbfb8aa3b, v74
	v_exp_f32_e32 v109, v108
	s_nop 0
	v_add_f32_e32 v110, 1.0, v109
	v_div_scale_f32 v111, s[54:55], v110, v110, 1.0
	v_rcp_f32_e32 v112, v111
	v_div_scale_f32 v113, vcc, 1.0, v110, 1.0
	v_fma_f32 v115, -v111, v112, 1.0
	v_fmac_f32_e32 v112, v115, v112
	v_mul_f32_e32 v114, v113, v112
	v_fma_f32 v115, -v111, v114, v113
	v_fmac_f32_e32 v114, v115, v112
	v_fma_f32 v115, -v111, v114, v113
	v_div_fmas_f32 v115, v115, v112, v114
	v_div_fixup_f32 v115, v115, v110, 1.0
	v_mul_f32_e32 v122, v74, v115
	v_mul_f32_e32 v108, 0xbfb8aa3b, v75
	v_exp_f32_e32 v109, v108
	s_nop 0
	v_add_f32_e32 v110, 1.0, v109
	v_div_scale_f32 v111, s[54:55], v110, v110, 1.0
	v_rcp_f32_e32 v112, v111
	v_div_scale_f32 v113, vcc, 1.0, v110, 1.0
	v_fma_f32 v115, -v111, v112, 1.0
	v_fmac_f32_e32 v112, v115, v112
	v_mul_f32_e32 v114, v113, v112
	v_fma_f32 v115, -v111, v114, v113
	v_fmac_f32_e32 v114, v115, v112
	v_fma_f32 v115, -v111, v114, v113
	v_div_fmas_f32 v115, v115, v112, v114
	v_div_fixup_f32 v115, v115, v110, 1.0
	v_mul_f32_e32 v123, v75, v115
	v_cvt_pk_bf16_f32 v124, v120, v121
	v_cvt_pk_bf16_f32 v125, v122, v123
	global_store_dwordx2 v196, v[124:125], s[44:45] offset:1024
	v_add_f32_e32 v100, v76, v77
	v_add_f32_e32 v100, v100, v78
	v_add_f32_e32 v100, v100, v79
	v_add_f32_e32 v100, v100, v80
	v_add_f32_e32 v100, v100, v81
	v_add_f32_e32 v100, v100, v82
	v_add_f32_e32 v100, v100, v83
	v_add_f32_e32 v100, v100, v84
	v_add_f32_e32 v100, v100, v85
	v_add_f32_e32 v100, v100, v86
	v_add_f32_e32 v100, v100, v87
	s_nop 1
	v_add_f32_dpp v100, v100, v100 row_shr:1 row_mask:0xf bank_mask:0xf bound_ctrl:1
	s_nop 1
	v_add_f32_dpp v100, v100, v100 row_shr:2 row_mask:0xf bank_mask:0xf bound_ctrl:1
	s_nop 1
	v_add_f32_dpp v100, v100, v100 row_shr:4 row_mask:0xf bank_mask:0xf bound_ctrl:1
	s_nop 1
	v_add_f32_dpp v100, v100, v100 row_shr:8 row_mask:0xf bank_mask:0xf bound_ctrl:1
	s_nop 1
	v_add_f32_dpp v100, v100, v100 row_bcast:15 row_mask:0xa bank_mask:0xf
	s_nop 1
	v_add_f32_dpp v100, v100, v100 row_bcast:31 row_mask:0xc bank_mask:0xf
	s_nop 0
	v_readlane_b32 s53, v100, 63
	s_nop 1
	v_mov_b32_e32 v101, s53
	v_fmac_f32_e32 v76, 0xbaaaaaab, v101
	v_fmac_f32_e32 v77, 0xbaaaaaab, v101
	v_fmac_f32_e32 v78, 0xbaaaaaab, v101
	v_fmac_f32_e32 v79, 0xbaaaaaab, v101
	v_fmac_f32_e32 v80, 0xbaaaaaab, v101
	v_fmac_f32_e32 v81, 0xbaaaaaab, v101
	v_fmac_f32_e32 v82, 0xbaaaaaab, v101
	v_fmac_f32_e32 v83, 0xbaaaaaab, v101
	v_fmac_f32_e32 v84, 0xbaaaaaab, v101
	v_fmac_f32_e32 v85, 0xbaaaaaab, v101
	v_fmac_f32_e32 v86, 0xbaaaaaab, v101
	v_fmac_f32_e32 v87, 0xbaaaaaab, v101
	v_mul_f32_e32 v102, v76, v76
	v_fmac_f32_e32 v102, v77, v77
	v_fmac_f32_e32 v102, v78, v78
	v_fmac_f32_e32 v102, v79, v79
	v_fmac_f32_e32 v102, v80, v80
	v_fmac_f32_e32 v102, v81, v81
	v_fmac_f32_e32 v102, v82, v82
	v_fmac_f32_e32 v102, v83, v83
	v_fmac_f32_e32 v102, v84, v84
	v_fmac_f32_e32 v102, v85, v85
	v_fmac_f32_e32 v102, v86, v86
	v_fmac_f32_e32 v102, v87, v87
	s_nop 1
	v_add_f32_dpp v102, v102, v102 row_shr:1 row_mask:0xf bank_mask:0xf bound_ctrl:1
	s_nop 1
	v_add_f32_dpp v102, v102, v102 row_shr:2 row_mask:0xf bank_mask:0xf bound_ctrl:1
	s_nop 1
	v_add_f32_dpp v102, v102, v102 row_shr:4 row_mask:0xf bank_mask:0xf bound_ctrl:1
	s_nop 1
	v_add_f32_dpp v102, v102, v102 row_shr:8 row_mask:0xf bank_mask:0xf bound_ctrl:1
	s_nop 1
	v_add_f32_dpp v102, v102, v102 row_bcast:15 row_mask:0xa bank_mask:0xf
	s_nop 1
	v_add_f32_dpp v102, v102, v102 row_bcast:31 row_mask:0xc bank_mask:0xf
	s_nop 0
	v_readlane_b32 s53, v102, 63
	s_nop 1
	v_mov_b32_e32 v101, s53
	v_fmamk_f32 v101, v101, 0x3aaaaaab, v197
	v_rsq_f32_e32 v103, v101
	s_nop 0
	v_mul_f32_e32 v76, v76, v103
	v_mul_f32_e32 v77, v77, v103
	v_mul_f32_e32 v78, v78, v103
	v_mul_f32_e32 v79, v79, v103
	v_mul_f32_e32 v80, v80, v103
	v_mul_f32_e32 v81, v81, v103
	v_mul_f32_e32 v82, v82, v103
	v_mul_f32_e32 v83, v83, v103
	v_mul_f32_e32 v84, v84, v103
	v_mul_f32_e32 v85, v85, v103
	v_mul_f32_e32 v86, v86, v103
	v_mul_f32_e32 v87, v87, v103
	v_fma_f32 v76, v222, v76, v234
	v_fma_f32 v77, v223, v77, v235
	v_fma_f32 v78, v224, v78, v236
	v_fma_f32 v79, v225, v79, v237
	v_fma_f32 v80, v226, v80, v238
	v_fma_f32 v81, v227, v81, v239
	v_fma_f32 v82, v228, v82, v240
	v_fma_f32 v83, v229, v83, v241
	v_fma_f32 v84, v230, v84, v242
	v_fma_f32 v85, v231, v85, v243
	v_fma_f32 v86, v232, v86, v244
	v_fma_f32 v87, v233, v87, v245
	s_lshl_b32 s52, s41, 11
	s_add_i32 s52, s52, 12288
	v_add_u32_e32 v196, s52, v3
	v_mul_f32_e32 v108, 0xbfb8aa3b, v76
	v_exp_f32_e32 v109, v108
	s_nop 0
	v_add_f32_e32 v110, 1.0, v109
	v_div_scale_f32 v111, s[54:55], v110, v110, 1.0
	v_rcp_f32_e32 v112, v111
	v_div_scale_f32 v113, vcc, 1.0, v110, 1.0
	v_fma_f32 v115, -v111, v112, 1.0
	v_fmac_f32_e32 v112, v115, v112
	v_mul_f32_e32 v114, v113, v112
	v_fma_f32 v115, -v111, v114, v113
	v_fmac_f32_e32 v114, v115, v112
	v_fma_f32 v115, -v111, v114, v113
	v_div_fmas_f32 v115, v115, v112, v114
	v_div_fixup_f32 v115, v115, v110, 1.0
	v_mul_f32_e32 v120, v76, v115
	v_mul_f32_e32 v108, 0xbfb8aa3b, v77
	v_exp_f32_e32 v109, v108
	s_nop 0
	v_add_f32_e32 v110, 1.0, v109
	v_div_scale_f32 v111, s[54:55], v110, v110, 1.0
	v_rcp_f32_e32 v112, v111
	v_div_scale_f32 v113, vcc, 1.0, v110, 1.0
	v_fma_f32 v115, -v111, v112, 1.0
	v_fmac_f32_e32 v112, v115, v112
	v_mul_f32_e32 v114, v113, v112
	v_fma_f32 v115, -v111, v114, v113
	v_fmac_f32_e32 v114, v115, v112
	v_fma_f32 v115, -v111, v114, v113
	v_div_fmas_f32 v115, v115, v112, v114
	v_div_fixup_f32 v115, v115, v110, 1.0
	v_mul_f32_e32 v121, v77, v115
	v_mul_f32_e32 v108, 0xbfb8aa3b, v78
	v_exp_f32_e32 v109, v108
	s_nop 0
	v_add_f32_e32 v110, 1.0, v109
	v_div_scale_f32 v111, s[54:55], v110, v110, 1.0
	v_rcp_f32_e32 v112, v111
	v_div_scale_f32 v113, vcc, 1.0, v110, 1.0
	v_fma_f32 v115, -v111, v112, 1.0
	v_fmac_f32_e32 v112, v115, v112
	v_mul_f32_e32 v114, v113, v112
	v_fma_f32 v115, -v111, v114, v113
	v_fmac_f32_e32 v114, v115, v112
	v_fma_f32 v115, -v111, v114, v113
	v_div_fmas_f32 v115, v115, v112, v114
	v_div_fixup_f32 v115, v115, v110, 1.0
	v_mul_f32_e32 v122, v78, v115
	v_mul_f32_e32 v108, 0xbfb8aa3b, v79
	v_exp_f32_e32 v109, v108
	s_nop 0
	v_add_f32_e32 v110, 1.0, v109
	v_div_scale_f32 v111, s[54:55], v110, v110, 1.0
	v_rcp_f32_e32 v112, v111
	v_div_scale_f32 v113, vcc, 1.0, v110, 1.0
	v_fma_f32 v115, -v111, v112, 1.0
	v_fmac_f32_e32 v112, v115, v112
	v_mul_f32_e32 v114, v113, v112
	v_fma_f32 v115, -v111, v114, v113
	v_fmac_f32_e32 v114, v115, v112
	v_fma_f32 v115, -v111, v114, v113
	v_div_fmas_f32 v115, v115, v112, v114
	v_div_fixup_f32 v115, v115, v110, 1.0
	v_mul_f32_e32 v123, v79, v115
	v_cvt_pk_bf16_f32 v124, v120, v121
	v_cvt_pk_bf16_f32 v125, v122, v123
	global_store_dwordx2 v196, v[124:125], s[44:45]
	v_mul_f32_e32 v108, 0xbfb8aa3b, v80
	v_exp_f32_e32 v109, v108
	s_nop 0
	v_add_f32_e32 v110, 1.0, v109
	v_div_scale_f32 v111, s[54:55], v110, v110, 1.0
	v_rcp_f32_e32 v112, v111
	v_div_scale_f32 v113, vcc, 1.0, v110, 1.0
	v_fma_f32 v115, -v111, v112, 1.0
	v_fmac_f32_e32 v112, v115, v112
	v_mul_f32_e32 v114, v113, v112
	v_fma_f32 v115, -v111, v114, v113
	v_fmac_f32_e32 v114, v115, v112
	v_fma_f32 v115, -v111, v114, v113
	v_div_fmas_f32 v115, v115, v112, v114
	v_div_fixup_f32 v115, v115, v110, 1.0
	v_mul_f32_e32 v120, v80, v115
	v_mul_f32_e32 v108, 0xbfb8aa3b, v81
	v_exp_f32_e32 v109, v108
	s_nop 0
	v_add_f32_e32 v110, 1.0, v109
	v_div_scale_f32 v111, s[54:55], v110, v110, 1.0
	v_rcp_f32_e32 v112, v111
	v_div_scale_f32 v113, vcc, 1.0, v110, 1.0
	v_fma_f32 v115, -v111, v112, 1.0
	v_fmac_f32_e32 v112, v115, v112
	v_mul_f32_e32 v114, v113, v112
	v_fma_f32 v115, -v111, v114, v113
	v_fmac_f32_e32 v114, v115, v112
	v_fma_f32 v115, -v111, v114, v113
	v_div_fmas_f32 v115, v115, v112, v114
	v_div_fixup_f32 v115, v115, v110, 1.0
	v_mul_f32_e32 v121, v81, v115
	v_mul_f32_e32 v108, 0xbfb8aa3b, v82
	v_exp_f32_e32 v109, v108
	s_nop 0
	v_add_f32_e32 v110, 1.0, v109
	v_div_scale_f32 v111, s[54:55], v110, v110, 1.0
	v_rcp_f32_e32 v112, v111
	v_div_scale_f32 v113, vcc, 1.0, v110, 1.0
	v_fma_f32 v115, -v111, v112, 1.0
	v_fmac_f32_e32 v112, v115, v112
	v_mul_f32_e32 v114, v113, v112
	v_fma_f32 v115, -v111, v114, v113
	v_fmac_f32_e32 v114, v115, v112
	v_fma_f32 v115, -v111, v114, v113
	v_div_fmas_f32 v115, v115, v112, v114
	v_div_fixup_f32 v115, v115, v110, 1.0
	v_mul_f32_e32 v122, v82, v115
	v_mul_f32_e32 v108, 0xbfb8aa3b, v83
	v_exp_f32_e32 v109, v108
	s_nop 0
	v_add_f32_e32 v110, 1.0, v109
	v_div_scale_f32 v111, s[54:55], v110, v110, 1.0
	v_rcp_f32_e32 v112, v111
	v_div_scale_f32 v113, vcc, 1.0, v110, 1.0
	v_fma_f32 v115, -v111, v112, 1.0
	v_fmac_f32_e32 v112, v115, v112
	v_mul_f32_e32 v114, v113, v112
	v_fma_f32 v115, -v111, v114, v113
	v_fmac_f32_e32 v114, v115, v112
	v_fma_f32 v115, -v111, v114, v113
	v_div_fmas_f32 v115, v115, v112, v114
	v_div_fixup_f32 v115, v115, v110, 1.0
	v_mul_f32_e32 v123, v83, v115
	v_cvt_pk_bf16_f32 v124, v120, v121
	v_cvt_pk_bf16_f32 v125, v122, v123
	global_store_dwordx2 v196, v[124:125], s[44:45] offset:512
	v_mul_f32_e32 v108, 0xbfb8aa3b, v84
	v_exp_f32_e32 v109, v108
	s_nop 0
	v_add_f32_e32 v110, 1.0, v109
	v_div_scale_f32 v111, s[54:55], v110, v110, 1.0
	v_rcp_f32_e32 v112, v111
	v_div_scale_f32 v113, vcc, 1.0, v110, 1.0
	v_fma_f32 v115, -v111, v112, 1.0
	v_fmac_f32_e32 v112, v115, v112
	v_mul_f32_e32 v114, v113, v112
	v_fma_f32 v115, -v111, v114, v113
	v_fmac_f32_e32 v114, v115, v112
	v_fma_f32 v115, -v111, v114, v113
	v_div_fmas_f32 v115, v115, v112, v114
	v_div_fixup_f32 v115, v115, v110, 1.0
	v_mul_f32_e32 v120, v84, v115
	v_mul_f32_e32 v108, 0xbfb8aa3b, v85
	v_exp_f32_e32 v109, v108
	s_nop 0
	v_add_f32_e32 v110, 1.0, v109
	v_div_scale_f32 v111, s[54:55], v110, v110, 1.0
	v_rcp_f32_e32 v112, v111
	v_div_scale_f32 v113, vcc, 1.0, v110, 1.0
	v_fma_f32 v115, -v111, v112, 1.0
	v_fmac_f32_e32 v112, v115, v112
	v_mul_f32_e32 v114, v113, v112
	v_fma_f32 v115, -v111, v114, v113
	v_fmac_f32_e32 v114, v115, v112
	v_fma_f32 v115, -v111, v114, v113
	v_div_fmas_f32 v115, v115, v112, v114
	v_div_fixup_f32 v115, v115, v110, 1.0
	v_mul_f32_e32 v121, v85, v115
	v_mul_f32_e32 v108, 0xbfb8aa3b, v86
	v_exp_f32_e32 v109, v108
	s_nop 0
	v_add_f32_e32 v110, 1.0, v109
	v_div_scale_f32 v111, s[54:55], v110, v110, 1.0
	v_rcp_f32_e32 v112, v111
	v_div_scale_f32 v113, vcc, 1.0, v110, 1.0
	v_fma_f32 v115, -v111, v112, 1.0
	v_fmac_f32_e32 v112, v115, v112
	v_mul_f32_e32 v114, v113, v112
	v_fma_f32 v115, -v111, v114, v113
	v_fmac_f32_e32 v114, v115, v112
	v_fma_f32 v115, -v111, v114, v113
	v_div_fmas_f32 v115, v115, v112, v114
	v_div_fixup_f32 v115, v115, v110, 1.0
	v_mul_f32_e32 v122, v86, v115
	v_mul_f32_e32 v108, 0xbfb8aa3b, v87
	v_exp_f32_e32 v109, v108
	s_nop 0
	v_add_f32_e32 v110, 1.0, v109
	v_div_scale_f32 v111, s[54:55], v110, v110, 1.0
	v_rcp_f32_e32 v112, v111
	v_div_scale_f32 v113, vcc, 1.0, v110, 1.0
	v_fma_f32 v115, -v111, v112, 1.0
	v_fmac_f32_e32 v112, v115, v112
	v_mul_f32_e32 v114, v113, v112
	v_fma_f32 v115, -v111, v114, v113
	v_fmac_f32_e32 v114, v115, v112
	v_fma_f32 v115, -v111, v114, v113
	v_div_fmas_f32 v115, v115, v112, v114
	v_div_fixup_f32 v115, v115, v110, 1.0
	v_mul_f32_e32 v123, v87, v115
	v_cvt_pk_bf16_f32 v124, v120, v121
	v_cvt_pk_bf16_f32 v125, v122, v123
	global_store_dwordx2 v196, v[124:125], s[44:45] offset:1024
	v_add_f32_e32 v100, v88, v89
	v_add_f32_e32 v100, v100, v90
	v_add_f32_e32 v100, v100, v91
	v_add_f32_e32 v100, v100, v92
	v_add_f32_e32 v100, v100, v93
	v_add_f32_e32 v100, v100, v94
	v_add_f32_e32 v100, v100, v95
	v_add_f32_e32 v100, v100, v96
	v_add_f32_e32 v100, v100, v97
	v_add_f32_e32 v100, v100, v98
	v_add_f32_e32 v100, v100, v99
	s_nop 1
	v_add_f32_dpp v100, v100, v100 row_shr:1 row_mask:0xf bank_mask:0xf bound_ctrl:1
	s_nop 1
	v_add_f32_dpp v100, v100, v100 row_shr:2 row_mask:0xf bank_mask:0xf bound_ctrl:1
	s_nop 1
	v_add_f32_dpp v100, v100, v100 row_shr:4 row_mask:0xf bank_mask:0xf bound_ctrl:1
	s_nop 1
	v_add_f32_dpp v100, v100, v100 row_shr:8 row_mask:0xf bank_mask:0xf bound_ctrl:1
	s_nop 1
	v_add_f32_dpp v100, v100, v100 row_bcast:15 row_mask:0xa bank_mask:0xf
	s_nop 1
	v_add_f32_dpp v100, v100, v100 row_bcast:31 row_mask:0xc bank_mask:0xf
	s_nop 0
	v_readlane_b32 s53, v100, 63
	s_nop 1
	v_mov_b32_e32 v101, s53
	v_fmac_f32_e32 v88, 0xbaaaaaab, v101
	v_fmac_f32_e32 v89, 0xbaaaaaab, v101
	v_fmac_f32_e32 v90, 0xbaaaaaab, v101
	v_fmac_f32_e32 v91, 0xbaaaaaab, v101
	v_fmac_f32_e32 v92, 0xbaaaaaab, v101
	v_fmac_f32_e32 v93, 0xbaaaaaab, v101
	v_fmac_f32_e32 v94, 0xbaaaaaab, v101
	v_fmac_f32_e32 v95, 0xbaaaaaab, v101
	v_fmac_f32_e32 v96, 0xbaaaaaab, v101
	v_fmac_f32_e32 v97, 0xbaaaaaab, v101
	v_fmac_f32_e32 v98, 0xbaaaaaab, v101
	v_fmac_f32_e32 v99, 0xbaaaaaab, v101
	v_mul_f32_e32 v102, v88, v88
	v_fmac_f32_e32 v102, v89, v89
	v_fmac_f32_e32 v102, v90, v90
	v_fmac_f32_e32 v102, v91, v91
	v_fmac_f32_e32 v102, v92, v92
	v_fmac_f32_e32 v102, v93, v93
	v_fmac_f32_e32 v102, v94, v94
	v_fmac_f32_e32 v102, v95, v95
	v_fmac_f32_e32 v102, v96, v96
	v_fmac_f32_e32 v102, v97, v97
	v_fmac_f32_e32 v102, v98, v98
	v_fmac_f32_e32 v102, v99, v99
	s_nop 1
	v_add_f32_dpp v102, v102, v102 row_shr:1 row_mask:0xf bank_mask:0xf bound_ctrl:1
	s_nop 1
	v_add_f32_dpp v102, v102, v102 row_shr:2 row_mask:0xf bank_mask:0xf bound_ctrl:1
	s_nop 1
	v_add_f32_dpp v102, v102, v102 row_shr:4 row_mask:0xf bank_mask:0xf bound_ctrl:1
	s_nop 1
	v_add_f32_dpp v102, v102, v102 row_shr:8 row_mask:0xf bank_mask:0xf bound_ctrl:1
	s_nop 1
	v_add_f32_dpp v102, v102, v102 row_bcast:15 row_mask:0xa bank_mask:0xf
	s_nop 1
	v_add_f32_dpp v102, v102, v102 row_bcast:31 row_mask:0xc bank_mask:0xf
	s_nop 0
	v_readlane_b32 s53, v102, 63
	s_nop 1
	v_mov_b32_e32 v101, s53
	v_fmamk_f32 v101, v101, 0x3aaaaaab, v197
	v_rsq_f32_e32 v103, v101
	s_nop 0
	v_mul_f32_e32 v88, v88, v103
	v_mul_f32_e32 v89, v89, v103
	v_mul_f32_e32 v90, v90, v103
	v_mul_f32_e32 v91, v91, v103
	v_mul_f32_e32 v92, v92, v103
	v_mul_f32_e32 v93, v93, v103
	v_mul_f32_e32 v94, v94, v103
	v_mul_f32_e32 v95, v95, v103
	v_mul_f32_e32 v96, v96, v103
	v_mul_f32_e32 v97, v97, v103
	v_mul_f32_e32 v98, v98, v103
	v_mul_f32_e32 v99, v99, v103
	v_fma_f32 v88, v222, v88, v234
	v_fma_f32 v89, v223, v89, v235
	v_fma_f32 v90, v224, v90, v236
	v_fma_f32 v91, v225, v91, v237
	v_fma_f32 v92, v226, v92, v238
	v_fma_f32 v93, v227, v93, v239
	v_fma_f32 v94, v228, v94, v240
	v_fma_f32 v95, v229, v95, v241
	v_fma_f32 v96, v230, v96, v242
	v_fma_f32 v97, v231, v97, v243
	v_fma_f32 v98, v232, v98, v244
	v_fma_f32 v99, v233, v99, v245
	s_lshl_b32 s52, s41, 11
	s_add_i32 s52, s52, 14336
	v_add_u32_e32 v196, s52, v3
	v_mul_f32_e32 v108, 0xbfb8aa3b, v88
	v_exp_f32_e32 v109, v108
	s_nop 0
	v_add_f32_e32 v110, 1.0, v109
	v_div_scale_f32 v111, s[54:55], v110, v110, 1.0
	v_rcp_f32_e32 v112, v111
	v_div_scale_f32 v113, vcc, 1.0, v110, 1.0
	v_fma_f32 v115, -v111, v112, 1.0
	v_fmac_f32_e32 v112, v115, v112
	v_mul_f32_e32 v114, v113, v112
	v_fma_f32 v115, -v111, v114, v113
	v_fmac_f32_e32 v114, v115, v112
	v_fma_f32 v115, -v111, v114, v113
	v_div_fmas_f32 v115, v115, v112, v114
	v_div_fixup_f32 v115, v115, v110, 1.0
	v_mul_f32_e32 v120, v88, v115
	v_mul_f32_e32 v108, 0xbfb8aa3b, v89
	v_exp_f32_e32 v109, v108
	s_nop 0
	v_add_f32_e32 v110, 1.0, v109
	v_div_scale_f32 v111, s[54:55], v110, v110, 1.0
	v_rcp_f32_e32 v112, v111
	v_div_scale_f32 v113, vcc, 1.0, v110, 1.0
	v_fma_f32 v115, -v111, v112, 1.0
	v_fmac_f32_e32 v112, v115, v112
	v_mul_f32_e32 v114, v113, v112
	v_fma_f32 v115, -v111, v114, v113
	v_fmac_f32_e32 v114, v115, v112
	v_fma_f32 v115, -v111, v114, v113
	v_div_fmas_f32 v115, v115, v112, v114
	v_div_fixup_f32 v115, v115, v110, 1.0
	v_mul_f32_e32 v121, v89, v115
	v_mul_f32_e32 v108, 0xbfb8aa3b, v90
	v_exp_f32_e32 v109, v108
	s_nop 0
	v_add_f32_e32 v110, 1.0, v109
	v_div_scale_f32 v111, s[54:55], v110, v110, 1.0
	v_rcp_f32_e32 v112, v111
	v_div_scale_f32 v113, vcc, 1.0, v110, 1.0
	v_fma_f32 v115, -v111, v112, 1.0
	v_fmac_f32_e32 v112, v115, v112
	v_mul_f32_e32 v114, v113, v112
	v_fma_f32 v115, -v111, v114, v113
	v_fmac_f32_e32 v114, v115, v112
	v_fma_f32 v115, -v111, v114, v113
	v_div_fmas_f32 v115, v115, v112, v114
	v_div_fixup_f32 v115, v115, v110, 1.0
	v_mul_f32_e32 v122, v90, v115
	v_mul_f32_e32 v108, 0xbfb8aa3b, v91
	v_exp_f32_e32 v109, v108
	s_nop 0
	v_add_f32_e32 v110, 1.0, v109
	v_div_scale_f32 v111, s[54:55], v110, v110, 1.0
	v_rcp_f32_e32 v112, v111
	v_div_scale_f32 v113, vcc, 1.0, v110, 1.0
	v_fma_f32 v115, -v111, v112, 1.0
	v_fmac_f32_e32 v112, v115, v112
	v_mul_f32_e32 v114, v113, v112
	v_fma_f32 v115, -v111, v114, v113
	v_fmac_f32_e32 v114, v115, v112
	v_fma_f32 v115, -v111, v114, v113
	v_div_fmas_f32 v115, v115, v112, v114
	v_div_fixup_f32 v115, v115, v110, 1.0
	v_mul_f32_e32 v123, v91, v115
	v_cvt_pk_bf16_f32 v124, v120, v121
	v_cvt_pk_bf16_f32 v125, v122, v123
	global_store_dwordx2 v196, v[124:125], s[44:45]
	v_mul_f32_e32 v108, 0xbfb8aa3b, v92
	v_exp_f32_e32 v109, v108
	s_nop 0
	v_add_f32_e32 v110, 1.0, v109
	v_div_scale_f32 v111, s[54:55], v110, v110, 1.0
	v_rcp_f32_e32 v112, v111
	v_div_scale_f32 v113, vcc, 1.0, v110, 1.0
	v_fma_f32 v115, -v111, v112, 1.0
	v_fmac_f32_e32 v112, v115, v112
	v_mul_f32_e32 v114, v113, v112
	v_fma_f32 v115, -v111, v114, v113
	v_fmac_f32_e32 v114, v115, v112
	v_fma_f32 v115, -v111, v114, v113
	v_div_fmas_f32 v115, v115, v112, v114
	v_div_fixup_f32 v115, v115, v110, 1.0
	v_mul_f32_e32 v120, v92, v115
	v_mul_f32_e32 v108, 0xbfb8aa3b, v93
	v_exp_f32_e32 v109, v108
	s_nop 0
	v_add_f32_e32 v110, 1.0, v109
	v_div_scale_f32 v111, s[54:55], v110, v110, 1.0
	v_rcp_f32_e32 v112, v111
	v_div_scale_f32 v113, vcc, 1.0, v110, 1.0
	v_fma_f32 v115, -v111, v112, 1.0
	v_fmac_f32_e32 v112, v115, v112
	v_mul_f32_e32 v114, v113, v112
	v_fma_f32 v115, -v111, v114, v113
	v_fmac_f32_e32 v114, v115, v112
	v_fma_f32 v115, -v111, v114, v113
	v_div_fmas_f32 v115, v115, v112, v114
	v_div_fixup_f32 v115, v115, v110, 1.0
	v_mul_f32_e32 v121, v93, v115
	v_mul_f32_e32 v108, 0xbfb8aa3b, v94
	v_exp_f32_e32 v109, v108
	s_nop 0
	v_add_f32_e32 v110, 1.0, v109
	v_div_scale_f32 v111, s[54:55], v110, v110, 1.0
	v_rcp_f32_e32 v112, v111
	v_div_scale_f32 v113, vcc, 1.0, v110, 1.0
	v_fma_f32 v115, -v111, v112, 1.0
	v_fmac_f32_e32 v112, v115, v112
	v_mul_f32_e32 v114, v113, v112
	v_fma_f32 v115, -v111, v114, v113
	v_fmac_f32_e32 v114, v115, v112
	v_fma_f32 v115, -v111, v114, v113
	v_div_fmas_f32 v115, v115, v112, v114
	v_div_fixup_f32 v115, v115, v110, 1.0
	v_mul_f32_e32 v122, v94, v115
	v_mul_f32_e32 v108, 0xbfb8aa3b, v95
	v_exp_f32_e32 v109, v108
	s_nop 0
	v_add_f32_e32 v110, 1.0, v109
	v_div_scale_f32 v111, s[54:55], v110, v110, 1.0
	v_rcp_f32_e32 v112, v111
	v_div_scale_f32 v113, vcc, 1.0, v110, 1.0
	v_fma_f32 v115, -v111, v112, 1.0
	v_fmac_f32_e32 v112, v115, v112
	v_mul_f32_e32 v114, v113, v112
	v_fma_f32 v115, -v111, v114, v113
	v_fmac_f32_e32 v114, v115, v112
	v_fma_f32 v115, -v111, v114, v113
	v_div_fmas_f32 v115, v115, v112, v114
	v_div_fixup_f32 v115, v115, v110, 1.0
	v_mul_f32_e32 v123, v95, v115
	v_cvt_pk_bf16_f32 v124, v120, v121
	v_cvt_pk_bf16_f32 v125, v122, v123
	global_store_dwordx2 v196, v[124:125], s[44:45] offset:512
	v_mul_f32_e32 v108, 0xbfb8aa3b, v96
	v_exp_f32_e32 v109, v108
	s_nop 0
	v_add_f32_e32 v110, 1.0, v109
	v_div_scale_f32 v111, s[54:55], v110, v110, 1.0
	v_rcp_f32_e32 v112, v111
	v_div_scale_f32 v113, vcc, 1.0, v110, 1.0
	v_fma_f32 v115, -v111, v112, 1.0
	v_fmac_f32_e32 v112, v115, v112
	v_mul_f32_e32 v114, v113, v112
	v_fma_f32 v115, -v111, v114, v113
	v_fmac_f32_e32 v114, v115, v112
	v_fma_f32 v115, -v111, v114, v113
	v_div_fmas_f32 v115, v115, v112, v114
	v_div_fixup_f32 v115, v115, v110, 1.0
	v_mul_f32_e32 v120, v96, v115
	v_mul_f32_e32 v108, 0xbfb8aa3b, v97
	v_exp_f32_e32 v109, v108
	s_nop 0
	v_add_f32_e32 v110, 1.0, v109
	v_div_scale_f32 v111, s[54:55], v110, v110, 1.0
	v_rcp_f32_e32 v112, v111
	v_div_scale_f32 v113, vcc, 1.0, v110, 1.0
	v_fma_f32 v115, -v111, v112, 1.0
	v_fmac_f32_e32 v112, v115, v112
	v_mul_f32_e32 v114, v113, v112
	v_fma_f32 v115, -v111, v114, v113
	v_fmac_f32_e32 v114, v115, v112
	v_fma_f32 v115, -v111, v114, v113
	v_div_fmas_f32 v115, v115, v112, v114
	v_div_fixup_f32 v115, v115, v110, 1.0
	v_mul_f32_e32 v121, v97, v115
	v_mul_f32_e32 v108, 0xbfb8aa3b, v98
	v_exp_f32_e32 v109, v108
	s_nop 0
	v_add_f32_e32 v110, 1.0, v109
	v_div_scale_f32 v111, s[54:55], v110, v110, 1.0
	v_rcp_f32_e32 v112, v111
	v_div_scale_f32 v113, vcc, 1.0, v110, 1.0
	v_fma_f32 v115, -v111, v112, 1.0
	v_fmac_f32_e32 v112, v115, v112
	v_mul_f32_e32 v114, v113, v112
	v_fma_f32 v115, -v111, v114, v113
	v_fmac_f32_e32 v114, v115, v112
	v_fma_f32 v115, -v111, v114, v113
	v_div_fmas_f32 v115, v115, v112, v114
	v_div_fixup_f32 v115, v115, v110, 1.0
	v_mul_f32_e32 v122, v98, v115
	v_mul_f32_e32 v108, 0xbfb8aa3b, v99
	v_exp_f32_e32 v109, v108
	s_nop 0
	v_add_f32_e32 v110, 1.0, v109
	v_div_scale_f32 v111, s[54:55], v110, v110, 1.0
	v_rcp_f32_e32 v112, v111
	v_div_scale_f32 v113, vcc, 1.0, v110, 1.0
	v_fma_f32 v115, -v111, v112, 1.0
	v_fmac_f32_e32 v112, v115, v112
	v_mul_f32_e32 v114, v113, v112
	v_fma_f32 v115, -v111, v114, v113
	v_fmac_f32_e32 v114, v115, v112
	v_fma_f32 v115, -v111, v114, v113
	v_div_fmas_f32 v115, v115, v112, v114
	v_div_fixup_f32 v115, v115, v110, 1.0
	v_mul_f32_e32 v123, v99, v115
	v_cvt_pk_bf16_f32 v124, v120, v121
	v_cvt_pk_bf16_f32 v125, v122, v123
	global_store_dwordx2 v196, v[124:125], s[44:45] offset:1024
	s_waitcnt vmcnt(0)
